# on v131: first K-loop iteration of five GEMM phases peeled with C=0 MFMAs, the 128-v_mov accumulator zeroing per unit removed
# speedup vs baseline: 1.0158x; 1.0085x over previous
.LBB0_244:
	s_ashr_i32 s37, s36, 31
	s_lshl_b64 s[38:39], s[36:37], 19
	s_add_u32 s38, s2, s38
	s_addc_u32 s39, s21, s39
	s_and_b64 s[40:41], s[4:5], exec
	s_cselect_b32 s7, s39, s45
	s_cselect_b32 s37, s38, s44
	s_ashr_i32 s25, s24, 31
	s_lshl_b64 s[40:41], s[24:25], 19
	s_add_u32 s40, s8, s40
	s_addc_u32 s41, s9, s41
	s_and_b64 s[48:49], s[4:5], exec
	s_cselect_b32 s25, s41, s47
	s_cselect_b32 s43, s40, s46
	s_add_u32 s44, s44, 0x40080
	s_addc_u32 s45, s45, 0
	s_add_u32 s61, s46, 0x100
	s_addc_u32 s62, s47, 0
	s_mov_b32 s63, -2
	ds_read_b128 v[144:147], v178
	ds_read_b128 v[148:151], v178 offset:1024
	ds_read_b128 v[152:155], v178 offset:2048
	ds_read_b128 v[156:159], v178 offset:3072
	ds_read_b128 v[160:163], v179
	ds_read_b128 v[164:167], v179 offset:1024
	ds_read_b128 v[168:171], v179 offset:2048
	ds_read_b128 v[182:185], v179 offset:3072
	s_add_u32 s46, s44, 0xfffc0080
	s_addc_u32 s47, s45, -1
	s_cmp_eq_u32 s63, 12
	s_cselect_b32 s49, s7, s47
	s_cselect_b32 s48, s37, s46
	s_cselect_b32 s47, s25, s62
	s_cselect_b32 s46, s43, s61
	s_add_i32 m0, s31, 0xc000
	ds_read_b128 v[186:189], v180
	ds_read_b128 v[190:193], v180 offset:1024
	ds_read_b128 v[194:197], v180 offset:2048
	ds_read_b128 v[198:201], v180 offset:3072
	ds_read_b128 v[202:205], v180 offset:4096
	ds_read_b128 v[210:213], v180 offset:5120
	ds_read_b128 v[214:217], v180 offset:6144
	ds_read_b128 v[218:221], v180 offset:7168
	global_load_lds_dwordx4 v136, s[44:45]
	s_add_i32 m0, s31, 0xe000
	s_nop 0
	global_load_lds_dwordx4 v138, s[44:45]
	s_waitcnt vmcnt(8)
	s_waitcnt lgkmcnt(0)
	s_barrier
	s_setprio 1
	s_waitcnt lgkmcnt(0)
	v_mfma_f32_16x16x32_bf16 v[124:127], v[144:147], v[186:189], 0
	v_mfma_f32_16x16x32_bf16 v[120:123], v[152:155], v[186:189], 0
	v_mfma_f32_16x16x32_bf16 v[108:111], v[144:147], v[194:197], 0
	v_mfma_f32_16x16x32_bf16 v[104:107], v[152:155], v[194:197], 0
	v_mfma_f32_16x16x32_bf16 v[92:95], v[144:147], v[202:205], 0
	v_mfma_f32_16x16x32_bf16 v[88:91], v[152:155], v[202:205], 0
	v_mfma_f32_16x16x32_bf16 v[76:79], v[144:147], v[214:217], 0
	v_mfma_f32_16x16x32_bf16 v[72:75], v[152:155], v[214:217], 0
	v_mfma_f32_16x16x32_bf16 v[124:127], v[148:151], v[190:193], v[124:127]
	v_mfma_f32_16x16x32_bf16 v[120:123], v[156:159], v[190:193], v[120:123]
	v_mfma_f32_16x16x32_bf16 v[108:111], v[148:151], v[198:201], v[108:111]
	v_mfma_f32_16x16x32_bf16 v[104:107], v[156:159], v[198:201], v[104:107]
	v_mfma_f32_16x16x32_bf16 v[92:95], v[148:151], v[210:213], v[92:95]
	v_mfma_f32_16x16x32_bf16 v[88:91], v[156:159], v[210:213], v[88:91]
	v_mfma_f32_16x16x32_bf16 v[76:79], v[148:151], v[218:221], v[76:79]
	v_mfma_f32_16x16x32_bf16 v[72:75], v[156:159], v[218:221], v[72:75]
	v_mfma_f32_16x16x32_bf16 v[116:119], v[160:163], v[186:189], 0
	v_mfma_f32_16x16x32_bf16 v[112:115], v[168:171], v[186:189], 0
	v_mfma_f32_16x16x32_bf16 v[100:103], v[160:163], v[194:197], 0
	v_mfma_f32_16x16x32_bf16 v[96:99], v[168:171], v[194:197], 0
	v_mfma_f32_16x16x32_bf16 v[84:87], v[160:163], v[202:205], 0
	v_mfma_f32_16x16x32_bf16 v[80:83], v[168:171], v[202:205], 0
	v_mfma_f32_16x16x32_bf16 v[68:71], v[160:163], v[214:217], 0
	v_mfma_f32_16x16x32_bf16 v[64:67], v[168:171], v[214:217], 0
	v_mfma_f32_16x16x32_bf16 v[116:119], v[164:167], v[190:193], v[116:119]
	v_mfma_f32_16x16x32_bf16 v[112:115], v[182:185], v[190:193], v[112:115]
	v_mfma_f32_16x16x32_bf16 v[100:103], v[164:167], v[198:201], v[100:103]
	v_mfma_f32_16x16x32_bf16 v[96:99], v[182:185], v[198:201], v[96:99]
	v_mfma_f32_16x16x32_bf16 v[84:87], v[164:167], v[210:213], v[84:87]
	v_mfma_f32_16x16x32_bf16 v[80:83], v[182:185], v[210:213], v[80:83]
	v_mfma_f32_16x16x32_bf16 v[68:71], v[164:167], v[218:221], v[68:71]
	v_mfma_f32_16x16x32_bf16 v[64:67], v[182:185], v[218:221], v[64:67]
	s_setprio 0
	s_barrier
	s_add_u32 s98, s46, s16
	s_addc_u32 s99, s47, s17
	s_add_u32 s100, s48, s16
	s_addc_u32 s101, s49, s17
	s_add_i32 s64, s35, s23
	s_mov_b32 m0, s64
	ds_read_b128 v[186:189], v180 offset:16384
	ds_read_b128 v[190:193], v180 offset:17408
	ds_read_b128 v[194:197], v180 offset:18432
	ds_read_b128 v[198:201], v180 offset:19456
	ds_read_b128 v[202:205], v180 offset:20480
	ds_read_b128 v[210:213], v180 offset:21504
	ds_read_b128 v[214:217], v180 offset:22528
	ds_read_b128 v[218:221], v180 offset:23552
	global_load_lds_dwordx4 v130, s[46:47]
	s_add_i32 m0, s64, 0x2000
	s_add_u32 s64, s46, 0x40000
	s_addc_u32 s65, s47, 0
	s_add_i32 s66, s59, s23
	global_load_lds_dwordx4 v134, s[46:47]
	s_mov_b32 m0, s66
	s_nop 0
	global_load_lds_dwordx4 v130, s[64:65]
	s_add_i32 m0, s66, 0x2000
	s_nop 0
	global_load_lds_dwordx4 v134, s[64:65]
	s_mov_b32 m0, s31
	s_nop 0
	global_load_lds_dwordx4 v128, s[48:49]
	s_mov_b32 m0, s50
	s_nop 0
	global_load_lds_dwordx4 v132, s[48:49]
	s_waitcnt vmcnt(8)
	s_waitcnt lgkmcnt(0)
	s_barrier
	s_setprio 1
	s_waitcnt lgkmcnt(0)
	v_mfma_f32_16x16x32_bf16 v[60:63], v[144:147], v[186:189], 0
	v_mfma_f32_16x16x32_bf16 v[56:59], v[152:155], v[186:189], 0
	v_mfma_f32_16x16x32_bf16 v[44:47], v[144:147], v[194:197], 0
	v_mfma_f32_16x16x32_bf16 v[40:43], v[152:155], v[194:197], 0
	v_mfma_f32_16x16x32_bf16 v[28:31], v[144:147], v[202:205], 0
	v_mfma_f32_16x16x32_bf16 v[24:27], v[152:155], v[202:205], 0
	v_mfma_f32_16x16x32_bf16 v[12:15], v[144:147], v[214:217], 0
	v_mfma_f32_16x16x32_bf16 v[8:11], v[152:155], v[214:217], 0
	v_mfma_f32_16x16x32_bf16 v[60:63], v[148:151], v[190:193], v[60:63]
	v_mfma_f32_16x16x32_bf16 v[56:59], v[156:159], v[190:193], v[56:59]
	v_mfma_f32_16x16x32_bf16 v[44:47], v[148:151], v[198:201], v[44:47]
	v_mfma_f32_16x16x32_bf16 v[40:43], v[156:159], v[198:201], v[40:43]
	v_mfma_f32_16x16x32_bf16 v[28:31], v[148:151], v[210:213], v[28:31]
	v_mfma_f32_16x16x32_bf16 v[24:27], v[156:159], v[210:213], v[24:27]
	v_mfma_f32_16x16x32_bf16 v[12:15], v[148:151], v[218:221], v[12:15]
	v_mfma_f32_16x16x32_bf16 v[8:11], v[156:159], v[218:221], v[8:11]
	v_mfma_f32_16x16x32_bf16 v[52:55], v[160:163], v[186:189], 0
	v_mfma_f32_16x16x32_bf16 v[48:51], v[168:171], v[186:189], 0
	v_mfma_f32_16x16x32_bf16 v[36:39], v[160:163], v[194:197], 0
	v_mfma_f32_16x16x32_bf16 v[32:35], v[168:171], v[194:197], 0
	v_mfma_f32_16x16x32_bf16 v[20:23], v[160:163], v[202:205], 0
	v_mfma_f32_16x16x32_bf16 v[16:19], v[168:171], v[202:205], 0
	v_mfma_f32_16x16x32_bf16 v[4:7], v[160:163], v[214:217], 0
	v_mfma_f32_16x16x32_bf16 v[0:3], v[168:171], v[214:217], 0
	v_mfma_f32_16x16x32_bf16 v[52:55], v[164:167], v[190:193], v[52:55]
	v_mfma_f32_16x16x32_bf16 v[48:51], v[182:185], v[190:193], v[48:51]
	v_mfma_f32_16x16x32_bf16 v[36:39], v[164:167], v[198:201], v[36:39]
	v_mfma_f32_16x16x32_bf16 v[32:35], v[182:185], v[198:201], v[32:35]
	v_mfma_f32_16x16x32_bf16 v[20:23], v[164:167], v[210:213], v[20:23]
	v_mfma_f32_16x16x32_bf16 v[16:19], v[182:185], v[210:213], v[16:19]
	v_mfma_f32_16x16x32_bf16 v[4:7], v[164:167], v[218:221], v[4:7]
	v_mfma_f32_16x16x32_bf16 v[0:3], v[182:185], v[218:221], v[0:3]
	s_setprio 0
	s_barrier
	s_add_i32 s64, 0, 0x18000
	s_add_i32 s65, 0, 0x1c000
	v_add_u32_e32 v156, s64, v176
	v_add_u32_e32 v181, s65, v176
	ds_read_b128 v[144:147], v156
	ds_read_b128 v[148:151], v156 offset:1024
	ds_read_b128 v[152:155], v156 offset:2048
	ds_read_b128 v[156:159], v156 offset:3072
	ds_read_b128 v[160:163], v181
	ds_read_b128 v[164:167], v181 offset:1024
	ds_read_b128 v[168:171], v181 offset:2048
	ds_read_b128 v[182:185], v181 offset:3072
	s_add_u32 s48, s48, 0x40000
	s_addc_u32 s49, s49, 0
	s_mov_b32 m0, s51
	ds_read_b128 v[186:189], v180 offset:32768
	ds_read_b128 v[190:193], v180 offset:33792
	ds_read_b128 v[194:197], v180 offset:34816
	ds_read_b128 v[198:201], v180 offset:35840
	ds_read_b128 v[202:205], v180 offset:36864
	ds_read_b128 v[210:213], v180 offset:37888
	ds_read_b128 v[214:217], v180 offset:38912
	ds_read_b128 v[218:221], v180 offset:39936
	global_load_lds_dwordx4 v128, s[48:49]
	s_mov_b32 m0, s52
	s_nop 0
	global_load_lds_dwordx4 v132, s[48:49]
	s_waitcnt vmcnt(8)
	s_waitcnt lgkmcnt(0)
	s_barrier
	s_setprio 1
	s_waitcnt lgkmcnt(0)
	v_mfma_f32_16x16x32_bf16 v[124:127], v[144:147], v[186:189], v[124:127]
	v_mfma_f32_16x16x32_bf16 v[120:123], v[152:155], v[186:189], v[120:123]
	v_mfma_f32_16x16x32_bf16 v[108:111], v[144:147], v[194:197], v[108:111]
	v_mfma_f32_16x16x32_bf16 v[104:107], v[152:155], v[194:197], v[104:107]
	v_mfma_f32_16x16x32_bf16 v[92:95], v[144:147], v[202:205], v[92:95]
	v_mfma_f32_16x16x32_bf16 v[88:91], v[152:155], v[202:205], v[88:91]
	v_mfma_f32_16x16x32_bf16 v[76:79], v[144:147], v[214:217], v[76:79]
	v_mfma_f32_16x16x32_bf16 v[72:75], v[152:155], v[214:217], v[72:75]
	v_mfma_f32_16x16x32_bf16 v[124:127], v[148:151], v[190:193], v[124:127]
	v_mfma_f32_16x16x32_bf16 v[120:123], v[156:159], v[190:193], v[120:123]
	v_mfma_f32_16x16x32_bf16 v[108:111], v[148:151], v[198:201], v[108:111]
	v_mfma_f32_16x16x32_bf16 v[104:107], v[156:159], v[198:201], v[104:107]
	v_mfma_f32_16x16x32_bf16 v[92:95], v[148:151], v[210:213], v[92:95]
	v_mfma_f32_16x16x32_bf16 v[88:91], v[156:159], v[210:213], v[88:91]
	v_mfma_f32_16x16x32_bf16 v[76:79], v[148:151], v[218:221], v[76:79]
	v_mfma_f32_16x16x32_bf16 v[72:75], v[156:159], v[218:221], v[72:75]
	v_mfma_f32_16x16x32_bf16 v[116:119], v[160:163], v[186:189], v[116:119]
	v_mfma_f32_16x16x32_bf16 v[112:115], v[168:171], v[186:189], v[112:115]
	v_mfma_f32_16x16x32_bf16 v[100:103], v[160:163], v[194:197], v[100:103]
	v_mfma_f32_16x16x32_bf16 v[96:99], v[168:171], v[194:197], v[96:99]
	v_mfma_f32_16x16x32_bf16 v[84:87], v[160:163], v[202:205], v[84:87]
	v_mfma_f32_16x16x32_bf16 v[80:83], v[168:171], v[202:205], v[80:83]
	v_mfma_f32_16x16x32_bf16 v[68:71], v[160:163], v[214:217], v[68:71]
	v_mfma_f32_16x16x32_bf16 v[64:67], v[168:171], v[214:217], v[64:67]
	v_mfma_f32_16x16x32_bf16 v[116:119], v[164:167], v[190:193], v[116:119]
	v_mfma_f32_16x16x32_bf16 v[112:115], v[182:185], v[190:193], v[112:115]
	v_mfma_f32_16x16x32_bf16 v[100:103], v[164:167], v[198:201], v[100:103]
	v_mfma_f32_16x16x32_bf16 v[96:99], v[182:185], v[198:201], v[96:99]
	v_mfma_f32_16x16x32_bf16 v[84:87], v[164:167], v[210:213], v[84:87]
	v_mfma_f32_16x16x32_bf16 v[80:83], v[182:185], v[210:213], v[80:83]
	v_mfma_f32_16x16x32_bf16 v[68:71], v[164:167], v[218:221], v[68:71]
	v_mfma_f32_16x16x32_bf16 v[64:67], v[182:185], v[218:221], v[64:67]
	s_setprio 0
	s_barrier
	s_add_i32 s48, s64, s23
	s_mov_b32 m0, s48
	ds_read_b128 v[186:189], v180 offset:49152
	ds_read_b128 v[190:193], v180 offset:50176
	ds_read_b128 v[194:197], v180 offset:51200
	ds_read_b128 v[198:201], v180 offset:52224
	ds_read_b128 v[202:205], v180 offset:53248
	ds_read_b128 v[210:213], v180 offset:54272
	ds_read_b128 v[214:217], v180 offset:55296
	ds_read_b128 v[218:221], v180 offset:56320
	global_load_lds_dwordx4 v130, s[98:99]
	s_add_i32 m0, s48, 0x2000
	s_add_u32 s46, s46, 0x40080
	s_addc_u32 s47, s47, 0
	s_add_i32 s48, s65, s23
	global_load_lds_dwordx4 v134, s[98:99]
	s_mov_b32 m0, s48
	s_nop 0
	global_load_lds_dwordx4 v130, s[46:47]
	s_add_i32 m0, s48, 0x2000
	s_nop 0
	global_load_lds_dwordx4 v134, s[46:47]
	s_mov_b32 m0, s54
	s_nop 0
	global_load_lds_dwordx4 v128, s[100:101]
	s_mov_b32 m0, s55
	s_nop 0
	global_load_lds_dwordx4 v132, s[100:101]
	s_waitcnt vmcnt(8)
	s_waitcnt lgkmcnt(0)
	s_barrier
	s_setprio 1
	s_waitcnt lgkmcnt(0)
	v_mfma_f32_16x16x32_bf16 v[60:63], v[144:147], v[186:189], v[60:63]
	v_mfma_f32_16x16x32_bf16 v[56:59], v[152:155], v[186:189], v[56:59]
	v_mfma_f32_16x16x32_bf16 v[44:47], v[144:147], v[194:197], v[44:47]
	v_mfma_f32_16x16x32_bf16 v[40:43], v[152:155], v[194:197], v[40:43]
	v_mfma_f32_16x16x32_bf16 v[28:31], v[144:147], v[202:205], v[28:31]
	v_mfma_f32_16x16x32_bf16 v[24:27], v[152:155], v[202:205], v[24:27]
	v_mfma_f32_16x16x32_bf16 v[12:15], v[144:147], v[214:217], v[12:15]
	v_mfma_f32_16x16x32_bf16 v[8:11], v[152:155], v[214:217], v[8:11]
	v_mfma_f32_16x16x32_bf16 v[60:63], v[148:151], v[190:193], v[60:63]
	v_mfma_f32_16x16x32_bf16 v[56:59], v[156:159], v[190:193], v[56:59]
	v_mfma_f32_16x16x32_bf16 v[44:47], v[148:151], v[198:201], v[44:47]
	v_mfma_f32_16x16x32_bf16 v[40:43], v[156:159], v[198:201], v[40:43]
	v_mfma_f32_16x16x32_bf16 v[28:31], v[148:151], v[210:213], v[28:31]
	v_mfma_f32_16x16x32_bf16 v[24:27], v[156:159], v[210:213], v[24:27]
	v_mfma_f32_16x16x32_bf16 v[12:15], v[148:151], v[218:221], v[12:15]
	v_mfma_f32_16x16x32_bf16 v[8:11], v[156:159], v[218:221], v[8:11]
	v_mfma_f32_16x16x32_bf16 v[52:55], v[160:163], v[186:189], v[52:55]
	v_mfma_f32_16x16x32_bf16 v[48:51], v[168:171], v[186:189], v[48:51]
	v_mfma_f32_16x16x32_bf16 v[36:39], v[160:163], v[194:197], v[36:39]
	v_mfma_f32_16x16x32_bf16 v[32:35], v[168:171], v[194:197], v[32:35]
	v_mfma_f32_16x16x32_bf16 v[20:23], v[160:163], v[202:205], v[20:23]
	v_mfma_f32_16x16x32_bf16 v[16:19], v[168:171], v[202:205], v[16:19]
	v_mfma_f32_16x16x32_bf16 v[4:7], v[160:163], v[214:217], v[4:7]
	v_mfma_f32_16x16x32_bf16 v[0:3], v[168:171], v[214:217], v[0:3]
	v_mfma_f32_16x16x32_bf16 v[52:55], v[164:167], v[190:193], v[52:55]
	v_mfma_f32_16x16x32_bf16 v[48:51], v[182:185], v[190:193], v[48:51]
	v_mfma_f32_16x16x32_bf16 v[36:39], v[164:167], v[198:201], v[36:39]
	v_mfma_f32_16x16x32_bf16 v[32:35], v[182:185], v[198:201], v[32:35]
	v_mfma_f32_16x16x32_bf16 v[20:23], v[164:167], v[210:213], v[20:23]
	v_mfma_f32_16x16x32_bf16 v[16:19], v[182:185], v[210:213], v[16:19]
	v_mfma_f32_16x16x32_bf16 v[4:7], v[164:167], v[218:221], v[4:7]
	v_mfma_f32_16x16x32_bf16 v[0:3], v[182:185], v[218:221], v[0:3]
	s_setprio 0
	s_barrier
	s_add_i32 s63, s63, 2
	s_add_u32 s44, s44, 0x100
	s_addc_u32 s45, s45, 0
	s_add_u32 s61, s61, 0x100
	s_addc_u32 s62, s62, 0
	s_cmp_gt_u32 s63, 13
	s_cbranch_scc1 .Lkexit_0
.LBB0_245:
	ds_read_b128 v[144:147], v178
	ds_read_b128 v[148:151], v178 offset:1024
	ds_read_b128 v[152:155], v178 offset:2048
	ds_read_b128 v[156:159], v178 offset:3072
	ds_read_b128 v[160:163], v179
	ds_read_b128 v[164:167], v179 offset:1024
	ds_read_b128 v[168:171], v179 offset:2048
	ds_read_b128 v[182:185], v179 offset:3072
	s_add_u32 s46, s44, 0xfffc0080
	s_addc_u32 s47, s45, -1
	s_cmp_eq_u32 s63, 12
	s_cselect_b32 s49, s7, s47
	s_cselect_b32 s48, s37, s46
	s_cselect_b32 s47, s25, s62
	s_cselect_b32 s46, s43, s61
	s_add_i32 m0, s31, 0xc000
	ds_read_b128 v[186:189], v180
	ds_read_b128 v[190:193], v180 offset:1024
	ds_read_b128 v[194:197], v180 offset:2048
	ds_read_b128 v[198:201], v180 offset:3072
	ds_read_b128 v[202:205], v180 offset:4096
	ds_read_b128 v[210:213], v180 offset:5120
	ds_read_b128 v[214:217], v180 offset:6144
	ds_read_b128 v[218:221], v180 offset:7168
	global_load_lds_dwordx4 v136, s[44:45]
	s_add_i32 m0, s31, 0xe000
	s_nop 0
	global_load_lds_dwordx4 v138, s[44:45]
	s_waitcnt vmcnt(8)
	s_waitcnt lgkmcnt(0)
	s_barrier
	s_setprio 1
	s_waitcnt lgkmcnt(0)
	v_mfma_f32_16x16x32_bf16 v[124:127], v[144:147], v[186:189], v[124:127]
	v_mfma_f32_16x16x32_bf16 v[120:123], v[152:155], v[186:189], v[120:123]
	v_mfma_f32_16x16x32_bf16 v[108:111], v[144:147], v[194:197], v[108:111]
	v_mfma_f32_16x16x32_bf16 v[104:107], v[152:155], v[194:197], v[104:107]
	v_mfma_f32_16x16x32_bf16 v[92:95], v[144:147], v[202:205], v[92:95]
	v_mfma_f32_16x16x32_bf16 v[88:91], v[152:155], v[202:205], v[88:91]
	v_mfma_f32_16x16x32_bf16 v[76:79], v[144:147], v[214:217], v[76:79]
	v_mfma_f32_16x16x32_bf16 v[72:75], v[152:155], v[214:217], v[72:75]
	v_mfma_f32_16x16x32_bf16 v[124:127], v[148:151], v[190:193], v[124:127]
	v_mfma_f32_16x16x32_bf16 v[120:123], v[156:159], v[190:193], v[120:123]
	v_mfma_f32_16x16x32_bf16 v[108:111], v[148:151], v[198:201], v[108:111]
	v_mfma_f32_16x16x32_bf16 v[104:107], v[156:159], v[198:201], v[104:107]
	v_mfma_f32_16x16x32_bf16 v[92:95], v[148:151], v[210:213], v[92:95]
	v_mfma_f32_16x16x32_bf16 v[88:91], v[156:159], v[210:213], v[88:91]
	v_mfma_f32_16x16x32_bf16 v[76:79], v[148:151], v[218:221], v[76:79]
	v_mfma_f32_16x16x32_bf16 v[72:75], v[156:159], v[218:221], v[72:75]
	v_mfma_f32_16x16x32_bf16 v[116:119], v[160:163], v[186:189], v[116:119]
	v_mfma_f32_16x16x32_bf16 v[112:115], v[168:171], v[186:189], v[112:115]
	v_mfma_f32_16x16x32_bf16 v[100:103], v[160:163], v[194:197], v[100:103]
	v_mfma_f32_16x16x32_bf16 v[96:99], v[168:171], v[194:197], v[96:99]
	v_mfma_f32_16x16x32_bf16 v[84:87], v[160:163], v[202:205], v[84:87]
	v_mfma_f32_16x16x32_bf16 v[80:83], v[168:171], v[202:205], v[80:83]
	v_mfma_f32_16x16x32_bf16 v[68:71], v[160:163], v[214:217], v[68:71]
	v_mfma_f32_16x16x32_bf16 v[64:67], v[168:171], v[214:217], v[64:67]
	v_mfma_f32_16x16x32_bf16 v[116:119], v[164:167], v[190:193], v[116:119]
	v_mfma_f32_16x16x32_bf16 v[112:115], v[182:185], v[190:193], v[112:115]
	v_mfma_f32_16x16x32_bf16 v[100:103], v[164:167], v[198:201], v[100:103]
	v_mfma_f32_16x16x32_bf16 v[96:99], v[182:185], v[198:201], v[96:99]
	v_mfma_f32_16x16x32_bf16 v[84:87], v[164:167], v[210:213], v[84:87]
	v_mfma_f32_16x16x32_bf16 v[80:83], v[182:185], v[210:213], v[80:83]
	v_mfma_f32_16x16x32_bf16 v[68:71], v[164:167], v[218:221], v[68:71]
	v_mfma_f32_16x16x32_bf16 v[64:67], v[182:185], v[218:221], v[64:67]
	s_setprio 0
	s_barrier
	s_add_u32 s98, s46, s16
	s_addc_u32 s99, s47, s17
	s_add_u32 s100, s48, s16
	s_addc_u32 s101, s49, s17
	s_add_i32 s64, s35, s23
	s_mov_b32 m0, s64
	ds_read_b128 v[186:189], v180 offset:16384
	ds_read_b128 v[190:193], v180 offset:17408
	ds_read_b128 v[194:197], v180 offset:18432
	ds_read_b128 v[198:201], v180 offset:19456
	ds_read_b128 v[202:205], v180 offset:20480
	ds_read_b128 v[210:213], v180 offset:21504
	ds_read_b128 v[214:217], v180 offset:22528
	ds_read_b128 v[218:221], v180 offset:23552
	global_load_lds_dwordx4 v130, s[46:47]
	s_add_i32 m0, s64, 0x2000
	s_add_u32 s64, s46, 0x40000
	s_addc_u32 s65, s47, 0
	s_add_i32 s66, s59, s23
	global_load_lds_dwordx4 v134, s[46:47]
	s_mov_b32 m0, s66
	s_nop 0
	global_load_lds_dwordx4 v130, s[64:65]
	s_add_i32 m0, s66, 0x2000
	s_nop 0
	global_load_lds_dwordx4 v134, s[64:65]
	s_mov_b32 m0, s31
	s_nop 0
	global_load_lds_dwordx4 v128, s[48:49]
	s_mov_b32 m0, s50
	s_nop 0
	global_load_lds_dwordx4 v132, s[48:49]
	s_waitcnt vmcnt(8)
	s_waitcnt lgkmcnt(0)
	s_barrier
	s_setprio 1
	s_waitcnt lgkmcnt(0)
	v_mfma_f32_16x16x32_bf16 v[60:63], v[144:147], v[186:189], v[60:63]
	v_mfma_f32_16x16x32_bf16 v[56:59], v[152:155], v[186:189], v[56:59]
	v_mfma_f32_16x16x32_bf16 v[44:47], v[144:147], v[194:197], v[44:47]
	v_mfma_f32_16x16x32_bf16 v[40:43], v[152:155], v[194:197], v[40:43]
	v_mfma_f32_16x16x32_bf16 v[28:31], v[144:147], v[202:205], v[28:31]
	v_mfma_f32_16x16x32_bf16 v[24:27], v[152:155], v[202:205], v[24:27]
	v_mfma_f32_16x16x32_bf16 v[12:15], v[144:147], v[214:217], v[12:15]
	v_mfma_f32_16x16x32_bf16 v[8:11], v[152:155], v[214:217], v[8:11]
	v_mfma_f32_16x16x32_bf16 v[60:63], v[148:151], v[190:193], v[60:63]
	v_mfma_f32_16x16x32_bf16 v[56:59], v[156:159], v[190:193], v[56:59]
	v_mfma_f32_16x16x32_bf16 v[44:47], v[148:151], v[198:201], v[44:47]
	v_mfma_f32_16x16x32_bf16 v[40:43], v[156:159], v[198:201], v[40:43]
	v_mfma_f32_16x16x32_bf16 v[28:31], v[148:151], v[210:213], v[28:31]
	v_mfma_f32_16x16x32_bf16 v[24:27], v[156:159], v[210:213], v[24:27]
	v_mfma_f32_16x16x32_bf16 v[12:15], v[148:151], v[218:221], v[12:15]
	v_mfma_f32_16x16x32_bf16 v[8:11], v[156:159], v[218:221], v[8:11]
	v_mfma_f32_16x16x32_bf16 v[52:55], v[160:163], v[186:189], v[52:55]
	v_mfma_f32_16x16x32_bf16 v[48:51], v[168:171], v[186:189], v[48:51]
	v_mfma_f32_16x16x32_bf16 v[36:39], v[160:163], v[194:197], v[36:39]
	v_mfma_f32_16x16x32_bf16 v[32:35], v[168:171], v[194:197], v[32:35]
	v_mfma_f32_16x16x32_bf16 v[20:23], v[160:163], v[202:205], v[20:23]
	v_mfma_f32_16x16x32_bf16 v[16:19], v[168:171], v[202:205], v[16:19]
	v_mfma_f32_16x16x32_bf16 v[4:7], v[160:163], v[214:217], v[4:7]
	v_mfma_f32_16x16x32_bf16 v[0:3], v[168:171], v[214:217], v[0:3]
	v_mfma_f32_16x16x32_bf16 v[52:55], v[164:167], v[190:193], v[52:55]
	v_mfma_f32_16x16x32_bf16 v[48:51], v[182:185], v[190:193], v[48:51]
	v_mfma_f32_16x16x32_bf16 v[36:39], v[164:167], v[198:201], v[36:39]
	v_mfma_f32_16x16x32_bf16 v[32:35], v[182:185], v[198:201], v[32:35]
	v_mfma_f32_16x16x32_bf16 v[20:23], v[164:167], v[210:213], v[20:23]
	v_mfma_f32_16x16x32_bf16 v[16:19], v[182:185], v[210:213], v[16:19]
	v_mfma_f32_16x16x32_bf16 v[4:7], v[164:167], v[218:221], v[4:7]
	v_mfma_f32_16x16x32_bf16 v[0:3], v[182:185], v[218:221], v[0:3]
	s_setprio 0
	s_barrier
	s_add_i32 s64, 0, 0x18000
	s_add_i32 s65, 0, 0x1c000
	v_add_u32_e32 v156, s64, v176
	v_add_u32_e32 v181, s65, v176
	ds_read_b128 v[144:147], v156
	ds_read_b128 v[148:151], v156 offset:1024
	ds_read_b128 v[152:155], v156 offset:2048
	ds_read_b128 v[156:159], v156 offset:3072
	ds_read_b128 v[160:163], v181
	ds_read_b128 v[164:167], v181 offset:1024
	ds_read_b128 v[168:171], v181 offset:2048
	ds_read_b128 v[182:185], v181 offset:3072
	s_add_u32 s48, s48, 0x40000
	s_addc_u32 s49, s49, 0
	s_mov_b32 m0, s51
	ds_read_b128 v[186:189], v180 offset:32768
	ds_read_b128 v[190:193], v180 offset:33792
	ds_read_b128 v[194:197], v180 offset:34816
	ds_read_b128 v[198:201], v180 offset:35840
	ds_read_b128 v[202:205], v180 offset:36864
	ds_read_b128 v[210:213], v180 offset:37888
	ds_read_b128 v[214:217], v180 offset:38912
	ds_read_b128 v[218:221], v180 offset:39936
	global_load_lds_dwordx4 v128, s[48:49]
	s_mov_b32 m0, s52
	s_nop 0
	global_load_lds_dwordx4 v132, s[48:49]
	s_waitcnt vmcnt(8)
	s_waitcnt lgkmcnt(0)
	s_barrier
	s_setprio 1
	s_waitcnt lgkmcnt(0)
	v_mfma_f32_16x16x32_bf16 v[124:127], v[144:147], v[186:189], v[124:127]
	v_mfma_f32_16x16x32_bf16 v[120:123], v[152:155], v[186:189], v[120:123]
	v_mfma_f32_16x16x32_bf16 v[108:111], v[144:147], v[194:197], v[108:111]
	v_mfma_f32_16x16x32_bf16 v[104:107], v[152:155], v[194:197], v[104:107]
	v_mfma_f32_16x16x32_bf16 v[92:95], v[144:147], v[202:205], v[92:95]
	v_mfma_f32_16x16x32_bf16 v[88:91], v[152:155], v[202:205], v[88:91]
	v_mfma_f32_16x16x32_bf16 v[76:79], v[144:147], v[214:217], v[76:79]
	v_mfma_f32_16x16x32_bf16 v[72:75], v[152:155], v[214:217], v[72:75]
	v_mfma_f32_16x16x32_bf16 v[124:127], v[148:151], v[190:193], v[124:127]
	v_mfma_f32_16x16x32_bf16 v[120:123], v[156:159], v[190:193], v[120:123]
	v_mfma_f32_16x16x32_bf16 v[108:111], v[148:151], v[198:201], v[108:111]
	v_mfma_f32_16x16x32_bf16 v[104:107], v[156:159], v[198:201], v[104:107]
	v_mfma_f32_16x16x32_bf16 v[92:95], v[148:151], v[210:213], v[92:95]
	v_mfma_f32_16x16x32_bf16 v[88:91], v[156:159], v[210:213], v[88:91]
	v_mfma_f32_16x16x32_bf16 v[76:79], v[148:151], v[218:221], v[76:79]
	v_mfma_f32_16x16x32_bf16 v[72:75], v[156:159], v[218:221], v[72:75]
	v_mfma_f32_16x16x32_bf16 v[116:119], v[160:163], v[186:189], v[116:119]
	v_mfma_f32_16x16x32_bf16 v[112:115], v[168:171], v[186:189], v[112:115]
	v_mfma_f32_16x16x32_bf16 v[100:103], v[160:163], v[194:197], v[100:103]
	v_mfma_f32_16x16x32_bf16 v[96:99], v[168:171], v[194:197], v[96:99]
	v_mfma_f32_16x16x32_bf16 v[84:87], v[160:163], v[202:205], v[84:87]
	v_mfma_f32_16x16x32_bf16 v[80:83], v[168:171], v[202:205], v[80:83]
	v_mfma_f32_16x16x32_bf16 v[68:71], v[160:163], v[214:217], v[68:71]
	v_mfma_f32_16x16x32_bf16 v[64:67], v[168:171], v[214:217], v[64:67]
	v_mfma_f32_16x16x32_bf16 v[116:119], v[164:167], v[190:193], v[116:119]
	v_mfma_f32_16x16x32_bf16 v[112:115], v[182:185], v[190:193], v[112:115]
	v_mfma_f32_16x16x32_bf16 v[100:103], v[164:167], v[198:201], v[100:103]
	v_mfma_f32_16x16x32_bf16 v[96:99], v[182:185], v[198:201], v[96:99]
	v_mfma_f32_16x16x32_bf16 v[84:87], v[164:167], v[210:213], v[84:87]
	v_mfma_f32_16x16x32_bf16 v[80:83], v[182:185], v[210:213], v[80:83]
	v_mfma_f32_16x16x32_bf16 v[68:71], v[164:167], v[218:221], v[68:71]
	v_mfma_f32_16x16x32_bf16 v[64:67], v[182:185], v[218:221], v[64:67]
	s_setprio 0
	s_barrier
	s_add_i32 s48, s64, s23
	s_mov_b32 m0, s48
	ds_read_b128 v[186:189], v180 offset:49152
	ds_read_b128 v[190:193], v180 offset:50176
	ds_read_b128 v[194:197], v180 offset:51200
	ds_read_b128 v[198:201], v180 offset:52224
	ds_read_b128 v[202:205], v180 offset:53248
	ds_read_b128 v[210:213], v180 offset:54272
	ds_read_b128 v[214:217], v180 offset:55296
	ds_read_b128 v[218:221], v180 offset:56320
	global_load_lds_dwordx4 v130, s[98:99]
	s_add_i32 m0, s48, 0x2000
	s_add_u32 s46, s46, 0x40080
	s_addc_u32 s47, s47, 0
	s_add_i32 s48, s65, s23
	global_load_lds_dwordx4 v134, s[98:99]
	s_mov_b32 m0, s48
	s_nop 0
	global_load_lds_dwordx4 v130, s[46:47]
	s_add_i32 m0, s48, 0x2000
	s_nop 0
	global_load_lds_dwordx4 v134, s[46:47]
	s_mov_b32 m0, s54
	s_nop 0
	global_load_lds_dwordx4 v128, s[100:101]
	s_mov_b32 m0, s55
	s_nop 0
	global_load_lds_dwordx4 v132, s[100:101]
	s_waitcnt vmcnt(8)
	s_waitcnt lgkmcnt(0)
	s_barrier
	s_setprio 1
	s_waitcnt lgkmcnt(0)
	v_mfma_f32_16x16x32_bf16 v[60:63], v[144:147], v[186:189], v[60:63]
	v_mfma_f32_16x16x32_bf16 v[56:59], v[152:155], v[186:189], v[56:59]
	v_mfma_f32_16x16x32_bf16 v[44:47], v[144:147], v[194:197], v[44:47]
	v_mfma_f32_16x16x32_bf16 v[40:43], v[152:155], v[194:197], v[40:43]
	v_mfma_f32_16x16x32_bf16 v[28:31], v[144:147], v[202:205], v[28:31]
	v_mfma_f32_16x16x32_bf16 v[24:27], v[152:155], v[202:205], v[24:27]
	v_mfma_f32_16x16x32_bf16 v[12:15], v[144:147], v[214:217], v[12:15]
	v_mfma_f32_16x16x32_bf16 v[8:11], v[152:155], v[214:217], v[8:11]
	v_mfma_f32_16x16x32_bf16 v[60:63], v[148:151], v[190:193], v[60:63]
	v_mfma_f32_16x16x32_bf16 v[56:59], v[156:159], v[190:193], v[56:59]
	v_mfma_f32_16x16x32_bf16 v[44:47], v[148:151], v[198:201], v[44:47]
	v_mfma_f32_16x16x32_bf16 v[40:43], v[156:159], v[198:201], v[40:43]
	v_mfma_f32_16x16x32_bf16 v[28:31], v[148:151], v[210:213], v[28:31]
	v_mfma_f32_16x16x32_bf16 v[24:27], v[156:159], v[210:213], v[24:27]
	v_mfma_f32_16x16x32_bf16 v[12:15], v[148:151], v[218:221], v[12:15]
	v_mfma_f32_16x16x32_bf16 v[8:11], v[156:159], v[218:221], v[8:11]
	v_mfma_f32_16x16x32_bf16 v[52:55], v[160:163], v[186:189], v[52:55]
	v_mfma_f32_16x16x32_bf16 v[48:51], v[168:171], v[186:189], v[48:51]
	v_mfma_f32_16x16x32_bf16 v[36:39], v[160:163], v[194:197], v[36:39]
	v_mfma_f32_16x16x32_bf16 v[32:35], v[168:171], v[194:197], v[32:35]
	v_mfma_f32_16x16x32_bf16 v[20:23], v[160:163], v[202:205], v[20:23]
	v_mfma_f32_16x16x32_bf16 v[16:19], v[168:171], v[202:205], v[16:19]
	v_mfma_f32_16x16x32_bf16 v[4:7], v[160:163], v[214:217], v[4:7]
	v_mfma_f32_16x16x32_bf16 v[0:3], v[168:171], v[214:217], v[0:3]
	v_mfma_f32_16x16x32_bf16 v[52:55], v[164:167], v[190:193], v[52:55]
	v_mfma_f32_16x16x32_bf16 v[48:51], v[182:185], v[190:193], v[48:51]
	v_mfma_f32_16x16x32_bf16 v[36:39], v[164:167], v[198:201], v[36:39]
	v_mfma_f32_16x16x32_bf16 v[32:35], v[182:185], v[198:201], v[32:35]
	v_mfma_f32_16x16x32_bf16 v[20:23], v[164:167], v[210:213], v[20:23]
	v_mfma_f32_16x16x32_bf16 v[16:19], v[182:185], v[210:213], v[16:19]
	v_mfma_f32_16x16x32_bf16 v[4:7], v[164:167], v[218:221], v[4:7]
	v_mfma_f32_16x16x32_bf16 v[0:3], v[182:185], v[218:221], v[0:3]
	s_setprio 0
	s_barrier
	s_add_i32 s63, s63, 2
	s_add_u32 s44, s44, 0x100
	s_addc_u32 s45, s45, 0
	s_add_u32 s61, s61, 0x100
	s_addc_u32 s62, s62, 0
	s_cmp_gt_u32 s63, 13
	s_cbranch_scc0 .LBB0_245
.Lkexit_0:
	s_and_b64 vcc, exec, s[18:19]
	s_cbranch_vccz .LBB0_248
	s_barrier

.LBB0_491:
	s_ashr_i32 s37, s36, 31
	s_lshl_b64 s[38:39], s[36:37], 19
	s_add_u32 s38, s2, s38
	s_addc_u32 s39, s31, s39
	s_and_b64 s[40:41], s[8:9], exec
	s_cselect_b32 s37, s39, s47
	s_cselect_b32 s43, s38, s46
	s_ashr_i32 s25, s24, 31
	s_lshl_b64 s[40:41], s[24:25], 19
	s_add_u32 s40, s34, s40
	s_addc_u32 s41, s35, s41
	s_and_b64 s[50:51], s[8:9], exec
	s_cselect_b32 s25, s41, s49
	s_cselect_b32 s63, s40, s48
	s_add_u32 s46, s46, 0x40080
	s_addc_u32 s47, s47, 0
	s_add_u32 s64, s48, 0x100
	s_addc_u32 s65, s49, 0
	s_mov_b32 s66, -2
	s_waitcnt lgkmcnt(0)
	ds_read_b128 v[128:131], v179
	ds_read_b128 v[132:135], v179 offset:1024
	ds_read_b128 v[136:139], v179 offset:2048
	ds_read_b128 v[140:143], v179 offset:3072
	ds_read_b128 v[144:147], v187
	ds_read_b128 v[148:151], v187 offset:1024
	ds_read_b128 v[180:183], v187 offset:2048
	ds_read_b128 v[188:191], v187 offset:3072
	s_add_u32 s48, s46, 0xfffc0080
	s_addc_u32 s49, s47, -1
	s_cmp_eq_u32 s66, 12
	s_cselect_b32 s51, s37, s49
	s_cselect_b32 s50, s43, s48
	s_cselect_b32 s49, s25, s65
	s_cselect_b32 s48, s63, s64
	s_add_i32 m0, s45, 0xc000
	ds_read_b128 v[196:199], v195
	ds_read_b128 v[202:205], v195 offset:1024
	ds_read_b128 v[210:213], v195 offset:2048
	ds_read_b128 v[214:217], v195 offset:3072
	ds_read_b128 v[218:221], v195 offset:4096
	ds_read_b128 v[222:225], v195 offset:5120
	ds_read_b128 v[226:229], v195 offset:6144
	ds_read_b128 v[230:233], v195 offset:7168
	global_load_lds_dwordx4 v160, s[46:47]
	s_add_i32 m0, s45, 0xe000
	s_nop 0
	global_load_lds_dwordx4 v162, s[46:47]
	s_waitcnt vmcnt(8)
	s_waitcnt lgkmcnt(0)
	s_barrier
	s_setprio 1
	s_waitcnt lgkmcnt(0)
	v_mfma_f32_16x16x32_bf16 v[124:127], v[128:131], v[196:199], 0
	v_mfma_f32_16x16x32_bf16 v[120:123], v[136:139], v[196:199], 0
	v_mfma_f32_16x16x32_bf16 v[108:111], v[128:131], v[210:213], 0
	v_mfma_f32_16x16x32_bf16 v[104:107], v[136:139], v[210:213], 0
	v_mfma_f32_16x16x32_bf16 v[92:95], v[128:131], v[218:221], 0
	v_mfma_f32_16x16x32_bf16 v[88:91], v[136:139], v[218:221], 0
	v_mfma_f32_16x16x32_bf16 v[76:79], v[128:131], v[226:229], 0
	v_mfma_f32_16x16x32_bf16 v[72:75], v[136:139], v[226:229], 0
	v_mfma_f32_16x16x32_bf16 v[124:127], v[132:135], v[202:205], v[124:127]
	v_mfma_f32_16x16x32_bf16 v[120:123], v[140:143], v[202:205], v[120:123]
	v_mfma_f32_16x16x32_bf16 v[108:111], v[132:135], v[214:217], v[108:111]
	v_mfma_f32_16x16x32_bf16 v[104:107], v[140:143], v[214:217], v[104:107]
	v_mfma_f32_16x16x32_bf16 v[92:95], v[132:135], v[222:225], v[92:95]
	v_mfma_f32_16x16x32_bf16 v[88:91], v[140:143], v[222:225], v[88:91]
	v_mfma_f32_16x16x32_bf16 v[76:79], v[132:135], v[230:233], v[76:79]
	v_mfma_f32_16x16x32_bf16 v[72:75], v[140:143], v[230:233], v[72:75]
	v_mfma_f32_16x16x32_bf16 v[116:119], v[144:147], v[196:199], 0
	v_mfma_f32_16x16x32_bf16 v[112:115], v[180:183], v[196:199], 0
	v_mfma_f32_16x16x32_bf16 v[100:103], v[144:147], v[210:213], 0
	v_mfma_f32_16x16x32_bf16 v[96:99], v[180:183], v[210:213], 0
	v_mfma_f32_16x16x32_bf16 v[84:87], v[144:147], v[218:221], 0
	v_mfma_f32_16x16x32_bf16 v[80:83], v[180:183], v[218:221], 0
	v_mfma_f32_16x16x32_bf16 v[68:71], v[144:147], v[226:229], 0
	v_mfma_f32_16x16x32_bf16 v[64:67], v[180:183], v[226:229], 0
	v_mfma_f32_16x16x32_bf16 v[116:119], v[148:151], v[202:205], v[116:119]
	v_mfma_f32_16x16x32_bf16 v[112:115], v[188:191], v[202:205], v[112:115]
	v_mfma_f32_16x16x32_bf16 v[100:103], v[148:151], v[214:217], v[100:103]
	v_mfma_f32_16x16x32_bf16 v[96:99], v[188:191], v[214:217], v[96:99]
	v_mfma_f32_16x16x32_bf16 v[84:87], v[148:151], v[222:225], v[84:87]
	v_mfma_f32_16x16x32_bf16 v[80:83], v[188:191], v[222:225], v[80:83]
	v_mfma_f32_16x16x32_bf16 v[68:71], v[148:151], v[230:233], v[68:71]
	v_mfma_f32_16x16x32_bf16 v[64:67], v[188:191], v[230:233], v[64:67]
	s_setprio 0
	s_barrier
	s_add_u32 s98, s48, s20
	s_addc_u32 s99, s49, s21
	s_add_u32 s100, s50, s20
	s_addc_u32 s101, s51, s21
	s_add_i32 s67, s61, s52
	s_mov_b32 m0, s67
	ds_read_b128 v[196:199], v195 offset:16384
	ds_read_b128 v[202:205], v195 offset:17408
	ds_read_b128 v[210:213], v195 offset:18432
	ds_read_b128 v[214:217], v195 offset:19456
	ds_read_b128 v[218:221], v195 offset:20480
	ds_read_b128 v[222:225], v195 offset:21504
	ds_read_b128 v[226:229], v195 offset:22528
	ds_read_b128 v[230:233], v195 offset:23552
	global_load_lds_dwordx4 v154, s[48:49]
	s_add_i32 m0, s67, 0x2000
	s_add_u32 s68, s48, 0x40000
	s_addc_u32 s69, s49, 0
	s_add_i32 s67, s62, s52
	global_load_lds_dwordx4 v158, s[48:49]
	s_mov_b32 m0, s67
	s_nop 0
	global_load_lds_dwordx4 v154, s[68:69]
	s_add_i32 m0, s67, 0x2000
	s_nop 0
	global_load_lds_dwordx4 v158, s[68:69]
	s_mov_b32 m0, s45
	s_nop 0
	global_load_lds_dwordx4 v152, s[50:51]
	s_mov_b32 m0, s53
	s_nop 0
	global_load_lds_dwordx4 v156, s[50:51]
	s_waitcnt vmcnt(8)
	s_waitcnt lgkmcnt(0)
	s_barrier
	s_setprio 1
	s_waitcnt lgkmcnt(0)
	v_mfma_f32_16x16x32_bf16 v[60:63], v[128:131], v[196:199], 0
	v_mfma_f32_16x16x32_bf16 v[56:59], v[136:139], v[196:199], 0
	v_mfma_f32_16x16x32_bf16 v[44:47], v[128:131], v[210:213], 0
	v_mfma_f32_16x16x32_bf16 v[40:43], v[136:139], v[210:213], 0
	v_mfma_f32_16x16x32_bf16 v[28:31], v[128:131], v[218:221], 0
	v_mfma_f32_16x16x32_bf16 v[24:27], v[136:139], v[218:221], 0
	v_mfma_f32_16x16x32_bf16 v[12:15], v[128:131], v[226:229], 0
	v_mfma_f32_16x16x32_bf16 v[8:11], v[136:139], v[226:229], 0
	v_mfma_f32_16x16x32_bf16 v[60:63], v[132:135], v[202:205], v[60:63]
	v_mfma_f32_16x16x32_bf16 v[56:59], v[140:143], v[202:205], v[56:59]
	v_mfma_f32_16x16x32_bf16 v[44:47], v[132:135], v[214:217], v[44:47]
	v_mfma_f32_16x16x32_bf16 v[40:43], v[140:143], v[214:217], v[40:43]
	v_mfma_f32_16x16x32_bf16 v[28:31], v[132:135], v[222:225], v[28:31]
	v_mfma_f32_16x16x32_bf16 v[24:27], v[140:143], v[222:225], v[24:27]
	v_mfma_f32_16x16x32_bf16 v[12:15], v[132:135], v[230:233], v[12:15]
	v_mfma_f32_16x16x32_bf16 v[8:11], v[140:143], v[230:233], v[8:11]
	v_mfma_f32_16x16x32_bf16 v[52:55], v[144:147], v[196:199], 0
	v_mfma_f32_16x16x32_bf16 v[48:51], v[180:183], v[196:199], 0
	v_mfma_f32_16x16x32_bf16 v[36:39], v[144:147], v[210:213], 0
	v_mfma_f32_16x16x32_bf16 v[32:35], v[180:183], v[210:213], 0
	v_mfma_f32_16x16x32_bf16 v[20:23], v[144:147], v[218:221], 0
	v_mfma_f32_16x16x32_bf16 v[16:19], v[180:183], v[218:221], 0
	v_mfma_f32_16x16x32_bf16 v[4:7], v[144:147], v[226:229], 0
	v_mfma_f32_16x16x32_bf16 v[0:3], v[180:183], v[226:229], 0
	v_mfma_f32_16x16x32_bf16 v[52:55], v[148:151], v[202:205], v[52:55]
	v_mfma_f32_16x16x32_bf16 v[48:51], v[188:191], v[202:205], v[48:51]
	v_mfma_f32_16x16x32_bf16 v[36:39], v[148:151], v[214:217], v[36:39]
	v_mfma_f32_16x16x32_bf16 v[32:35], v[188:191], v[214:217], v[32:35]
	v_mfma_f32_16x16x32_bf16 v[20:23], v[148:151], v[222:225], v[20:23]
	v_mfma_f32_16x16x32_bf16 v[16:19], v[188:191], v[222:225], v[16:19]
	v_mfma_f32_16x16x32_bf16 v[4:7], v[148:151], v[230:233], v[4:7]
	v_mfma_f32_16x16x32_bf16 v[0:3], v[188:191], v[230:233], v[0:3]
	s_setprio 0
	s_barrier
	s_add_i32 s67, 0, 0x18000
	s_add_i32 s68, 0, 0x1c000
	v_add_u32_e32 v140, s67, v173
	v_add_u32_e32 v170, s68, v173
	ds_read_b128 v[128:131], v140
	ds_read_b128 v[132:135], v140 offset:1024
	ds_read_b128 v[136:139], v140 offset:2048
	ds_read_b128 v[140:143], v140 offset:3072
	ds_read_b128 v[144:147], v170
	ds_read_b128 v[148:151], v170 offset:1024
	ds_read_b128 v[180:183], v170 offset:2048
	ds_read_b128 v[188:191], v170 offset:3072
	s_add_u32 s50, s50, 0x40000
	s_addc_u32 s51, s51, 0
	s_mov_b32 m0, s54
	ds_read_b128 v[196:199], v195 offset:32768
	ds_read_b128 v[202:205], v195 offset:33792
	ds_read_b128 v[210:213], v195 offset:34816
	ds_read_b128 v[214:217], v195 offset:35840
	ds_read_b128 v[218:221], v195 offset:36864
	ds_read_b128 v[222:225], v195 offset:37888
	ds_read_b128 v[226:229], v195 offset:38912
	ds_read_b128 v[230:233], v195 offset:39936
	global_load_lds_dwordx4 v152, s[50:51]
	s_mov_b32 m0, s55
	s_nop 0
	global_load_lds_dwordx4 v156, s[50:51]
	s_waitcnt vmcnt(8)
	s_waitcnt lgkmcnt(0)
	s_barrier
	s_setprio 1
	s_waitcnt lgkmcnt(0)
	v_mfma_f32_16x16x32_bf16 v[124:127], v[128:131], v[196:199], v[124:127]
	v_mfma_f32_16x16x32_bf16 v[120:123], v[136:139], v[196:199], v[120:123]
	v_mfma_f32_16x16x32_bf16 v[108:111], v[128:131], v[210:213], v[108:111]
	v_mfma_f32_16x16x32_bf16 v[104:107], v[136:139], v[210:213], v[104:107]
	v_mfma_f32_16x16x32_bf16 v[92:95], v[128:131], v[218:221], v[92:95]
	v_mfma_f32_16x16x32_bf16 v[88:91], v[136:139], v[218:221], v[88:91]
	v_mfma_f32_16x16x32_bf16 v[76:79], v[128:131], v[226:229], v[76:79]
	v_mfma_f32_16x16x32_bf16 v[72:75], v[136:139], v[226:229], v[72:75]
	v_mfma_f32_16x16x32_bf16 v[124:127], v[132:135], v[202:205], v[124:127]
	v_mfma_f32_16x16x32_bf16 v[120:123], v[140:143], v[202:205], v[120:123]
	v_mfma_f32_16x16x32_bf16 v[108:111], v[132:135], v[214:217], v[108:111]
	v_mfma_f32_16x16x32_bf16 v[104:107], v[140:143], v[214:217], v[104:107]
	v_mfma_f32_16x16x32_bf16 v[92:95], v[132:135], v[222:225], v[92:95]
	v_mfma_f32_16x16x32_bf16 v[88:91], v[140:143], v[222:225], v[88:91]
	v_mfma_f32_16x16x32_bf16 v[76:79], v[132:135], v[230:233], v[76:79]
	v_mfma_f32_16x16x32_bf16 v[72:75], v[140:143], v[230:233], v[72:75]
	v_mfma_f32_16x16x32_bf16 v[116:119], v[144:147], v[196:199], v[116:119]
	v_mfma_f32_16x16x32_bf16 v[112:115], v[180:183], v[196:199], v[112:115]
	v_mfma_f32_16x16x32_bf16 v[100:103], v[144:147], v[210:213], v[100:103]
	v_mfma_f32_16x16x32_bf16 v[96:99], v[180:183], v[210:213], v[96:99]
	v_mfma_f32_16x16x32_bf16 v[84:87], v[144:147], v[218:221], v[84:87]
	v_mfma_f32_16x16x32_bf16 v[80:83], v[180:183], v[218:221], v[80:83]
	v_mfma_f32_16x16x32_bf16 v[68:71], v[144:147], v[226:229], v[68:71]
	v_mfma_f32_16x16x32_bf16 v[64:67], v[180:183], v[226:229], v[64:67]
	v_mfma_f32_16x16x32_bf16 v[116:119], v[148:151], v[202:205], v[116:119]
	v_mfma_f32_16x16x32_bf16 v[112:115], v[188:191], v[202:205], v[112:115]
	v_mfma_f32_16x16x32_bf16 v[100:103], v[148:151], v[214:217], v[100:103]
	v_mfma_f32_16x16x32_bf16 v[96:99], v[188:191], v[214:217], v[96:99]
	v_mfma_f32_16x16x32_bf16 v[84:87], v[148:151], v[222:225], v[84:87]
	v_mfma_f32_16x16x32_bf16 v[80:83], v[188:191], v[222:225], v[80:83]
	v_mfma_f32_16x16x32_bf16 v[68:71], v[148:151], v[230:233], v[68:71]
	v_mfma_f32_16x16x32_bf16 v[64:67], v[188:191], v[230:233], v[64:67]
	s_setprio 0
	s_barrier
	s_add_i32 s50, s67, s52
	s_mov_b32 m0, s50
	ds_read_b128 v[196:199], v195 offset:49152
	ds_read_b128 v[202:205], v195 offset:50176
	ds_read_b128 v[210:213], v195 offset:51200
	ds_read_b128 v[214:217], v195 offset:52224
	ds_read_b128 v[218:221], v195 offset:53248
	ds_read_b128 v[222:225], v195 offset:54272
	ds_read_b128 v[226:229], v195 offset:55296
	ds_read_b128 v[230:233], v195 offset:56320
	global_load_lds_dwordx4 v154, s[98:99]
	s_add_i32 m0, s50, 0x2000
	s_add_u32 s48, s48, 0x40080
	s_addc_u32 s49, s49, 0
	s_add_i32 s50, s68, s52
	global_load_lds_dwordx4 v158, s[98:99]
	s_mov_b32 m0, s50
	s_nop 0
	global_load_lds_dwordx4 v154, s[48:49]
	s_add_i32 m0, s50, 0x2000
	s_nop 0
	global_load_lds_dwordx4 v158, s[48:49]
	s_mov_b32 m0, s57
	s_nop 0
	global_load_lds_dwordx4 v152, s[100:101]
	s_mov_b32 m0, s58
	s_nop 0
	global_load_lds_dwordx4 v156, s[100:101]
	s_waitcnt vmcnt(8)
	s_waitcnt lgkmcnt(0)
	s_barrier
	s_setprio 1
	s_waitcnt lgkmcnt(0)
	v_mfma_f32_16x16x32_bf16 v[60:63], v[128:131], v[196:199], v[60:63]
	v_mfma_f32_16x16x32_bf16 v[56:59], v[136:139], v[196:199], v[56:59]
	v_mfma_f32_16x16x32_bf16 v[44:47], v[128:131], v[210:213], v[44:47]
	v_mfma_f32_16x16x32_bf16 v[40:43], v[136:139], v[210:213], v[40:43]
	v_mfma_f32_16x16x32_bf16 v[28:31], v[128:131], v[218:221], v[28:31]
	v_mfma_f32_16x16x32_bf16 v[24:27], v[136:139], v[218:221], v[24:27]
	v_mfma_f32_16x16x32_bf16 v[12:15], v[128:131], v[226:229], v[12:15]
	v_mfma_f32_16x16x32_bf16 v[8:11], v[136:139], v[226:229], v[8:11]
	v_mfma_f32_16x16x32_bf16 v[60:63], v[132:135], v[202:205], v[60:63]
	v_mfma_f32_16x16x32_bf16 v[56:59], v[140:143], v[202:205], v[56:59]
	v_mfma_f32_16x16x32_bf16 v[44:47], v[132:135], v[214:217], v[44:47]
	v_mfma_f32_16x16x32_bf16 v[40:43], v[140:143], v[214:217], v[40:43]
	v_mfma_f32_16x16x32_bf16 v[28:31], v[132:135], v[222:225], v[28:31]
	v_mfma_f32_16x16x32_bf16 v[24:27], v[140:143], v[222:225], v[24:27]
	v_mfma_f32_16x16x32_bf16 v[12:15], v[132:135], v[230:233], v[12:15]
	v_mfma_f32_16x16x32_bf16 v[8:11], v[140:143], v[230:233], v[8:11]
	v_mfma_f32_16x16x32_bf16 v[52:55], v[144:147], v[196:199], v[52:55]
	v_mfma_f32_16x16x32_bf16 v[48:51], v[180:183], v[196:199], v[48:51]
	v_mfma_f32_16x16x32_bf16 v[36:39], v[144:147], v[210:213], v[36:39]
	v_mfma_f32_16x16x32_bf16 v[32:35], v[180:183], v[210:213], v[32:35]
	v_mfma_f32_16x16x32_bf16 v[20:23], v[144:147], v[218:221], v[20:23]
	v_mfma_f32_16x16x32_bf16 v[16:19], v[180:183], v[218:221], v[16:19]
	v_mfma_f32_16x16x32_bf16 v[4:7], v[144:147], v[226:229], v[4:7]
	v_mfma_f32_16x16x32_bf16 v[0:3], v[180:183], v[226:229], v[0:3]
	v_mfma_f32_16x16x32_bf16 v[52:55], v[148:151], v[202:205], v[52:55]
	v_mfma_f32_16x16x32_bf16 v[48:51], v[188:191], v[202:205], v[48:51]
	v_mfma_f32_16x16x32_bf16 v[36:39], v[148:151], v[214:217], v[36:39]
	v_mfma_f32_16x16x32_bf16 v[32:35], v[188:191], v[214:217], v[32:35]
	v_mfma_f32_16x16x32_bf16 v[20:23], v[148:151], v[222:225], v[20:23]
	v_mfma_f32_16x16x32_bf16 v[16:19], v[188:191], v[222:225], v[16:19]
	v_mfma_f32_16x16x32_bf16 v[4:7], v[148:151], v[230:233], v[4:7]
	v_mfma_f32_16x16x32_bf16 v[0:3], v[188:191], v[230:233], v[0:3]
	s_setprio 0
	s_barrier
	s_add_i32 s66, s66, 2
	s_add_u32 s46, s46, 0x100
	s_addc_u32 s47, s47, 0
	s_add_u32 s64, s64, 0x100
	s_addc_u32 s65, s65, 0
	s_cmp_gt_u32 s66, 13
	s_cbranch_scc1 .Lkexit_1
.LBB0_492:
	ds_read_b128 v[128:131], v179
	ds_read_b128 v[132:135], v179 offset:1024
	ds_read_b128 v[136:139], v179 offset:2048
	ds_read_b128 v[140:143], v179 offset:3072
	ds_read_b128 v[144:147], v187
	ds_read_b128 v[148:151], v187 offset:1024
	ds_read_b128 v[180:183], v187 offset:2048
	ds_read_b128 v[188:191], v187 offset:3072
	s_add_u32 s48, s46, 0xfffc0080
	s_addc_u32 s49, s47, -1
	s_cmp_eq_u32 s66, 12
	s_cselect_b32 s51, s37, s49
	s_cselect_b32 s50, s43, s48
	s_cselect_b32 s49, s25, s65
	s_cselect_b32 s48, s63, s64
	s_add_i32 m0, s45, 0xc000
	ds_read_b128 v[196:199], v195
	ds_read_b128 v[202:205], v195 offset:1024
	ds_read_b128 v[210:213], v195 offset:2048
	ds_read_b128 v[214:217], v195 offset:3072
	ds_read_b128 v[218:221], v195 offset:4096
	ds_read_b128 v[222:225], v195 offset:5120
	ds_read_b128 v[226:229], v195 offset:6144
	ds_read_b128 v[230:233], v195 offset:7168
	global_load_lds_dwordx4 v160, s[46:47]
	s_add_i32 m0, s45, 0xe000
	s_nop 0
	global_load_lds_dwordx4 v162, s[46:47]
	s_waitcnt vmcnt(8)
	s_waitcnt lgkmcnt(0)
	s_barrier
	s_setprio 1
	s_waitcnt lgkmcnt(0)
	v_mfma_f32_16x16x32_bf16 v[124:127], v[128:131], v[196:199], v[124:127]
	v_mfma_f32_16x16x32_bf16 v[120:123], v[136:139], v[196:199], v[120:123]
	v_mfma_f32_16x16x32_bf16 v[108:111], v[128:131], v[210:213], v[108:111]
	v_mfma_f32_16x16x32_bf16 v[104:107], v[136:139], v[210:213], v[104:107]
	v_mfma_f32_16x16x32_bf16 v[92:95], v[128:131], v[218:221], v[92:95]
	v_mfma_f32_16x16x32_bf16 v[88:91], v[136:139], v[218:221], v[88:91]
	v_mfma_f32_16x16x32_bf16 v[76:79], v[128:131], v[226:229], v[76:79]
	v_mfma_f32_16x16x32_bf16 v[72:75], v[136:139], v[226:229], v[72:75]
	v_mfma_f32_16x16x32_bf16 v[124:127], v[132:135], v[202:205], v[124:127]
	v_mfma_f32_16x16x32_bf16 v[120:123], v[140:143], v[202:205], v[120:123]
	v_mfma_f32_16x16x32_bf16 v[108:111], v[132:135], v[214:217], v[108:111]
	v_mfma_f32_16x16x32_bf16 v[104:107], v[140:143], v[214:217], v[104:107]
	v_mfma_f32_16x16x32_bf16 v[92:95], v[132:135], v[222:225], v[92:95]
	v_mfma_f32_16x16x32_bf16 v[88:91], v[140:143], v[222:225], v[88:91]
	v_mfma_f32_16x16x32_bf16 v[76:79], v[132:135], v[230:233], v[76:79]
	v_mfma_f32_16x16x32_bf16 v[72:75], v[140:143], v[230:233], v[72:75]
	v_mfma_f32_16x16x32_bf16 v[116:119], v[144:147], v[196:199], v[116:119]
	v_mfma_f32_16x16x32_bf16 v[112:115], v[180:183], v[196:199], v[112:115]
	v_mfma_f32_16x16x32_bf16 v[100:103], v[144:147], v[210:213], v[100:103]
	v_mfma_f32_16x16x32_bf16 v[96:99], v[180:183], v[210:213], v[96:99]
	v_mfma_f32_16x16x32_bf16 v[84:87], v[144:147], v[218:221], v[84:87]
	v_mfma_f32_16x16x32_bf16 v[80:83], v[180:183], v[218:221], v[80:83]
	v_mfma_f32_16x16x32_bf16 v[68:71], v[144:147], v[226:229], v[68:71]
	v_mfma_f32_16x16x32_bf16 v[64:67], v[180:183], v[226:229], v[64:67]
	v_mfma_f32_16x16x32_bf16 v[116:119], v[148:151], v[202:205], v[116:119]
	v_mfma_f32_16x16x32_bf16 v[112:115], v[188:191], v[202:205], v[112:115]
	v_mfma_f32_16x16x32_bf16 v[100:103], v[148:151], v[214:217], v[100:103]
	v_mfma_f32_16x16x32_bf16 v[96:99], v[188:191], v[214:217], v[96:99]
	v_mfma_f32_16x16x32_bf16 v[84:87], v[148:151], v[222:225], v[84:87]
	v_mfma_f32_16x16x32_bf16 v[80:83], v[188:191], v[222:225], v[80:83]
	v_mfma_f32_16x16x32_bf16 v[68:71], v[148:151], v[230:233], v[68:71]
	v_mfma_f32_16x16x32_bf16 v[64:67], v[188:191], v[230:233], v[64:67]
	s_setprio 0
	s_barrier
	s_add_u32 s98, s48, s20
	s_addc_u32 s99, s49, s21
	s_add_u32 s100, s50, s20
	s_addc_u32 s101, s51, s21
	s_add_i32 s67, s61, s52
	s_mov_b32 m0, s67
	ds_read_b128 v[196:199], v195 offset:16384
	ds_read_b128 v[202:205], v195 offset:17408
	ds_read_b128 v[210:213], v195 offset:18432
	ds_read_b128 v[214:217], v195 offset:19456
	ds_read_b128 v[218:221], v195 offset:20480
	ds_read_b128 v[222:225], v195 offset:21504
	ds_read_b128 v[226:229], v195 offset:22528
	ds_read_b128 v[230:233], v195 offset:23552
	global_load_lds_dwordx4 v154, s[48:49]
	s_add_i32 m0, s67, 0x2000
	s_add_u32 s68, s48, 0x40000
	s_addc_u32 s69, s49, 0
	s_add_i32 s67, s62, s52
	global_load_lds_dwordx4 v158, s[48:49]
	s_mov_b32 m0, s67
	s_nop 0
	global_load_lds_dwordx4 v154, s[68:69]
	s_add_i32 m0, s67, 0x2000
	s_nop 0
	global_load_lds_dwordx4 v158, s[68:69]
	s_mov_b32 m0, s45
	s_nop 0
	global_load_lds_dwordx4 v152, s[50:51]
	s_mov_b32 m0, s53
	s_nop 0
	global_load_lds_dwordx4 v156, s[50:51]
	s_waitcnt vmcnt(8)
	s_waitcnt lgkmcnt(0)
	s_barrier
	s_setprio 1
	s_waitcnt lgkmcnt(0)
	v_mfma_f32_16x16x32_bf16 v[60:63], v[128:131], v[196:199], v[60:63]
	v_mfma_f32_16x16x32_bf16 v[56:59], v[136:139], v[196:199], v[56:59]
	v_mfma_f32_16x16x32_bf16 v[44:47], v[128:131], v[210:213], v[44:47]
	v_mfma_f32_16x16x32_bf16 v[40:43], v[136:139], v[210:213], v[40:43]
	v_mfma_f32_16x16x32_bf16 v[28:31], v[128:131], v[218:221], v[28:31]
	v_mfma_f32_16x16x32_bf16 v[24:27], v[136:139], v[218:221], v[24:27]
	v_mfma_f32_16x16x32_bf16 v[12:15], v[128:131], v[226:229], v[12:15]
	v_mfma_f32_16x16x32_bf16 v[8:11], v[136:139], v[226:229], v[8:11]
	v_mfma_f32_16x16x32_bf16 v[60:63], v[132:135], v[202:205], v[60:63]
	v_mfma_f32_16x16x32_bf16 v[56:59], v[140:143], v[202:205], v[56:59]
	v_mfma_f32_16x16x32_bf16 v[44:47], v[132:135], v[214:217], v[44:47]
	v_mfma_f32_16x16x32_bf16 v[40:43], v[140:143], v[214:217], v[40:43]
	v_mfma_f32_16x16x32_bf16 v[28:31], v[132:135], v[222:225], v[28:31]
	v_mfma_f32_16x16x32_bf16 v[24:27], v[140:143], v[222:225], v[24:27]
	v_mfma_f32_16x16x32_bf16 v[12:15], v[132:135], v[230:233], v[12:15]
	v_mfma_f32_16x16x32_bf16 v[8:11], v[140:143], v[230:233], v[8:11]
	v_mfma_f32_16x16x32_bf16 v[52:55], v[144:147], v[196:199], v[52:55]
	v_mfma_f32_16x16x32_bf16 v[48:51], v[180:183], v[196:199], v[48:51]
	v_mfma_f32_16x16x32_bf16 v[36:39], v[144:147], v[210:213], v[36:39]
	v_mfma_f32_16x16x32_bf16 v[32:35], v[180:183], v[210:213], v[32:35]
	v_mfma_f32_16x16x32_bf16 v[20:23], v[144:147], v[218:221], v[20:23]
	v_mfma_f32_16x16x32_bf16 v[16:19], v[180:183], v[218:221], v[16:19]
	v_mfma_f32_16x16x32_bf16 v[4:7], v[144:147], v[226:229], v[4:7]
	v_mfma_f32_16x16x32_bf16 v[0:3], v[180:183], v[226:229], v[0:3]
	v_mfma_f32_16x16x32_bf16 v[52:55], v[148:151], v[202:205], v[52:55]
	v_mfma_f32_16x16x32_bf16 v[48:51], v[188:191], v[202:205], v[48:51]
	v_mfma_f32_16x16x32_bf16 v[36:39], v[148:151], v[214:217], v[36:39]
	v_mfma_f32_16x16x32_bf16 v[32:35], v[188:191], v[214:217], v[32:35]
	v_mfma_f32_16x16x32_bf16 v[20:23], v[148:151], v[222:225], v[20:23]
	v_mfma_f32_16x16x32_bf16 v[16:19], v[188:191], v[222:225], v[16:19]
	v_mfma_f32_16x16x32_bf16 v[4:7], v[148:151], v[230:233], v[4:7]
	v_mfma_f32_16x16x32_bf16 v[0:3], v[188:191], v[230:233], v[0:3]
	s_setprio 0
	s_barrier
	s_add_i32 s67, 0, 0x18000
	s_add_i32 s68, 0, 0x1c000
	v_add_u32_e32 v140, s67, v173
	v_add_u32_e32 v170, s68, v173
	ds_read_b128 v[128:131], v140
	ds_read_b128 v[132:135], v140 offset:1024
	ds_read_b128 v[136:139], v140 offset:2048
	ds_read_b128 v[140:143], v140 offset:3072
	ds_read_b128 v[144:147], v170
	ds_read_b128 v[148:151], v170 offset:1024
	ds_read_b128 v[180:183], v170 offset:2048
	ds_read_b128 v[188:191], v170 offset:3072
	s_add_u32 s50, s50, 0x40000
	s_addc_u32 s51, s51, 0
	s_mov_b32 m0, s54
	ds_read_b128 v[196:199], v195 offset:32768
	ds_read_b128 v[202:205], v195 offset:33792
	ds_read_b128 v[210:213], v195 offset:34816
	ds_read_b128 v[214:217], v195 offset:35840
	ds_read_b128 v[218:221], v195 offset:36864
	ds_read_b128 v[222:225], v195 offset:37888
	ds_read_b128 v[226:229], v195 offset:38912
	ds_read_b128 v[230:233], v195 offset:39936
	global_load_lds_dwordx4 v152, s[50:51]
	s_mov_b32 m0, s55
	s_nop 0
	global_load_lds_dwordx4 v156, s[50:51]
	s_waitcnt vmcnt(8)
	s_waitcnt lgkmcnt(0)
	s_barrier
	s_setprio 1
	s_waitcnt lgkmcnt(0)
	v_mfma_f32_16x16x32_bf16 v[124:127], v[128:131], v[196:199], v[124:127]
	v_mfma_f32_16x16x32_bf16 v[120:123], v[136:139], v[196:199], v[120:123]
	v_mfma_f32_16x16x32_bf16 v[108:111], v[128:131], v[210:213], v[108:111]
	v_mfma_f32_16x16x32_bf16 v[104:107], v[136:139], v[210:213], v[104:107]
	v_mfma_f32_16x16x32_bf16 v[92:95], v[128:131], v[218:221], v[92:95]
	v_mfma_f32_16x16x32_bf16 v[88:91], v[136:139], v[218:221], v[88:91]
	v_mfma_f32_16x16x32_bf16 v[76:79], v[128:131], v[226:229], v[76:79]
	v_mfma_f32_16x16x32_bf16 v[72:75], v[136:139], v[226:229], v[72:75]
	v_mfma_f32_16x16x32_bf16 v[124:127], v[132:135], v[202:205], v[124:127]
	v_mfma_f32_16x16x32_bf16 v[120:123], v[140:143], v[202:205], v[120:123]
	v_mfma_f32_16x16x32_bf16 v[108:111], v[132:135], v[214:217], v[108:111]
	v_mfma_f32_16x16x32_bf16 v[104:107], v[140:143], v[214:217], v[104:107]
	v_mfma_f32_16x16x32_bf16 v[92:95], v[132:135], v[222:225], v[92:95]
	v_mfma_f32_16x16x32_bf16 v[88:91], v[140:143], v[222:225], v[88:91]
	v_mfma_f32_16x16x32_bf16 v[76:79], v[132:135], v[230:233], v[76:79]
	v_mfma_f32_16x16x32_bf16 v[72:75], v[140:143], v[230:233], v[72:75]
	v_mfma_f32_16x16x32_bf16 v[116:119], v[144:147], v[196:199], v[116:119]
	v_mfma_f32_16x16x32_bf16 v[112:115], v[180:183], v[196:199], v[112:115]
	v_mfma_f32_16x16x32_bf16 v[100:103], v[144:147], v[210:213], v[100:103]
	v_mfma_f32_16x16x32_bf16 v[96:99], v[180:183], v[210:213], v[96:99]
	v_mfma_f32_16x16x32_bf16 v[84:87], v[144:147], v[218:221], v[84:87]
	v_mfma_f32_16x16x32_bf16 v[80:83], v[180:183], v[218:221], v[80:83]
	v_mfma_f32_16x16x32_bf16 v[68:71], v[144:147], v[226:229], v[68:71]
	v_mfma_f32_16x16x32_bf16 v[64:67], v[180:183], v[226:229], v[64:67]
	v_mfma_f32_16x16x32_bf16 v[116:119], v[148:151], v[202:205], v[116:119]
	v_mfma_f32_16x16x32_bf16 v[112:115], v[188:191], v[202:205], v[112:115]
	v_mfma_f32_16x16x32_bf16 v[100:103], v[148:151], v[214:217], v[100:103]
	v_mfma_f32_16x16x32_bf16 v[96:99], v[188:191], v[214:217], v[96:99]
	v_mfma_f32_16x16x32_bf16 v[84:87], v[148:151], v[222:225], v[84:87]
	v_mfma_f32_16x16x32_bf16 v[80:83], v[188:191], v[222:225], v[80:83]
	v_mfma_f32_16x16x32_bf16 v[68:71], v[148:151], v[230:233], v[68:71]
	v_mfma_f32_16x16x32_bf16 v[64:67], v[188:191], v[230:233], v[64:67]
	s_setprio 0
	s_barrier
	s_add_i32 s50, s67, s52
	s_mov_b32 m0, s50
	ds_read_b128 v[196:199], v195 offset:49152
	ds_read_b128 v[202:205], v195 offset:50176
	ds_read_b128 v[210:213], v195 offset:51200
	ds_read_b128 v[214:217], v195 offset:52224
	ds_read_b128 v[218:221], v195 offset:53248
	ds_read_b128 v[222:225], v195 offset:54272
	ds_read_b128 v[226:229], v195 offset:55296
	ds_read_b128 v[230:233], v195 offset:56320
	global_load_lds_dwordx4 v154, s[98:99]
	s_add_i32 m0, s50, 0x2000
	s_add_u32 s48, s48, 0x40080
	s_addc_u32 s49, s49, 0
	s_add_i32 s50, s68, s52
	global_load_lds_dwordx4 v158, s[98:99]
	s_mov_b32 m0, s50
	s_nop 0
	global_load_lds_dwordx4 v154, s[48:49]
	s_add_i32 m0, s50, 0x2000
	s_nop 0
	global_load_lds_dwordx4 v158, s[48:49]
	s_mov_b32 m0, s57
	s_nop 0
	global_load_lds_dwordx4 v152, s[100:101]
	s_mov_b32 m0, s58
	s_nop 0
	global_load_lds_dwordx4 v156, s[100:101]
	s_waitcnt vmcnt(8)
	s_waitcnt lgkmcnt(0)
	s_barrier
	s_setprio 1
	s_waitcnt lgkmcnt(0)
	v_mfma_f32_16x16x32_bf16 v[60:63], v[128:131], v[196:199], v[60:63]
	v_mfma_f32_16x16x32_bf16 v[56:59], v[136:139], v[196:199], v[56:59]
	v_mfma_f32_16x16x32_bf16 v[44:47], v[128:131], v[210:213], v[44:47]
	v_mfma_f32_16x16x32_bf16 v[40:43], v[136:139], v[210:213], v[40:43]
	v_mfma_f32_16x16x32_bf16 v[28:31], v[128:131], v[218:221], v[28:31]
	v_mfma_f32_16x16x32_bf16 v[24:27], v[136:139], v[218:221], v[24:27]
	v_mfma_f32_16x16x32_bf16 v[12:15], v[128:131], v[226:229], v[12:15]
	v_mfma_f32_16x16x32_bf16 v[8:11], v[136:139], v[226:229], v[8:11]
	v_mfma_f32_16x16x32_bf16 v[60:63], v[132:135], v[202:205], v[60:63]
	v_mfma_f32_16x16x32_bf16 v[56:59], v[140:143], v[202:205], v[56:59]
	v_mfma_f32_16x16x32_bf16 v[44:47], v[132:135], v[214:217], v[44:47]
	v_mfma_f32_16x16x32_bf16 v[40:43], v[140:143], v[214:217], v[40:43]
	v_mfma_f32_16x16x32_bf16 v[28:31], v[132:135], v[222:225], v[28:31]
	v_mfma_f32_16x16x32_bf16 v[24:27], v[140:143], v[222:225], v[24:27]
	v_mfma_f32_16x16x32_bf16 v[12:15], v[132:135], v[230:233], v[12:15]
	v_mfma_f32_16x16x32_bf16 v[8:11], v[140:143], v[230:233], v[8:11]
	v_mfma_f32_16x16x32_bf16 v[52:55], v[144:147], v[196:199], v[52:55]
	v_mfma_f32_16x16x32_bf16 v[48:51], v[180:183], v[196:199], v[48:51]
	v_mfma_f32_16x16x32_bf16 v[36:39], v[144:147], v[210:213], v[36:39]
	v_mfma_f32_16x16x32_bf16 v[32:35], v[180:183], v[210:213], v[32:35]
	v_mfma_f32_16x16x32_bf16 v[20:23], v[144:147], v[218:221], v[20:23]
	v_mfma_f32_16x16x32_bf16 v[16:19], v[180:183], v[218:221], v[16:19]
	v_mfma_f32_16x16x32_bf16 v[4:7], v[144:147], v[226:229], v[4:7]
	v_mfma_f32_16x16x32_bf16 v[0:3], v[180:183], v[226:229], v[0:3]
	v_mfma_f32_16x16x32_bf16 v[52:55], v[148:151], v[202:205], v[52:55]
	v_mfma_f32_16x16x32_bf16 v[48:51], v[188:191], v[202:205], v[48:51]
	v_mfma_f32_16x16x32_bf16 v[36:39], v[148:151], v[214:217], v[36:39]
	v_mfma_f32_16x16x32_bf16 v[32:35], v[188:191], v[214:217], v[32:35]
	v_mfma_f32_16x16x32_bf16 v[20:23], v[148:151], v[222:225], v[20:23]
	v_mfma_f32_16x16x32_bf16 v[16:19], v[188:191], v[222:225], v[16:19]
	v_mfma_f32_16x16x32_bf16 v[4:7], v[148:151], v[230:233], v[4:7]
	v_mfma_f32_16x16x32_bf16 v[0:3], v[188:191], v[230:233], v[0:3]
	s_setprio 0
	s_barrier
	s_add_i32 s66, s66, 2
	s_add_u32 s46, s46, 0x100
	s_addc_u32 s47, s47, 0
	s_add_u32 s64, s64, 0x100
	s_addc_u32 s65, s65, 0
	s_cmp_gt_u32 s66, 13
	s_cbranch_scc0 .LBB0_492
.Lkexit_1:
	s_and_b64 vcc, exec, s[22:23]
	s_cbranch_vccz .LBB0_495
	s_barrier

.LBB0_577:
	s_ashr_i32 s47, s46, 31
	s_lshl_b64 s[48:49], s[46:47], 19
	s_add_u32 s48, s2, s48
	s_addc_u32 s49, s31, s49
	s_and_b64 s[50:51], s[10:11], exec
	s_cselect_b32 s47, s49, s57
	s_cselect_b32 s53, s48, s56
	s_ashr_i32 s45, s44, 31
	s_lshl_b64 s[50:51], s[44:45], 19
	s_add_u32 s50, s34, s50
	s_addc_u32 s51, s35, s51
	s_and_b64 s[60:61], s[10:11], exec
	s_cselect_b32 s45, s51, s59
	s_cselect_b32 s76, s50, s58
	s_add_u32 s77, s58, 0x100
	s_addc_u32 s78, s59, 0
	s_mov_b32 s79, -2
	ds_read_b128 v[72:75], v206
	ds_read_b128 v[76:79], v206 offset:1024
	ds_read_b128 v[80:83], v206 offset:2048
	ds_read_b128 v[84:87], v206 offset:3072
	ds_read_b128 v[116:119], v207
	ds_read_b128 v[120:123], v207 offset:1024
	ds_read_b128 v[124:127], v207 offset:2048
	ds_read_b128 v[128:131], v207 offset:3072
	s_add_u32 s58, s56, 0x100
	s_addc_u32 s59, s57, 0
	s_cmp_eq_u32 s79, 12
	s_cselect_b32 s63, s47, s59
	s_cselect_b32 s62, s53, s58
	s_cselect_b32 s61, s45, s78
	s_cselect_b32 s60, s76, s77
	s_add_i32 m0, s43, 0xc000
	ds_read_b128 v[140:143], v209
	ds_read_b128 v[164:167], v209 offset:1024
	ds_read_b128 v[168:171], v209 offset:2048
	ds_read_b128 v[192:195], v209 offset:3072
	ds_read_b128 v[196:199], v209 offset:4096
	ds_read_b128 v[200:203], v209 offset:5120
	ds_read_b128 v[212:215], v209 offset:6144
	ds_read_b128 v[216:219], v209 offset:7168
	global_load_lds_dwordx4 v184, s[56:57]
	s_add_i32 m0, s43, 0xe000
	s_nop 0
	global_load_lds_dwordx4 v186, s[56:57]
	s_waitcnt vmcnt(8)
	s_waitcnt lgkmcnt(0)
	s_barrier
	s_setprio 1
	s_waitcnt lgkmcnt(0)
	v_mfma_f32_16x16x32_bf16 v[160:163], v[72:75], v[140:143], 0
	v_mfma_f32_16x16x32_bf16 v[108:111], v[80:83], v[140:143], 0
	v_mfma_f32_16x16x32_bf16 v[156:159], v[72:75], v[168:171], 0
	v_mfma_f32_16x16x32_bf16 v[104:107], v[80:83], v[168:171], 0
	v_mfma_f32_16x16x32_bf16 v[144:147], v[72:75], v[196:199], 0
	v_mfma_f32_16x16x32_bf16 v[92:95], v[80:83], v[196:199], 0
	v_mfma_f32_16x16x32_bf16 v[152:155], v[72:75], v[212:215], 0
	v_mfma_f32_16x16x32_bf16 v[100:103], v[80:83], v[212:215], 0
	v_mfma_f32_16x16x32_bf16 v[160:163], v[76:79], v[164:167], v[160:163]
	v_mfma_f32_16x16x32_bf16 v[108:111], v[84:87], v[164:167], v[108:111]
	v_mfma_f32_16x16x32_bf16 v[156:159], v[76:79], v[192:195], v[156:159]
	v_mfma_f32_16x16x32_bf16 v[104:107], v[84:87], v[192:195], v[104:107]
	v_mfma_f32_16x16x32_bf16 v[144:147], v[76:79], v[200:203], v[144:147]
	v_mfma_f32_16x16x32_bf16 v[92:95], v[84:87], v[200:203], v[92:95]
	v_mfma_f32_16x16x32_bf16 v[152:155], v[76:79], v[216:219], v[152:155]
	v_mfma_f32_16x16x32_bf16 v[100:103], v[84:87], v[216:219], v[100:103]
	v_mfma_f32_16x16x32_bf16 v[148:151], v[116:119], v[140:143], 0
	v_mfma_f32_16x16x32_bf16 v[96:99], v[124:127], v[140:143], 0
	v_mfma_f32_16x16x32_bf16 v[136:139], v[116:119], v[168:171], 0
	v_mfma_f32_16x16x32_bf16 v[88:91], v[124:127], v[168:171], 0
	v_mfma_f32_16x16x32_bf16 v[132:135], v[116:119], v[196:199], 0
	v_mfma_f32_16x16x32_bf16 v[68:71], v[124:127], v[196:199], 0
	v_mfma_f32_16x16x32_bf16 v[112:115], v[116:119], v[212:215], 0
	v_mfma_f32_16x16x32_bf16 v[64:67], v[124:127], v[212:215], 0
	v_mfma_f32_16x16x32_bf16 v[148:151], v[120:123], v[164:167], v[148:151]
	v_mfma_f32_16x16x32_bf16 v[96:99], v[128:131], v[164:167], v[96:99]
	v_mfma_f32_16x16x32_bf16 v[136:139], v[120:123], v[192:195], v[136:139]
	v_mfma_f32_16x16x32_bf16 v[88:91], v[128:131], v[192:195], v[88:91]
	v_mfma_f32_16x16x32_bf16 v[132:135], v[120:123], v[200:203], v[132:135]
	v_mfma_f32_16x16x32_bf16 v[68:71], v[128:131], v[200:203], v[68:71]
	v_mfma_f32_16x16x32_bf16 v[112:115], v[120:123], v[216:219], v[112:115]
	v_mfma_f32_16x16x32_bf16 v[64:67], v[128:131], v[216:219], v[64:67]
	s_setprio 0
	s_barrier
	s_add_u32 s98, s60, s22
	s_addc_u32 s99, s61, s23
	s_add_u32 s100, s62, s22
	s_addc_u32 s101, s63, s23
	s_add_i32 s56, s73, s41
	s_mov_b32 m0, s56
	ds_read_b128 v[140:143], v209 offset:16384
	ds_read_b128 v[164:167], v209 offset:17408
	ds_read_b128 v[168:171], v209 offset:18432
	ds_read_b128 v[192:195], v209 offset:19456
	ds_read_b128 v[196:199], v209 offset:20480
	ds_read_b128 v[200:203], v209 offset:21504
	ds_read_b128 v[212:215], v209 offset:22528
	ds_read_b128 v[216:219], v209 offset:23552
	global_load_lds_dwordx4 v176, s[60:61]
	s_add_i32 m0, s56, 0x2000
	s_add_u32 s56, s60, 0x40000
	s_addc_u32 s57, s61, 0
	s_add_i32 s80, s74, s41
	global_load_lds_dwordx4 v180, s[60:61]
	s_mov_b32 m0, s80
	s_nop 0
	global_load_lds_dwordx4 v176, s[56:57]
	s_add_i32 m0, s80, 0x2000
	s_nop 0
	global_load_lds_dwordx4 v180, s[56:57]
	s_mov_b32 m0, s43
	s_nop 0
	global_load_lds_dwordx4 v174, s[62:63]
	s_mov_b32 m0, s55
	s_nop 0
	global_load_lds_dwordx4 v178, s[62:63]
	s_waitcnt vmcnt(8)
	s_waitcnt lgkmcnt(0)
	s_barrier
	s_setprio 1
	s_waitcnt lgkmcnt(0)
	v_mfma_f32_16x16x32_bf16 v[60:63], v[72:75], v[140:143], 0
	v_mfma_f32_16x16x32_bf16 v[28:31], v[80:83], v[140:143], 0
	v_mfma_f32_16x16x32_bf16 v[56:59], v[72:75], v[168:171], 0
	v_mfma_f32_16x16x32_bf16 v[24:27], v[80:83], v[168:171], 0
	v_mfma_f32_16x16x32_bf16 v[44:47], v[72:75], v[196:199], 0
	v_mfma_f32_16x16x32_bf16 v[12:15], v[80:83], v[196:199], 0
	v_mfma_f32_16x16x32_bf16 v[52:55], v[72:75], v[212:215], 0
	v_mfma_f32_16x16x32_bf16 v[20:23], v[80:83], v[212:215], 0
	v_mfma_f32_16x16x32_bf16 v[60:63], v[76:79], v[164:167], v[60:63]
	v_mfma_f32_16x16x32_bf16 v[28:31], v[84:87], v[164:167], v[28:31]
	v_mfma_f32_16x16x32_bf16 v[56:59], v[76:79], v[192:195], v[56:59]
	v_mfma_f32_16x16x32_bf16 v[24:27], v[84:87], v[192:195], v[24:27]
	v_mfma_f32_16x16x32_bf16 v[44:47], v[76:79], v[200:203], v[44:47]
	v_mfma_f32_16x16x32_bf16 v[12:15], v[84:87], v[200:203], v[12:15]
	v_mfma_f32_16x16x32_bf16 v[52:55], v[76:79], v[216:219], v[52:55]
	v_mfma_f32_16x16x32_bf16 v[20:23], v[84:87], v[216:219], v[20:23]
	v_mfma_f32_16x16x32_bf16 v[48:51], v[116:119], v[140:143], 0
	v_mfma_f32_16x16x32_bf16 v[16:19], v[124:127], v[140:143], 0
	v_mfma_f32_16x16x32_bf16 v[40:43], v[116:119], v[168:171], 0
	v_mfma_f32_16x16x32_bf16 v[8:11], v[124:127], v[168:171], 0
	v_mfma_f32_16x16x32_bf16 v[36:39], v[116:119], v[196:199], 0
	v_mfma_f32_16x16x32_bf16 v[4:7], v[124:127], v[196:199], 0
	v_mfma_f32_16x16x32_bf16 v[32:35], v[116:119], v[212:215], 0
	v_mfma_f32_16x16x32_bf16 v[0:3], v[124:127], v[212:215], 0
	v_mfma_f32_16x16x32_bf16 v[48:51], v[120:123], v[164:167], v[48:51]
	v_mfma_f32_16x16x32_bf16 v[16:19], v[128:131], v[164:167], v[16:19]
	v_mfma_f32_16x16x32_bf16 v[40:43], v[120:123], v[192:195], v[40:43]
	v_mfma_f32_16x16x32_bf16 v[8:11], v[128:131], v[192:195], v[8:11]
	v_mfma_f32_16x16x32_bf16 v[36:39], v[120:123], v[200:203], v[36:39]
	v_mfma_f32_16x16x32_bf16 v[4:7], v[128:131], v[200:203], v[4:7]
	v_mfma_f32_16x16x32_bf16 v[32:35], v[120:123], v[216:219], v[32:35]
	v_mfma_f32_16x16x32_bf16 v[0:3], v[128:131], v[216:219], v[0:3]
	s_setprio 0
	s_barrier
	s_add_i32 s80, 0, 0x18000
	s_add_i32 s81, 0, 0x1c000
	v_add_u32_e32 v84, s80, v204
	v_add_u32_e32 v128, s81, v204
	ds_read_b128 v[72:75], v84
	ds_read_b128 v[76:79], v84 offset:1024
	ds_read_b128 v[80:83], v84 offset:2048
	ds_read_b128 v[84:87], v84 offset:3072
	ds_read_b128 v[116:119], v128
	ds_read_b128 v[120:123], v128 offset:1024
	ds_read_b128 v[124:127], v128 offset:2048
	ds_read_b128 v[128:131], v128 offset:3072
	s_add_u32 s56, s62, 0x40000
	s_addc_u32 s57, s63, 0
	s_mov_b32 m0, s64
	ds_read_b128 v[140:143], v209 offset:32768
	ds_read_b128 v[164:167], v209 offset:33792
	ds_read_b128 v[168:171], v209 offset:34816
	ds_read_b128 v[192:195], v209 offset:35840
	ds_read_b128 v[196:199], v209 offset:36864
	ds_read_b128 v[200:203], v209 offset:37888
	ds_read_b128 v[212:215], v209 offset:38912
	ds_read_b128 v[216:219], v209 offset:39936
	global_load_lds_dwordx4 v174, s[56:57]
	s_mov_b32 m0, s65
	s_nop 0
	global_load_lds_dwordx4 v178, s[56:57]
	s_waitcnt vmcnt(8)
	s_waitcnt lgkmcnt(0)
	s_barrier
	s_setprio 1
	s_waitcnt lgkmcnt(0)
	v_mfma_f32_16x16x32_bf16 v[160:163], v[72:75], v[140:143], v[160:163]
	v_mfma_f32_16x16x32_bf16 v[108:111], v[80:83], v[140:143], v[108:111]
	v_mfma_f32_16x16x32_bf16 v[156:159], v[72:75], v[168:171], v[156:159]
	v_mfma_f32_16x16x32_bf16 v[104:107], v[80:83], v[168:171], v[104:107]
	v_mfma_f32_16x16x32_bf16 v[144:147], v[72:75], v[196:199], v[144:147]
	v_mfma_f32_16x16x32_bf16 v[92:95], v[80:83], v[196:199], v[92:95]
	v_mfma_f32_16x16x32_bf16 v[152:155], v[72:75], v[212:215], v[152:155]
	v_mfma_f32_16x16x32_bf16 v[100:103], v[80:83], v[212:215], v[100:103]
	v_mfma_f32_16x16x32_bf16 v[160:163], v[76:79], v[164:167], v[160:163]
	v_mfma_f32_16x16x32_bf16 v[108:111], v[84:87], v[164:167], v[108:111]
	v_mfma_f32_16x16x32_bf16 v[156:159], v[76:79], v[192:195], v[156:159]
	v_mfma_f32_16x16x32_bf16 v[104:107], v[84:87], v[192:195], v[104:107]
	v_mfma_f32_16x16x32_bf16 v[144:147], v[76:79], v[200:203], v[144:147]
	v_mfma_f32_16x16x32_bf16 v[92:95], v[84:87], v[200:203], v[92:95]
	v_mfma_f32_16x16x32_bf16 v[152:155], v[76:79], v[216:219], v[152:155]
	v_mfma_f32_16x16x32_bf16 v[100:103], v[84:87], v[216:219], v[100:103]
	v_mfma_f32_16x16x32_bf16 v[148:151], v[116:119], v[140:143], v[148:151]
	v_mfma_f32_16x16x32_bf16 v[96:99], v[124:127], v[140:143], v[96:99]
	v_mfma_f32_16x16x32_bf16 v[136:139], v[116:119], v[168:171], v[136:139]
	v_mfma_f32_16x16x32_bf16 v[88:91], v[124:127], v[168:171], v[88:91]
	v_mfma_f32_16x16x32_bf16 v[132:135], v[116:119], v[196:199], v[132:135]
	v_mfma_f32_16x16x32_bf16 v[68:71], v[124:127], v[196:199], v[68:71]
	v_mfma_f32_16x16x32_bf16 v[112:115], v[116:119], v[212:215], v[112:115]
	v_mfma_f32_16x16x32_bf16 v[64:67], v[124:127], v[212:215], v[64:67]
	v_mfma_f32_16x16x32_bf16 v[148:151], v[120:123], v[164:167], v[148:151]
	v_mfma_f32_16x16x32_bf16 v[96:99], v[128:131], v[164:167], v[96:99]
	v_mfma_f32_16x16x32_bf16 v[136:139], v[120:123], v[192:195], v[136:139]
	v_mfma_f32_16x16x32_bf16 v[88:91], v[128:131], v[192:195], v[88:91]
	v_mfma_f32_16x16x32_bf16 v[132:135], v[120:123], v[200:203], v[132:135]
	v_mfma_f32_16x16x32_bf16 v[68:71], v[128:131], v[200:203], v[68:71]
	v_mfma_f32_16x16x32_bf16 v[112:115], v[120:123], v[216:219], v[112:115]
	v_mfma_f32_16x16x32_bf16 v[64:67], v[128:131], v[216:219], v[64:67]
	s_setprio 0
	s_barrier
	s_add_i32 s56, s80, s41
	s_mov_b32 m0, s56
	ds_read_b128 v[140:143], v209 offset:49152
	ds_read_b128 v[164:167], v209 offset:50176
	ds_read_b128 v[168:171], v209 offset:51200
	ds_read_b128 v[192:195], v209 offset:52224
	ds_read_b128 v[196:199], v209 offset:53248
	ds_read_b128 v[200:203], v209 offset:54272
	ds_read_b128 v[212:215], v209 offset:55296
	ds_read_b128 v[216:219], v209 offset:56320
	global_load_lds_dwordx4 v176, s[98:99]
	s_add_i32 m0, s56, 0x2000
	s_add_u32 s56, s60, 0x40080
	s_addc_u32 s57, s61, 0
	s_add_i32 s60, s81, s41
	global_load_lds_dwordx4 v180, s[98:99]
	s_mov_b32 m0, s60
	s_nop 0
	global_load_lds_dwordx4 v176, s[56:57]
	s_add_i32 m0, s60, 0x2000
	s_nop 0
	global_load_lds_dwordx4 v180, s[56:57]
	s_mov_b32 m0, s69
	s_nop 0
	global_load_lds_dwordx4 v174, s[100:101]
	s_mov_b32 m0, s70
	s_nop 0
	global_load_lds_dwordx4 v178, s[100:101]
	s_waitcnt vmcnt(8)
	s_waitcnt lgkmcnt(0)
	s_barrier
	s_setprio 1
	s_waitcnt lgkmcnt(0)
	v_mfma_f32_16x16x32_bf16 v[60:63], v[72:75], v[140:143], v[60:63]
	v_mfma_f32_16x16x32_bf16 v[28:31], v[80:83], v[140:143], v[28:31]
	v_mfma_f32_16x16x32_bf16 v[56:59], v[72:75], v[168:171], v[56:59]
	v_mfma_f32_16x16x32_bf16 v[24:27], v[80:83], v[168:171], v[24:27]
	v_mfma_f32_16x16x32_bf16 v[44:47], v[72:75], v[196:199], v[44:47]
	v_mfma_f32_16x16x32_bf16 v[12:15], v[80:83], v[196:199], v[12:15]
	v_mfma_f32_16x16x32_bf16 v[52:55], v[72:75], v[212:215], v[52:55]
	v_mfma_f32_16x16x32_bf16 v[20:23], v[80:83], v[212:215], v[20:23]
	v_mfma_f32_16x16x32_bf16 v[60:63], v[76:79], v[164:167], v[60:63]
	v_mfma_f32_16x16x32_bf16 v[28:31], v[84:87], v[164:167], v[28:31]
	v_mfma_f32_16x16x32_bf16 v[56:59], v[76:79], v[192:195], v[56:59]
	v_mfma_f32_16x16x32_bf16 v[24:27], v[84:87], v[192:195], v[24:27]
	v_mfma_f32_16x16x32_bf16 v[44:47], v[76:79], v[200:203], v[44:47]
	v_mfma_f32_16x16x32_bf16 v[12:15], v[84:87], v[200:203], v[12:15]
	v_mfma_f32_16x16x32_bf16 v[52:55], v[76:79], v[216:219], v[52:55]
	v_mfma_f32_16x16x32_bf16 v[20:23], v[84:87], v[216:219], v[20:23]
	v_mfma_f32_16x16x32_bf16 v[48:51], v[116:119], v[140:143], v[48:51]
	v_mfma_f32_16x16x32_bf16 v[16:19], v[124:127], v[140:143], v[16:19]
	v_mfma_f32_16x16x32_bf16 v[40:43], v[116:119], v[168:171], v[40:43]
	v_mfma_f32_16x16x32_bf16 v[8:11], v[124:127], v[168:171], v[8:11]
	v_mfma_f32_16x16x32_bf16 v[36:39], v[116:119], v[196:199], v[36:39]
	v_mfma_f32_16x16x32_bf16 v[4:7], v[124:127], v[196:199], v[4:7]
	v_mfma_f32_16x16x32_bf16 v[32:35], v[116:119], v[212:215], v[32:35]
	v_mfma_f32_16x16x32_bf16 v[0:3], v[124:127], v[212:215], v[0:3]
	v_mfma_f32_16x16x32_bf16 v[48:51], v[120:123], v[164:167], v[48:51]
	v_mfma_f32_16x16x32_bf16 v[16:19], v[128:131], v[164:167], v[16:19]
	v_mfma_f32_16x16x32_bf16 v[40:43], v[120:123], v[192:195], v[40:43]
	v_mfma_f32_16x16x32_bf16 v[8:11], v[128:131], v[192:195], v[8:11]
	v_mfma_f32_16x16x32_bf16 v[36:39], v[120:123], v[200:203], v[36:39]
	v_mfma_f32_16x16x32_bf16 v[4:7], v[128:131], v[200:203], v[4:7]
	v_mfma_f32_16x16x32_bf16 v[32:35], v[120:123], v[216:219], v[32:35]
	v_mfma_f32_16x16x32_bf16 v[0:3], v[128:131], v[216:219], v[0:3]
	s_setprio 0
	s_barrier
	s_add_i32 s79, s79, 2
	s_add_u32 s77, s77, 0x100
	s_addc_u32 s78, s78, 0
	s_cmp_gt_u32 s79, 13
	s_mov_b64 s[56:57], s[58:59]
	s_cbranch_scc1 .Lkexit_2
.LBB0_578:
	ds_read_b128 v[72:75], v206
	ds_read_b128 v[76:79], v206 offset:1024
	ds_read_b128 v[80:83], v206 offset:2048
	ds_read_b128 v[84:87], v206 offset:3072
	ds_read_b128 v[116:119], v207
	ds_read_b128 v[120:123], v207 offset:1024
	ds_read_b128 v[124:127], v207 offset:2048
	ds_read_b128 v[128:131], v207 offset:3072
	s_add_u32 s58, s56, 0x100
	s_addc_u32 s59, s57, 0
	s_cmp_eq_u32 s79, 12
	s_cselect_b32 s63, s47, s59
	s_cselect_b32 s62, s53, s58
	s_cselect_b32 s61, s45, s78
	s_cselect_b32 s60, s76, s77
	s_add_i32 m0, s43, 0xc000
	ds_read_b128 v[140:143], v209
	ds_read_b128 v[164:167], v209 offset:1024
	ds_read_b128 v[168:171], v209 offset:2048
	ds_read_b128 v[192:195], v209 offset:3072
	ds_read_b128 v[196:199], v209 offset:4096
	ds_read_b128 v[200:203], v209 offset:5120
	ds_read_b128 v[212:215], v209 offset:6144
	ds_read_b128 v[216:219], v209 offset:7168
	global_load_lds_dwordx4 v184, s[56:57]
	s_add_i32 m0, s43, 0xe000
	s_nop 0
	global_load_lds_dwordx4 v186, s[56:57]
	s_waitcnt vmcnt(8)
	s_waitcnt lgkmcnt(0)
	s_barrier
	s_setprio 1
	s_waitcnt lgkmcnt(0)
	v_mfma_f32_16x16x32_bf16 v[160:163], v[72:75], v[140:143], v[160:163]
	v_mfma_f32_16x16x32_bf16 v[108:111], v[80:83], v[140:143], v[108:111]
	v_mfma_f32_16x16x32_bf16 v[156:159], v[72:75], v[168:171], v[156:159]
	v_mfma_f32_16x16x32_bf16 v[104:107], v[80:83], v[168:171], v[104:107]
	v_mfma_f32_16x16x32_bf16 v[144:147], v[72:75], v[196:199], v[144:147]
	v_mfma_f32_16x16x32_bf16 v[92:95], v[80:83], v[196:199], v[92:95]
	v_mfma_f32_16x16x32_bf16 v[152:155], v[72:75], v[212:215], v[152:155]
	v_mfma_f32_16x16x32_bf16 v[100:103], v[80:83], v[212:215], v[100:103]
	v_mfma_f32_16x16x32_bf16 v[160:163], v[76:79], v[164:167], v[160:163]
	v_mfma_f32_16x16x32_bf16 v[108:111], v[84:87], v[164:167], v[108:111]
	v_mfma_f32_16x16x32_bf16 v[156:159], v[76:79], v[192:195], v[156:159]
	v_mfma_f32_16x16x32_bf16 v[104:107], v[84:87], v[192:195], v[104:107]
	v_mfma_f32_16x16x32_bf16 v[144:147], v[76:79], v[200:203], v[144:147]
	v_mfma_f32_16x16x32_bf16 v[92:95], v[84:87], v[200:203], v[92:95]
	v_mfma_f32_16x16x32_bf16 v[152:155], v[76:79], v[216:219], v[152:155]
	v_mfma_f32_16x16x32_bf16 v[100:103], v[84:87], v[216:219], v[100:103]
	v_mfma_f32_16x16x32_bf16 v[148:151], v[116:119], v[140:143], v[148:151]
	v_mfma_f32_16x16x32_bf16 v[96:99], v[124:127], v[140:143], v[96:99]
	v_mfma_f32_16x16x32_bf16 v[136:139], v[116:119], v[168:171], v[136:139]
	v_mfma_f32_16x16x32_bf16 v[88:91], v[124:127], v[168:171], v[88:91]
	v_mfma_f32_16x16x32_bf16 v[132:135], v[116:119], v[196:199], v[132:135]
	v_mfma_f32_16x16x32_bf16 v[68:71], v[124:127], v[196:199], v[68:71]
	v_mfma_f32_16x16x32_bf16 v[112:115], v[116:119], v[212:215], v[112:115]
	v_mfma_f32_16x16x32_bf16 v[64:67], v[124:127], v[212:215], v[64:67]
	v_mfma_f32_16x16x32_bf16 v[148:151], v[120:123], v[164:167], v[148:151]
	v_mfma_f32_16x16x32_bf16 v[96:99], v[128:131], v[164:167], v[96:99]
	v_mfma_f32_16x16x32_bf16 v[136:139], v[120:123], v[192:195], v[136:139]
	v_mfma_f32_16x16x32_bf16 v[88:91], v[128:131], v[192:195], v[88:91]
	v_mfma_f32_16x16x32_bf16 v[132:135], v[120:123], v[200:203], v[132:135]
	v_mfma_f32_16x16x32_bf16 v[68:71], v[128:131], v[200:203], v[68:71]
	v_mfma_f32_16x16x32_bf16 v[112:115], v[120:123], v[216:219], v[112:115]
	v_mfma_f32_16x16x32_bf16 v[64:67], v[128:131], v[216:219], v[64:67]
	s_setprio 0
	s_barrier
	s_add_u32 s98, s60, s22
	s_addc_u32 s99, s61, s23
	s_add_u32 s100, s62, s22
	s_addc_u32 s101, s63, s23
	s_add_i32 s56, s73, s41
	s_mov_b32 m0, s56
	ds_read_b128 v[140:143], v209 offset:16384
	ds_read_b128 v[164:167], v209 offset:17408
	ds_read_b128 v[168:171], v209 offset:18432
	ds_read_b128 v[192:195], v209 offset:19456
	ds_read_b128 v[196:199], v209 offset:20480
	ds_read_b128 v[200:203], v209 offset:21504
	ds_read_b128 v[212:215], v209 offset:22528
	ds_read_b128 v[216:219], v209 offset:23552
	global_load_lds_dwordx4 v176, s[60:61]
	s_add_i32 m0, s56, 0x2000
	s_add_u32 s56, s60, 0x40000
	s_addc_u32 s57, s61, 0
	s_add_i32 s80, s74, s41
	global_load_lds_dwordx4 v180, s[60:61]
	s_mov_b32 m0, s80
	s_nop 0
	global_load_lds_dwordx4 v176, s[56:57]
	s_add_i32 m0, s80, 0x2000
	s_nop 0
	global_load_lds_dwordx4 v180, s[56:57]
	s_mov_b32 m0, s43
	s_nop 0
	global_load_lds_dwordx4 v174, s[62:63]
	s_mov_b32 m0, s55
	s_nop 0
	global_load_lds_dwordx4 v178, s[62:63]
	s_waitcnt vmcnt(8)
	s_waitcnt lgkmcnt(0)
	s_barrier
	s_setprio 1
	s_waitcnt lgkmcnt(0)
	v_mfma_f32_16x16x32_bf16 v[60:63], v[72:75], v[140:143], v[60:63]
	v_mfma_f32_16x16x32_bf16 v[28:31], v[80:83], v[140:143], v[28:31]
	v_mfma_f32_16x16x32_bf16 v[56:59], v[72:75], v[168:171], v[56:59]
	v_mfma_f32_16x16x32_bf16 v[24:27], v[80:83], v[168:171], v[24:27]
	v_mfma_f32_16x16x32_bf16 v[44:47], v[72:75], v[196:199], v[44:47]
	v_mfma_f32_16x16x32_bf16 v[12:15], v[80:83], v[196:199], v[12:15]
	v_mfma_f32_16x16x32_bf16 v[52:55], v[72:75], v[212:215], v[52:55]
	v_mfma_f32_16x16x32_bf16 v[20:23], v[80:83], v[212:215], v[20:23]
	v_mfma_f32_16x16x32_bf16 v[60:63], v[76:79], v[164:167], v[60:63]
	v_mfma_f32_16x16x32_bf16 v[28:31], v[84:87], v[164:167], v[28:31]
	v_mfma_f32_16x16x32_bf16 v[56:59], v[76:79], v[192:195], v[56:59]
	v_mfma_f32_16x16x32_bf16 v[24:27], v[84:87], v[192:195], v[24:27]
	v_mfma_f32_16x16x32_bf16 v[44:47], v[76:79], v[200:203], v[44:47]
	v_mfma_f32_16x16x32_bf16 v[12:15], v[84:87], v[200:203], v[12:15]
	v_mfma_f32_16x16x32_bf16 v[52:55], v[76:79], v[216:219], v[52:55]
	v_mfma_f32_16x16x32_bf16 v[20:23], v[84:87], v[216:219], v[20:23]
	v_mfma_f32_16x16x32_bf16 v[48:51], v[116:119], v[140:143], v[48:51]
	v_mfma_f32_16x16x32_bf16 v[16:19], v[124:127], v[140:143], v[16:19]
	v_mfma_f32_16x16x32_bf16 v[40:43], v[116:119], v[168:171], v[40:43]
	v_mfma_f32_16x16x32_bf16 v[8:11], v[124:127], v[168:171], v[8:11]
	v_mfma_f32_16x16x32_bf16 v[36:39], v[116:119], v[196:199], v[36:39]
	v_mfma_f32_16x16x32_bf16 v[4:7], v[124:127], v[196:199], v[4:7]
	v_mfma_f32_16x16x32_bf16 v[32:35], v[116:119], v[212:215], v[32:35]
	v_mfma_f32_16x16x32_bf16 v[0:3], v[124:127], v[212:215], v[0:3]
	v_mfma_f32_16x16x32_bf16 v[48:51], v[120:123], v[164:167], v[48:51]
	v_mfma_f32_16x16x32_bf16 v[16:19], v[128:131], v[164:167], v[16:19]
	v_mfma_f32_16x16x32_bf16 v[40:43], v[120:123], v[192:195], v[40:43]
	v_mfma_f32_16x16x32_bf16 v[8:11], v[128:131], v[192:195], v[8:11]
	v_mfma_f32_16x16x32_bf16 v[36:39], v[120:123], v[200:203], v[36:39]
	v_mfma_f32_16x16x32_bf16 v[4:7], v[128:131], v[200:203], v[4:7]
	v_mfma_f32_16x16x32_bf16 v[32:35], v[120:123], v[216:219], v[32:35]
	v_mfma_f32_16x16x32_bf16 v[0:3], v[128:131], v[216:219], v[0:3]
	s_setprio 0
	s_barrier
	s_add_i32 s80, 0, 0x18000
	s_add_i32 s81, 0, 0x1c000
	v_add_u32_e32 v84, s80, v204
	v_add_u32_e32 v128, s81, v204
	ds_read_b128 v[72:75], v84
	ds_read_b128 v[76:79], v84 offset:1024
	ds_read_b128 v[80:83], v84 offset:2048
	ds_read_b128 v[84:87], v84 offset:3072
	ds_read_b128 v[116:119], v128
	ds_read_b128 v[120:123], v128 offset:1024
	ds_read_b128 v[124:127], v128 offset:2048
	ds_read_b128 v[128:131], v128 offset:3072
	s_add_u32 s56, s62, 0x40000
	s_addc_u32 s57, s63, 0
	s_mov_b32 m0, s64
	ds_read_b128 v[140:143], v209 offset:32768
	ds_read_b128 v[164:167], v209 offset:33792
	ds_read_b128 v[168:171], v209 offset:34816
	ds_read_b128 v[192:195], v209 offset:35840
	ds_read_b128 v[196:199], v209 offset:36864
	ds_read_b128 v[200:203], v209 offset:37888
	ds_read_b128 v[212:215], v209 offset:38912
	ds_read_b128 v[216:219], v209 offset:39936
	global_load_lds_dwordx4 v174, s[56:57]
	s_mov_b32 m0, s65
	s_nop 0
	global_load_lds_dwordx4 v178, s[56:57]
	s_waitcnt vmcnt(8)
	s_waitcnt lgkmcnt(0)
	s_barrier
	s_setprio 1
	s_waitcnt lgkmcnt(0)
	v_mfma_f32_16x16x32_bf16 v[160:163], v[72:75], v[140:143], v[160:163]
	v_mfma_f32_16x16x32_bf16 v[108:111], v[80:83], v[140:143], v[108:111]
	v_mfma_f32_16x16x32_bf16 v[156:159], v[72:75], v[168:171], v[156:159]
	v_mfma_f32_16x16x32_bf16 v[104:107], v[80:83], v[168:171], v[104:107]
	v_mfma_f32_16x16x32_bf16 v[144:147], v[72:75], v[196:199], v[144:147]
	v_mfma_f32_16x16x32_bf16 v[92:95], v[80:83], v[196:199], v[92:95]
	v_mfma_f32_16x16x32_bf16 v[152:155], v[72:75], v[212:215], v[152:155]
	v_mfma_f32_16x16x32_bf16 v[100:103], v[80:83], v[212:215], v[100:103]
	v_mfma_f32_16x16x32_bf16 v[160:163], v[76:79], v[164:167], v[160:163]
	v_mfma_f32_16x16x32_bf16 v[108:111], v[84:87], v[164:167], v[108:111]
	v_mfma_f32_16x16x32_bf16 v[156:159], v[76:79], v[192:195], v[156:159]
	v_mfma_f32_16x16x32_bf16 v[104:107], v[84:87], v[192:195], v[104:107]
	v_mfma_f32_16x16x32_bf16 v[144:147], v[76:79], v[200:203], v[144:147]
	v_mfma_f32_16x16x32_bf16 v[92:95], v[84:87], v[200:203], v[92:95]
	v_mfma_f32_16x16x32_bf16 v[152:155], v[76:79], v[216:219], v[152:155]
	v_mfma_f32_16x16x32_bf16 v[100:103], v[84:87], v[216:219], v[100:103]
	v_mfma_f32_16x16x32_bf16 v[148:151], v[116:119], v[140:143], v[148:151]
	v_mfma_f32_16x16x32_bf16 v[96:99], v[124:127], v[140:143], v[96:99]
	v_mfma_f32_16x16x32_bf16 v[136:139], v[116:119], v[168:171], v[136:139]
	v_mfma_f32_16x16x32_bf16 v[88:91], v[124:127], v[168:171], v[88:91]
	v_mfma_f32_16x16x32_bf16 v[132:135], v[116:119], v[196:199], v[132:135]
	v_mfma_f32_16x16x32_bf16 v[68:71], v[124:127], v[196:199], v[68:71]
	v_mfma_f32_16x16x32_bf16 v[112:115], v[116:119], v[212:215], v[112:115]
	v_mfma_f32_16x16x32_bf16 v[64:67], v[124:127], v[212:215], v[64:67]
	v_mfma_f32_16x16x32_bf16 v[148:151], v[120:123], v[164:167], v[148:151]
	v_mfma_f32_16x16x32_bf16 v[96:99], v[128:131], v[164:167], v[96:99]
	v_mfma_f32_16x16x32_bf16 v[136:139], v[120:123], v[192:195], v[136:139]
	v_mfma_f32_16x16x32_bf16 v[88:91], v[128:131], v[192:195], v[88:91]
	v_mfma_f32_16x16x32_bf16 v[132:135], v[120:123], v[200:203], v[132:135]
	v_mfma_f32_16x16x32_bf16 v[68:71], v[128:131], v[200:203], v[68:71]
	v_mfma_f32_16x16x32_bf16 v[112:115], v[120:123], v[216:219], v[112:115]
	v_mfma_f32_16x16x32_bf16 v[64:67], v[128:131], v[216:219], v[64:67]
	s_setprio 0
	s_barrier
	s_add_i32 s56, s80, s41
	s_mov_b32 m0, s56
	ds_read_b128 v[140:143], v209 offset:49152
	ds_read_b128 v[164:167], v209 offset:50176
	ds_read_b128 v[168:171], v209 offset:51200
	ds_read_b128 v[192:195], v209 offset:52224
	ds_read_b128 v[196:199], v209 offset:53248
	ds_read_b128 v[200:203], v209 offset:54272
	ds_read_b128 v[212:215], v209 offset:55296
	ds_read_b128 v[216:219], v209 offset:56320
	global_load_lds_dwordx4 v176, s[98:99]
	s_add_i32 m0, s56, 0x2000
	s_add_u32 s56, s60, 0x40080
	s_addc_u32 s57, s61, 0
	s_add_i32 s60, s81, s41
	global_load_lds_dwordx4 v180, s[98:99]
	s_mov_b32 m0, s60
	s_nop 0
	global_load_lds_dwordx4 v176, s[56:57]
	s_add_i32 m0, s60, 0x2000
	s_nop 0
	global_load_lds_dwordx4 v180, s[56:57]
	s_mov_b32 m0, s69
	s_nop 0
	global_load_lds_dwordx4 v174, s[100:101]
	s_mov_b32 m0, s70
	s_nop 0
	global_load_lds_dwordx4 v178, s[100:101]
	s_waitcnt vmcnt(8)
	s_waitcnt lgkmcnt(0)
	s_barrier
	s_setprio 1
	s_waitcnt lgkmcnt(0)
	v_mfma_f32_16x16x32_bf16 v[60:63], v[72:75], v[140:143], v[60:63]
	v_mfma_f32_16x16x32_bf16 v[28:31], v[80:83], v[140:143], v[28:31]
	v_mfma_f32_16x16x32_bf16 v[56:59], v[72:75], v[168:171], v[56:59]
	v_mfma_f32_16x16x32_bf16 v[24:27], v[80:83], v[168:171], v[24:27]
	v_mfma_f32_16x16x32_bf16 v[44:47], v[72:75], v[196:199], v[44:47]
	v_mfma_f32_16x16x32_bf16 v[12:15], v[80:83], v[196:199], v[12:15]
	v_mfma_f32_16x16x32_bf16 v[52:55], v[72:75], v[212:215], v[52:55]
	v_mfma_f32_16x16x32_bf16 v[20:23], v[80:83], v[212:215], v[20:23]
	v_mfma_f32_16x16x32_bf16 v[60:63], v[76:79], v[164:167], v[60:63]
	v_mfma_f32_16x16x32_bf16 v[28:31], v[84:87], v[164:167], v[28:31]
	v_mfma_f32_16x16x32_bf16 v[56:59], v[76:79], v[192:195], v[56:59]
	v_mfma_f32_16x16x32_bf16 v[24:27], v[84:87], v[192:195], v[24:27]
	v_mfma_f32_16x16x32_bf16 v[44:47], v[76:79], v[200:203], v[44:47]
	v_mfma_f32_16x16x32_bf16 v[12:15], v[84:87], v[200:203], v[12:15]
	v_mfma_f32_16x16x32_bf16 v[52:55], v[76:79], v[216:219], v[52:55]
	v_mfma_f32_16x16x32_bf16 v[20:23], v[84:87], v[216:219], v[20:23]
	v_mfma_f32_16x16x32_bf16 v[48:51], v[116:119], v[140:143], v[48:51]
	v_mfma_f32_16x16x32_bf16 v[16:19], v[124:127], v[140:143], v[16:19]
	v_mfma_f32_16x16x32_bf16 v[40:43], v[116:119], v[168:171], v[40:43]
	v_mfma_f32_16x16x32_bf16 v[8:11], v[124:127], v[168:171], v[8:11]
	v_mfma_f32_16x16x32_bf16 v[36:39], v[116:119], v[196:199], v[36:39]
	v_mfma_f32_16x16x32_bf16 v[4:7], v[124:127], v[196:199], v[4:7]
	v_mfma_f32_16x16x32_bf16 v[32:35], v[116:119], v[212:215], v[32:35]
	v_mfma_f32_16x16x32_bf16 v[0:3], v[124:127], v[212:215], v[0:3]
	v_mfma_f32_16x16x32_bf16 v[48:51], v[120:123], v[164:167], v[48:51]
	v_mfma_f32_16x16x32_bf16 v[16:19], v[128:131], v[164:167], v[16:19]
	v_mfma_f32_16x16x32_bf16 v[40:43], v[120:123], v[192:195], v[40:43]
	v_mfma_f32_16x16x32_bf16 v[8:11], v[128:131], v[192:195], v[8:11]
	v_mfma_f32_16x16x32_bf16 v[36:39], v[120:123], v[200:203], v[36:39]
	v_mfma_f32_16x16x32_bf16 v[4:7], v[128:131], v[200:203], v[4:7]
	v_mfma_f32_16x16x32_bf16 v[32:35], v[120:123], v[216:219], v[32:35]
	v_mfma_f32_16x16x32_bf16 v[0:3], v[128:131], v[216:219], v[0:3]
	s_setprio 0
	s_barrier
	s_add_i32 s79, s79, 2
	s_add_u32 s77, s77, 0x100
	s_addc_u32 s78, s78, 0
	s_cmp_gt_u32 s79, 13
	s_mov_b64 s[56:57], s[58:59]
	s_cbranch_scc0 .LBB0_578
.Lkexit_2:
	s_and_b64 vcc, exec, s[24:25]
	s_cbranch_vccz .LBB0_581
	s_barrier

.LBB0_740:
	s_add_u32 s60, s38, 0x100
	s_addc_u32 s61, s39, 0
	s_mov_b32 s62, -2
	s_waitcnt lgkmcnt(0)
	ds_read_b128 v[128:131], v194
	ds_read_b128 v[132:135], v194 offset:1024
	ds_read_b128 v[136:139], v194 offset:2048
	ds_read_b128 v[140:143], v194 offset:3072
	ds_read_b128 v[144:147], v195
	ds_read_b128 v[148:151], v195 offset:1024
	ds_read_b128 v[168:171], v195 offset:2048
	ds_read_b128 v[174:177], v195 offset:3072
	s_add_u32 s38, s36, 0x100
	s_addc_u32 s39, s37, 0
	s_cmp_eq_u32 s62, 40
	s_cselect_b32 s43, s11, s39
	s_cselect_b32 s42, s10, s38
	s_cselect_b32 s41, s25, s61
	s_cselect_b32 s40, s24, s60
	s_add_i32 m0, s45, 0xc000
	ds_read_b128 v[178:181], v196
	ds_read_b128 v[182:185], v196 offset:1024
	ds_read_b128 v[186:189], v196 offset:2048
	ds_read_b128 v[198:201], v196 offset:3072
	ds_read_b128 v[202:205], v196 offset:4096
	ds_read_b128 v[210:213], v196 offset:5120
	ds_read_b128 v[214:217], v196 offset:6144
	ds_read_b128 v[218:221], v196 offset:7168
	global_load_lds_dwordx4 v160, s[36:37]
	s_add_i32 m0, s45, 0xe000
	s_nop 0
	global_load_lds_dwordx4 v162, s[36:37]
	s_waitcnt vmcnt(8)
	s_waitcnt lgkmcnt(0)
	s_barrier
	s_setprio 1
	s_waitcnt lgkmcnt(0)
	v_mfma_f32_16x16x32_bf16 v[124:127], v[128:131], v[178:181], 0
	v_mfma_f32_16x16x32_bf16 v[120:123], v[136:139], v[178:181], 0
	v_mfma_f32_16x16x32_bf16 v[108:111], v[128:131], v[186:189], 0
	v_mfma_f32_16x16x32_bf16 v[104:107], v[136:139], v[186:189], 0
	v_mfma_f32_16x16x32_bf16 v[92:95], v[128:131], v[202:205], 0
	v_mfma_f32_16x16x32_bf16 v[88:91], v[136:139], v[202:205], 0
	v_mfma_f32_16x16x32_bf16 v[76:79], v[128:131], v[214:217], 0
	v_mfma_f32_16x16x32_bf16 v[72:75], v[136:139], v[214:217], 0
	v_mfma_f32_16x16x32_bf16 v[124:127], v[132:135], v[182:185], v[124:127]
	v_mfma_f32_16x16x32_bf16 v[120:123], v[140:143], v[182:185], v[120:123]
	v_mfma_f32_16x16x32_bf16 v[108:111], v[132:135], v[198:201], v[108:111]
	v_mfma_f32_16x16x32_bf16 v[104:107], v[140:143], v[198:201], v[104:107]
	v_mfma_f32_16x16x32_bf16 v[92:95], v[132:135], v[210:213], v[92:95]
	v_mfma_f32_16x16x32_bf16 v[88:91], v[140:143], v[210:213], v[88:91]
	v_mfma_f32_16x16x32_bf16 v[76:79], v[132:135], v[218:221], v[76:79]
	v_mfma_f32_16x16x32_bf16 v[72:75], v[140:143], v[218:221], v[72:75]
	v_mfma_f32_16x16x32_bf16 v[116:119], v[144:147], v[178:181], 0
	v_mfma_f32_16x16x32_bf16 v[112:115], v[168:171], v[178:181], 0
	v_mfma_f32_16x16x32_bf16 v[100:103], v[144:147], v[186:189], 0
	v_mfma_f32_16x16x32_bf16 v[96:99], v[168:171], v[186:189], 0
	v_mfma_f32_16x16x32_bf16 v[84:87], v[144:147], v[202:205], 0
	v_mfma_f32_16x16x32_bf16 v[80:83], v[168:171], v[202:205], 0
	v_mfma_f32_16x16x32_bf16 v[68:71], v[144:147], v[214:217], 0
	v_mfma_f32_16x16x32_bf16 v[64:67], v[168:171], v[214:217], 0
	v_mfma_f32_16x16x32_bf16 v[116:119], v[148:151], v[182:185], v[116:119]
	v_mfma_f32_16x16x32_bf16 v[112:115], v[174:177], v[182:185], v[112:115]
	v_mfma_f32_16x16x32_bf16 v[100:103], v[148:151], v[198:201], v[100:103]
	v_mfma_f32_16x16x32_bf16 v[96:99], v[174:177], v[198:201], v[96:99]
	v_mfma_f32_16x16x32_bf16 v[84:87], v[148:151], v[210:213], v[84:87]
	v_mfma_f32_16x16x32_bf16 v[80:83], v[174:177], v[210:213], v[80:83]
	v_mfma_f32_16x16x32_bf16 v[68:71], v[148:151], v[218:221], v[68:71]
	v_mfma_f32_16x16x32_bf16 v[64:67], v[174:177], v[218:221], v[64:67]
	s_setprio 0
	s_barrier
	s_add_u32 s98, s40, s20
	s_addc_u32 s99, s41, s21
	s_add_u32 s100, s42, s20
	s_addc_u32 s101, s43, s21
	s_add_i32 s36, s54, s44
	s_mov_b32 m0, s36
	ds_read_b128 v[178:181], v196 offset:16384
	ds_read_b128 v[182:185], v196 offset:17408
	ds_read_b128 v[186:189], v196 offset:18432
	ds_read_b128 v[198:201], v196 offset:19456
	ds_read_b128 v[202:205], v196 offset:20480
	ds_read_b128 v[210:213], v196 offset:21504
	ds_read_b128 v[214:217], v196 offset:22528
	ds_read_b128 v[218:221], v196 offset:23552
	global_load_lds_dwordx4 v154, s[40:41]
	s_add_i32 m0, s36, 0x2000
	s_add_u32 s36, s40, 0xb0000
	s_addc_u32 s37, s41, 0
	s_add_i32 s63, s55, s44
	global_load_lds_dwordx4 v158, s[40:41]
	s_mov_b32 m0, s63
	s_nop 0
	global_load_lds_dwordx4 v154, s[36:37]
	s_add_i32 m0, s63, 0x2000
	s_nop 0
	global_load_lds_dwordx4 v158, s[36:37]
	s_mov_b32 m0, s45
	s_nop 0
	global_load_lds_dwordx4 v152, s[42:43]
	s_mov_b32 m0, s46
	s_nop 0
	global_load_lds_dwordx4 v156, s[42:43]
	s_waitcnt vmcnt(8)
	s_waitcnt lgkmcnt(0)
	s_barrier
	s_setprio 1
	s_waitcnt lgkmcnt(0)
	v_mfma_f32_16x16x32_bf16 v[60:63], v[128:131], v[178:181], 0
	v_mfma_f32_16x16x32_bf16 v[56:59], v[136:139], v[178:181], 0
	v_mfma_f32_16x16x32_bf16 v[44:47], v[128:131], v[186:189], 0
	v_mfma_f32_16x16x32_bf16 v[40:43], v[136:139], v[186:189], 0
	v_mfma_f32_16x16x32_bf16 v[28:31], v[128:131], v[202:205], 0
	v_mfma_f32_16x16x32_bf16 v[24:27], v[136:139], v[202:205], 0
	v_mfma_f32_16x16x32_bf16 v[12:15], v[128:131], v[214:217], 0
	v_mfma_f32_16x16x32_bf16 v[8:11], v[136:139], v[214:217], 0
	v_mfma_f32_16x16x32_bf16 v[60:63], v[132:135], v[182:185], v[60:63]
	v_mfma_f32_16x16x32_bf16 v[56:59], v[140:143], v[182:185], v[56:59]
	v_mfma_f32_16x16x32_bf16 v[44:47], v[132:135], v[198:201], v[44:47]
	v_mfma_f32_16x16x32_bf16 v[40:43], v[140:143], v[198:201], v[40:43]
	v_mfma_f32_16x16x32_bf16 v[28:31], v[132:135], v[210:213], v[28:31]
	v_mfma_f32_16x16x32_bf16 v[24:27], v[140:143], v[210:213], v[24:27]
	v_mfma_f32_16x16x32_bf16 v[12:15], v[132:135], v[218:221], v[12:15]
	v_mfma_f32_16x16x32_bf16 v[8:11], v[140:143], v[218:221], v[8:11]
	v_mfma_f32_16x16x32_bf16 v[52:55], v[144:147], v[178:181], 0
	v_mfma_f32_16x16x32_bf16 v[48:51], v[168:171], v[178:181], 0
	v_mfma_f32_16x16x32_bf16 v[36:39], v[144:147], v[186:189], 0
	v_mfma_f32_16x16x32_bf16 v[32:35], v[168:171], v[186:189], 0
	v_mfma_f32_16x16x32_bf16 v[20:23], v[144:147], v[202:205], 0
	v_mfma_f32_16x16x32_bf16 v[16:19], v[168:171], v[202:205], 0
	v_mfma_f32_16x16x32_bf16 v[4:7], v[144:147], v[214:217], 0
	v_mfma_f32_16x16x32_bf16 v[0:3], v[168:171], v[214:217], 0
	v_mfma_f32_16x16x32_bf16 v[52:55], v[148:151], v[182:185], v[52:55]
	v_mfma_f32_16x16x32_bf16 v[48:51], v[174:177], v[182:185], v[48:51]
	v_mfma_f32_16x16x32_bf16 v[36:39], v[148:151], v[198:201], v[36:39]
	v_mfma_f32_16x16x32_bf16 v[32:35], v[174:177], v[198:201], v[32:35]
	v_mfma_f32_16x16x32_bf16 v[20:23], v[148:151], v[210:213], v[20:23]
	v_mfma_f32_16x16x32_bf16 v[16:19], v[174:177], v[210:213], v[16:19]
	v_mfma_f32_16x16x32_bf16 v[4:7], v[148:151], v[218:221], v[4:7]
	v_mfma_f32_16x16x32_bf16 v[0:3], v[174:177], v[218:221], v[0:3]
	s_setprio 0
	s_barrier
	s_add_i32 s63, 0, 0x18000
	s_add_i32 s64, 0, 0x1c000
	v_add_u32_e32 v140, s63, v192
	v_add_u32_e32 v174, s64, v192
	ds_read_b128 v[128:131], v140
	ds_read_b128 v[132:135], v140 offset:1024
	ds_read_b128 v[136:139], v140 offset:2048
	ds_read_b128 v[140:143], v140 offset:3072
	ds_read_b128 v[144:147], v174
	ds_read_b128 v[148:151], v174 offset:1024
	ds_read_b128 v[168:171], v174 offset:2048
	ds_read_b128 v[174:177], v174 offset:3072
	s_add_u32 s36, s42, 0xb0000
	s_addc_u32 s37, s43, 0
	s_mov_b32 m0, s47
	ds_read_b128 v[178:181], v196 offset:32768
	ds_read_b128 v[182:185], v196 offset:33792
	ds_read_b128 v[186:189], v196 offset:34816
	ds_read_b128 v[198:201], v196 offset:35840
	ds_read_b128 v[202:205], v196 offset:36864
	ds_read_b128 v[210:213], v196 offset:37888
	ds_read_b128 v[214:217], v196 offset:38912
	ds_read_b128 v[218:221], v196 offset:39936
	global_load_lds_dwordx4 v152, s[36:37]
	s_mov_b32 m0, s48
	s_nop 0
	global_load_lds_dwordx4 v156, s[36:37]
	s_waitcnt vmcnt(8)
	s_waitcnt lgkmcnt(0)
	s_barrier
	s_setprio 1
	s_waitcnt lgkmcnt(0)
	v_mfma_f32_16x16x32_bf16 v[124:127], v[128:131], v[178:181], v[124:127]
	v_mfma_f32_16x16x32_bf16 v[120:123], v[136:139], v[178:181], v[120:123]
	v_mfma_f32_16x16x32_bf16 v[108:111], v[128:131], v[186:189], v[108:111]
	v_mfma_f32_16x16x32_bf16 v[104:107], v[136:139], v[186:189], v[104:107]
	v_mfma_f32_16x16x32_bf16 v[92:95], v[128:131], v[202:205], v[92:95]
	v_mfma_f32_16x16x32_bf16 v[88:91], v[136:139], v[202:205], v[88:91]
	v_mfma_f32_16x16x32_bf16 v[76:79], v[128:131], v[214:217], v[76:79]
	v_mfma_f32_16x16x32_bf16 v[72:75], v[136:139], v[214:217], v[72:75]
	v_mfma_f32_16x16x32_bf16 v[124:127], v[132:135], v[182:185], v[124:127]
	v_mfma_f32_16x16x32_bf16 v[120:123], v[140:143], v[182:185], v[120:123]
	v_mfma_f32_16x16x32_bf16 v[108:111], v[132:135], v[198:201], v[108:111]
	v_mfma_f32_16x16x32_bf16 v[104:107], v[140:143], v[198:201], v[104:107]
	v_mfma_f32_16x16x32_bf16 v[92:95], v[132:135], v[210:213], v[92:95]
	v_mfma_f32_16x16x32_bf16 v[88:91], v[140:143], v[210:213], v[88:91]
	v_mfma_f32_16x16x32_bf16 v[76:79], v[132:135], v[218:221], v[76:79]
	v_mfma_f32_16x16x32_bf16 v[72:75], v[140:143], v[218:221], v[72:75]
	v_mfma_f32_16x16x32_bf16 v[116:119], v[144:147], v[178:181], v[116:119]
	v_mfma_f32_16x16x32_bf16 v[112:115], v[168:171], v[178:181], v[112:115]
	v_mfma_f32_16x16x32_bf16 v[100:103], v[144:147], v[186:189], v[100:103]
	v_mfma_f32_16x16x32_bf16 v[96:99], v[168:171], v[186:189], v[96:99]
	v_mfma_f32_16x16x32_bf16 v[84:87], v[144:147], v[202:205], v[84:87]
	v_mfma_f32_16x16x32_bf16 v[80:83], v[168:171], v[202:205], v[80:83]
	v_mfma_f32_16x16x32_bf16 v[68:71], v[144:147], v[214:217], v[68:71]
	v_mfma_f32_16x16x32_bf16 v[64:67], v[168:171], v[214:217], v[64:67]
	v_mfma_f32_16x16x32_bf16 v[116:119], v[148:151], v[182:185], v[116:119]
	v_mfma_f32_16x16x32_bf16 v[112:115], v[174:177], v[182:185], v[112:115]
	v_mfma_f32_16x16x32_bf16 v[100:103], v[148:151], v[198:201], v[100:103]
	v_mfma_f32_16x16x32_bf16 v[96:99], v[174:177], v[198:201], v[96:99]
	v_mfma_f32_16x16x32_bf16 v[84:87], v[148:151], v[210:213], v[84:87]
	v_mfma_f32_16x16x32_bf16 v[80:83], v[174:177], v[210:213], v[80:83]
	v_mfma_f32_16x16x32_bf16 v[68:71], v[148:151], v[218:221], v[68:71]
	v_mfma_f32_16x16x32_bf16 v[64:67], v[174:177], v[218:221], v[64:67]
	s_setprio 0
	s_barrier
	s_add_i32 s36, s63, s44
	s_mov_b32 m0, s36
	ds_read_b128 v[178:181], v196 offset:49152
	ds_read_b128 v[182:185], v196 offset:50176
	ds_read_b128 v[186:189], v196 offset:51200
	ds_read_b128 v[198:201], v196 offset:52224
	ds_read_b128 v[202:205], v196 offset:53248
	ds_read_b128 v[210:213], v196 offset:54272
	ds_read_b128 v[214:217], v196 offset:55296
	ds_read_b128 v[218:221], v196 offset:56320
	global_load_lds_dwordx4 v154, s[98:99]
	s_add_i32 m0, s36, 0x2000
	s_add_u32 s36, s40, 0xb0080
	s_addc_u32 s37, s41, 0
	s_add_i32 s40, s64, s44
	global_load_lds_dwordx4 v158, s[98:99]
	s_mov_b32 m0, s40
	s_nop 0
	global_load_lds_dwordx4 v154, s[36:37]
	s_add_i32 m0, s40, 0x2000
	s_nop 0
	global_load_lds_dwordx4 v158, s[36:37]
	s_mov_b32 m0, s50
	s_nop 0
	global_load_lds_dwordx4 v152, s[100:101]
	s_mov_b32 m0, s51
	s_nop 0
	global_load_lds_dwordx4 v156, s[100:101]
	s_waitcnt vmcnt(8)
	s_waitcnt lgkmcnt(0)
	s_barrier
	s_setprio 1
	s_waitcnt lgkmcnt(0)
	v_mfma_f32_16x16x32_bf16 v[60:63], v[128:131], v[178:181], v[60:63]
	v_mfma_f32_16x16x32_bf16 v[56:59], v[136:139], v[178:181], v[56:59]
	v_mfma_f32_16x16x32_bf16 v[44:47], v[128:131], v[186:189], v[44:47]
	v_mfma_f32_16x16x32_bf16 v[40:43], v[136:139], v[186:189], v[40:43]
	v_mfma_f32_16x16x32_bf16 v[28:31], v[128:131], v[202:205], v[28:31]
	v_mfma_f32_16x16x32_bf16 v[24:27], v[136:139], v[202:205], v[24:27]
	v_mfma_f32_16x16x32_bf16 v[12:15], v[128:131], v[214:217], v[12:15]
	v_mfma_f32_16x16x32_bf16 v[8:11], v[136:139], v[214:217], v[8:11]
	v_mfma_f32_16x16x32_bf16 v[60:63], v[132:135], v[182:185], v[60:63]
	v_mfma_f32_16x16x32_bf16 v[56:59], v[140:143], v[182:185], v[56:59]
	v_mfma_f32_16x16x32_bf16 v[44:47], v[132:135], v[198:201], v[44:47]
	v_mfma_f32_16x16x32_bf16 v[40:43], v[140:143], v[198:201], v[40:43]
	v_mfma_f32_16x16x32_bf16 v[28:31], v[132:135], v[210:213], v[28:31]
	v_mfma_f32_16x16x32_bf16 v[24:27], v[140:143], v[210:213], v[24:27]
	v_mfma_f32_16x16x32_bf16 v[12:15], v[132:135], v[218:221], v[12:15]
	v_mfma_f32_16x16x32_bf16 v[8:11], v[140:143], v[218:221], v[8:11]
	v_mfma_f32_16x16x32_bf16 v[52:55], v[144:147], v[178:181], v[52:55]
	v_mfma_f32_16x16x32_bf16 v[48:51], v[168:171], v[178:181], v[48:51]
	v_mfma_f32_16x16x32_bf16 v[36:39], v[144:147], v[186:189], v[36:39]
	v_mfma_f32_16x16x32_bf16 v[32:35], v[168:171], v[186:189], v[32:35]
	v_mfma_f32_16x16x32_bf16 v[20:23], v[144:147], v[202:205], v[20:23]
	v_mfma_f32_16x16x32_bf16 v[16:19], v[168:171], v[202:205], v[16:19]
	v_mfma_f32_16x16x32_bf16 v[4:7], v[144:147], v[214:217], v[4:7]
	v_mfma_f32_16x16x32_bf16 v[0:3], v[168:171], v[214:217], v[0:3]
	v_mfma_f32_16x16x32_bf16 v[52:55], v[148:151], v[182:185], v[52:55]
	v_mfma_f32_16x16x32_bf16 v[48:51], v[174:177], v[182:185], v[48:51]
	v_mfma_f32_16x16x32_bf16 v[36:39], v[148:151], v[198:201], v[36:39]
	v_mfma_f32_16x16x32_bf16 v[32:35], v[174:177], v[198:201], v[32:35]
	v_mfma_f32_16x16x32_bf16 v[20:23], v[148:151], v[210:213], v[20:23]
	v_mfma_f32_16x16x32_bf16 v[16:19], v[174:177], v[210:213], v[16:19]
	v_mfma_f32_16x16x32_bf16 v[4:7], v[148:151], v[218:221], v[4:7]
	v_mfma_f32_16x16x32_bf16 v[0:3], v[174:177], v[218:221], v[0:3]
	s_setprio 0
	s_barrier
	s_add_i32 s62, s62, 2
	s_add_u32 s60, s60, 0x100
	s_addc_u32 s61, s61, 0
	s_cmp_gt_u32 s62, 41
	s_mov_b64 s[36:37], s[38:39]
	s_cbranch_scc1 .Lkexit_3
.LBB0_741:
	ds_read_b128 v[128:131], v194
	ds_read_b128 v[132:135], v194 offset:1024
	ds_read_b128 v[136:139], v194 offset:2048
	ds_read_b128 v[140:143], v194 offset:3072
	ds_read_b128 v[144:147], v195
	ds_read_b128 v[148:151], v195 offset:1024
	ds_read_b128 v[168:171], v195 offset:2048
	ds_read_b128 v[174:177], v195 offset:3072
	s_add_u32 s38, s36, 0x100
	s_addc_u32 s39, s37, 0
	s_cmp_eq_u32 s62, 40
	s_cselect_b32 s43, s11, s39
	s_cselect_b32 s42, s10, s38
	s_cselect_b32 s41, s25, s61
	s_cselect_b32 s40, s24, s60
	s_add_i32 m0, s45, 0xc000
	ds_read_b128 v[178:181], v196
	ds_read_b128 v[182:185], v196 offset:1024
	ds_read_b128 v[186:189], v196 offset:2048
	ds_read_b128 v[198:201], v196 offset:3072
	ds_read_b128 v[202:205], v196 offset:4096
	ds_read_b128 v[210:213], v196 offset:5120
	ds_read_b128 v[214:217], v196 offset:6144
	ds_read_b128 v[218:221], v196 offset:7168
	global_load_lds_dwordx4 v160, s[36:37]
	s_add_i32 m0, s45, 0xe000
	s_nop 0
	global_load_lds_dwordx4 v162, s[36:37]
	s_waitcnt vmcnt(8)
	s_waitcnt lgkmcnt(0)
	s_barrier
	s_setprio 1
	s_waitcnt lgkmcnt(0)
	v_mfma_f32_16x16x32_bf16 v[124:127], v[128:131], v[178:181], v[124:127]
	v_mfma_f32_16x16x32_bf16 v[120:123], v[136:139], v[178:181], v[120:123]
	v_mfma_f32_16x16x32_bf16 v[108:111], v[128:131], v[186:189], v[108:111]
	v_mfma_f32_16x16x32_bf16 v[104:107], v[136:139], v[186:189], v[104:107]
	v_mfma_f32_16x16x32_bf16 v[92:95], v[128:131], v[202:205], v[92:95]
	v_mfma_f32_16x16x32_bf16 v[88:91], v[136:139], v[202:205], v[88:91]
	v_mfma_f32_16x16x32_bf16 v[76:79], v[128:131], v[214:217], v[76:79]
	v_mfma_f32_16x16x32_bf16 v[72:75], v[136:139], v[214:217], v[72:75]
	v_mfma_f32_16x16x32_bf16 v[124:127], v[132:135], v[182:185], v[124:127]
	v_mfma_f32_16x16x32_bf16 v[120:123], v[140:143], v[182:185], v[120:123]
	v_mfma_f32_16x16x32_bf16 v[108:111], v[132:135], v[198:201], v[108:111]
	v_mfma_f32_16x16x32_bf16 v[104:107], v[140:143], v[198:201], v[104:107]
	v_mfma_f32_16x16x32_bf16 v[92:95], v[132:135], v[210:213], v[92:95]
	v_mfma_f32_16x16x32_bf16 v[88:91], v[140:143], v[210:213], v[88:91]
	v_mfma_f32_16x16x32_bf16 v[76:79], v[132:135], v[218:221], v[76:79]
	v_mfma_f32_16x16x32_bf16 v[72:75], v[140:143], v[218:221], v[72:75]
	v_mfma_f32_16x16x32_bf16 v[116:119], v[144:147], v[178:181], v[116:119]
	v_mfma_f32_16x16x32_bf16 v[112:115], v[168:171], v[178:181], v[112:115]
	v_mfma_f32_16x16x32_bf16 v[100:103], v[144:147], v[186:189], v[100:103]
	v_mfma_f32_16x16x32_bf16 v[96:99], v[168:171], v[186:189], v[96:99]
	v_mfma_f32_16x16x32_bf16 v[84:87], v[144:147], v[202:205], v[84:87]
	v_mfma_f32_16x16x32_bf16 v[80:83], v[168:171], v[202:205], v[80:83]
	v_mfma_f32_16x16x32_bf16 v[68:71], v[144:147], v[214:217], v[68:71]
	v_mfma_f32_16x16x32_bf16 v[64:67], v[168:171], v[214:217], v[64:67]
	v_mfma_f32_16x16x32_bf16 v[116:119], v[148:151], v[182:185], v[116:119]
	v_mfma_f32_16x16x32_bf16 v[112:115], v[174:177], v[182:185], v[112:115]
	v_mfma_f32_16x16x32_bf16 v[100:103], v[148:151], v[198:201], v[100:103]
	v_mfma_f32_16x16x32_bf16 v[96:99], v[174:177], v[198:201], v[96:99]
	v_mfma_f32_16x16x32_bf16 v[84:87], v[148:151], v[210:213], v[84:87]
	v_mfma_f32_16x16x32_bf16 v[80:83], v[174:177], v[210:213], v[80:83]
	v_mfma_f32_16x16x32_bf16 v[68:71], v[148:151], v[218:221], v[68:71]
	v_mfma_f32_16x16x32_bf16 v[64:67], v[174:177], v[218:221], v[64:67]
	s_setprio 0
	s_barrier
	s_add_u32 s98, s40, s20
	s_addc_u32 s99, s41, s21
	s_add_u32 s100, s42, s20
	s_addc_u32 s101, s43, s21
	s_add_i32 s36, s54, s44
	s_mov_b32 m0, s36
	ds_read_b128 v[178:181], v196 offset:16384
	ds_read_b128 v[182:185], v196 offset:17408
	ds_read_b128 v[186:189], v196 offset:18432
	ds_read_b128 v[198:201], v196 offset:19456
	ds_read_b128 v[202:205], v196 offset:20480
	ds_read_b128 v[210:213], v196 offset:21504
	ds_read_b128 v[214:217], v196 offset:22528
	ds_read_b128 v[218:221], v196 offset:23552
	global_load_lds_dwordx4 v154, s[40:41]
	s_add_i32 m0, s36, 0x2000
	s_add_u32 s36, s40, 0xb0000
	s_addc_u32 s37, s41, 0
	s_add_i32 s63, s55, s44
	global_load_lds_dwordx4 v158, s[40:41]
	s_mov_b32 m0, s63
	s_nop 0
	global_load_lds_dwordx4 v154, s[36:37]
	s_add_i32 m0, s63, 0x2000
	s_nop 0
	global_load_lds_dwordx4 v158, s[36:37]
	s_mov_b32 m0, s45
	s_nop 0
	global_load_lds_dwordx4 v152, s[42:43]
	s_mov_b32 m0, s46
	s_nop 0
	global_load_lds_dwordx4 v156, s[42:43]
	s_waitcnt vmcnt(8)
	s_waitcnt lgkmcnt(0)
	s_barrier
	s_setprio 1
	s_waitcnt lgkmcnt(0)
	v_mfma_f32_16x16x32_bf16 v[60:63], v[128:131], v[178:181], v[60:63]
	v_mfma_f32_16x16x32_bf16 v[56:59], v[136:139], v[178:181], v[56:59]
	v_mfma_f32_16x16x32_bf16 v[44:47], v[128:131], v[186:189], v[44:47]
	v_mfma_f32_16x16x32_bf16 v[40:43], v[136:139], v[186:189], v[40:43]
	v_mfma_f32_16x16x32_bf16 v[28:31], v[128:131], v[202:205], v[28:31]
	v_mfma_f32_16x16x32_bf16 v[24:27], v[136:139], v[202:205], v[24:27]
	v_mfma_f32_16x16x32_bf16 v[12:15], v[128:131], v[214:217], v[12:15]
	v_mfma_f32_16x16x32_bf16 v[8:11], v[136:139], v[214:217], v[8:11]
	v_mfma_f32_16x16x32_bf16 v[60:63], v[132:135], v[182:185], v[60:63]
	v_mfma_f32_16x16x32_bf16 v[56:59], v[140:143], v[182:185], v[56:59]
	v_mfma_f32_16x16x32_bf16 v[44:47], v[132:135], v[198:201], v[44:47]
	v_mfma_f32_16x16x32_bf16 v[40:43], v[140:143], v[198:201], v[40:43]
	v_mfma_f32_16x16x32_bf16 v[28:31], v[132:135], v[210:213], v[28:31]
	v_mfma_f32_16x16x32_bf16 v[24:27], v[140:143], v[210:213], v[24:27]
	v_mfma_f32_16x16x32_bf16 v[12:15], v[132:135], v[218:221], v[12:15]
	v_mfma_f32_16x16x32_bf16 v[8:11], v[140:143], v[218:221], v[8:11]
	v_mfma_f32_16x16x32_bf16 v[52:55], v[144:147], v[178:181], v[52:55]
	v_mfma_f32_16x16x32_bf16 v[48:51], v[168:171], v[178:181], v[48:51]
	v_mfma_f32_16x16x32_bf16 v[36:39], v[144:147], v[186:189], v[36:39]
	v_mfma_f32_16x16x32_bf16 v[32:35], v[168:171], v[186:189], v[32:35]
	v_mfma_f32_16x16x32_bf16 v[20:23], v[144:147], v[202:205], v[20:23]
	v_mfma_f32_16x16x32_bf16 v[16:19], v[168:171], v[202:205], v[16:19]
	v_mfma_f32_16x16x32_bf16 v[4:7], v[144:147], v[214:217], v[4:7]
	v_mfma_f32_16x16x32_bf16 v[0:3], v[168:171], v[214:217], v[0:3]
	v_mfma_f32_16x16x32_bf16 v[52:55], v[148:151], v[182:185], v[52:55]
	v_mfma_f32_16x16x32_bf16 v[48:51], v[174:177], v[182:185], v[48:51]
	v_mfma_f32_16x16x32_bf16 v[36:39], v[148:151], v[198:201], v[36:39]
	v_mfma_f32_16x16x32_bf16 v[32:35], v[174:177], v[198:201], v[32:35]
	v_mfma_f32_16x16x32_bf16 v[20:23], v[148:151], v[210:213], v[20:23]
	v_mfma_f32_16x16x32_bf16 v[16:19], v[174:177], v[210:213], v[16:19]
	v_mfma_f32_16x16x32_bf16 v[4:7], v[148:151], v[218:221], v[4:7]
	v_mfma_f32_16x16x32_bf16 v[0:3], v[174:177], v[218:221], v[0:3]
	s_setprio 0
	s_barrier
	s_add_i32 s63, 0, 0x18000
	s_add_i32 s64, 0, 0x1c000
	v_add_u32_e32 v140, s63, v192
	v_add_u32_e32 v174, s64, v192
	ds_read_b128 v[128:131], v140
	ds_read_b128 v[132:135], v140 offset:1024
	ds_read_b128 v[136:139], v140 offset:2048
	ds_read_b128 v[140:143], v140 offset:3072
	ds_read_b128 v[144:147], v174
	ds_read_b128 v[148:151], v174 offset:1024
	ds_read_b128 v[168:171], v174 offset:2048
	ds_read_b128 v[174:177], v174 offset:3072
	s_add_u32 s36, s42, 0xb0000
	s_addc_u32 s37, s43, 0
	s_mov_b32 m0, s47
	ds_read_b128 v[178:181], v196 offset:32768
	ds_read_b128 v[182:185], v196 offset:33792
	ds_read_b128 v[186:189], v196 offset:34816
	ds_read_b128 v[198:201], v196 offset:35840
	ds_read_b128 v[202:205], v196 offset:36864
	ds_read_b128 v[210:213], v196 offset:37888
	ds_read_b128 v[214:217], v196 offset:38912
	ds_read_b128 v[218:221], v196 offset:39936
	global_load_lds_dwordx4 v152, s[36:37]
	s_mov_b32 m0, s48
	s_nop 0
	global_load_lds_dwordx4 v156, s[36:37]
	s_waitcnt vmcnt(8)
	s_waitcnt lgkmcnt(0)
	s_barrier
	s_setprio 1
	s_waitcnt lgkmcnt(0)
	v_mfma_f32_16x16x32_bf16 v[124:127], v[128:131], v[178:181], v[124:127]
	v_mfma_f32_16x16x32_bf16 v[120:123], v[136:139], v[178:181], v[120:123]
	v_mfma_f32_16x16x32_bf16 v[108:111], v[128:131], v[186:189], v[108:111]
	v_mfma_f32_16x16x32_bf16 v[104:107], v[136:139], v[186:189], v[104:107]
	v_mfma_f32_16x16x32_bf16 v[92:95], v[128:131], v[202:205], v[92:95]
	v_mfma_f32_16x16x32_bf16 v[88:91], v[136:139], v[202:205], v[88:91]
	v_mfma_f32_16x16x32_bf16 v[76:79], v[128:131], v[214:217], v[76:79]
	v_mfma_f32_16x16x32_bf16 v[72:75], v[136:139], v[214:217], v[72:75]
	v_mfma_f32_16x16x32_bf16 v[124:127], v[132:135], v[182:185], v[124:127]
	v_mfma_f32_16x16x32_bf16 v[120:123], v[140:143], v[182:185], v[120:123]
	v_mfma_f32_16x16x32_bf16 v[108:111], v[132:135], v[198:201], v[108:111]
	v_mfma_f32_16x16x32_bf16 v[104:107], v[140:143], v[198:201], v[104:107]
	v_mfma_f32_16x16x32_bf16 v[92:95], v[132:135], v[210:213], v[92:95]
	v_mfma_f32_16x16x32_bf16 v[88:91], v[140:143], v[210:213], v[88:91]
	v_mfma_f32_16x16x32_bf16 v[76:79], v[132:135], v[218:221], v[76:79]
	v_mfma_f32_16x16x32_bf16 v[72:75], v[140:143], v[218:221], v[72:75]
	v_mfma_f32_16x16x32_bf16 v[116:119], v[144:147], v[178:181], v[116:119]
	v_mfma_f32_16x16x32_bf16 v[112:115], v[168:171], v[178:181], v[112:115]
	v_mfma_f32_16x16x32_bf16 v[100:103], v[144:147], v[186:189], v[100:103]
	v_mfma_f32_16x16x32_bf16 v[96:99], v[168:171], v[186:189], v[96:99]
	v_mfma_f32_16x16x32_bf16 v[84:87], v[144:147], v[202:205], v[84:87]
	v_mfma_f32_16x16x32_bf16 v[80:83], v[168:171], v[202:205], v[80:83]
	v_mfma_f32_16x16x32_bf16 v[68:71], v[144:147], v[214:217], v[68:71]
	v_mfma_f32_16x16x32_bf16 v[64:67], v[168:171], v[214:217], v[64:67]
	v_mfma_f32_16x16x32_bf16 v[116:119], v[148:151], v[182:185], v[116:119]
	v_mfma_f32_16x16x32_bf16 v[112:115], v[174:177], v[182:185], v[112:115]
	v_mfma_f32_16x16x32_bf16 v[100:103], v[148:151], v[198:201], v[100:103]
	v_mfma_f32_16x16x32_bf16 v[96:99], v[174:177], v[198:201], v[96:99]
	v_mfma_f32_16x16x32_bf16 v[84:87], v[148:151], v[210:213], v[84:87]
	v_mfma_f32_16x16x32_bf16 v[80:83], v[174:177], v[210:213], v[80:83]
	v_mfma_f32_16x16x32_bf16 v[68:71], v[148:151], v[218:221], v[68:71]
	v_mfma_f32_16x16x32_bf16 v[64:67], v[174:177], v[218:221], v[64:67]
	s_setprio 0
	s_barrier
	s_add_i32 s36, s63, s44
	s_mov_b32 m0, s36
	ds_read_b128 v[178:181], v196 offset:49152
	ds_read_b128 v[182:185], v196 offset:50176
	ds_read_b128 v[186:189], v196 offset:51200
	ds_read_b128 v[198:201], v196 offset:52224
	ds_read_b128 v[202:205], v196 offset:53248
	ds_read_b128 v[210:213], v196 offset:54272
	ds_read_b128 v[214:217], v196 offset:55296
	ds_read_b128 v[218:221], v196 offset:56320
	global_load_lds_dwordx4 v154, s[98:99]
	s_add_i32 m0, s36, 0x2000
	s_add_u32 s36, s40, 0xb0080
	s_addc_u32 s37, s41, 0
	s_add_i32 s40, s64, s44
	global_load_lds_dwordx4 v158, s[98:99]
	s_mov_b32 m0, s40
	s_nop 0
	global_load_lds_dwordx4 v154, s[36:37]
	s_add_i32 m0, s40, 0x2000
	s_nop 0
	global_load_lds_dwordx4 v158, s[36:37]
	s_mov_b32 m0, s50
	s_nop 0
	global_load_lds_dwordx4 v152, s[100:101]
	s_mov_b32 m0, s51
	s_nop 0
	global_load_lds_dwordx4 v156, s[100:101]
	s_waitcnt vmcnt(8)
	s_waitcnt lgkmcnt(0)
	s_barrier
	s_setprio 1
	s_waitcnt lgkmcnt(0)
	v_mfma_f32_16x16x32_bf16 v[60:63], v[128:131], v[178:181], v[60:63]
	v_mfma_f32_16x16x32_bf16 v[56:59], v[136:139], v[178:181], v[56:59]
	v_mfma_f32_16x16x32_bf16 v[44:47], v[128:131], v[186:189], v[44:47]
	v_mfma_f32_16x16x32_bf16 v[40:43], v[136:139], v[186:189], v[40:43]
	v_mfma_f32_16x16x32_bf16 v[28:31], v[128:131], v[202:205], v[28:31]
	v_mfma_f32_16x16x32_bf16 v[24:27], v[136:139], v[202:205], v[24:27]
	v_mfma_f32_16x16x32_bf16 v[12:15], v[128:131], v[214:217], v[12:15]
	v_mfma_f32_16x16x32_bf16 v[8:11], v[136:139], v[214:217], v[8:11]
	v_mfma_f32_16x16x32_bf16 v[60:63], v[132:135], v[182:185], v[60:63]
	v_mfma_f32_16x16x32_bf16 v[56:59], v[140:143], v[182:185], v[56:59]
	v_mfma_f32_16x16x32_bf16 v[44:47], v[132:135], v[198:201], v[44:47]
	v_mfma_f32_16x16x32_bf16 v[40:43], v[140:143], v[198:201], v[40:43]
	v_mfma_f32_16x16x32_bf16 v[28:31], v[132:135], v[210:213], v[28:31]
	v_mfma_f32_16x16x32_bf16 v[24:27], v[140:143], v[210:213], v[24:27]
	v_mfma_f32_16x16x32_bf16 v[12:15], v[132:135], v[218:221], v[12:15]
	v_mfma_f32_16x16x32_bf16 v[8:11], v[140:143], v[218:221], v[8:11]
	v_mfma_f32_16x16x32_bf16 v[52:55], v[144:147], v[178:181], v[52:55]
	v_mfma_f32_16x16x32_bf16 v[48:51], v[168:171], v[178:181], v[48:51]
	v_mfma_f32_16x16x32_bf16 v[36:39], v[144:147], v[186:189], v[36:39]
	v_mfma_f32_16x16x32_bf16 v[32:35], v[168:171], v[186:189], v[32:35]
	v_mfma_f32_16x16x32_bf16 v[20:23], v[144:147], v[202:205], v[20:23]
	v_mfma_f32_16x16x32_bf16 v[16:19], v[168:171], v[202:205], v[16:19]
	v_mfma_f32_16x16x32_bf16 v[4:7], v[144:147], v[214:217], v[4:7]
	v_mfma_f32_16x16x32_bf16 v[0:3], v[168:171], v[214:217], v[0:3]
	v_mfma_f32_16x16x32_bf16 v[52:55], v[148:151], v[182:185], v[52:55]
	v_mfma_f32_16x16x32_bf16 v[48:51], v[174:177], v[182:185], v[48:51]
	v_mfma_f32_16x16x32_bf16 v[36:39], v[148:151], v[198:201], v[36:39]
	v_mfma_f32_16x16x32_bf16 v[32:35], v[174:177], v[198:201], v[32:35]
	v_mfma_f32_16x16x32_bf16 v[20:23], v[148:151], v[210:213], v[20:23]
	v_mfma_f32_16x16x32_bf16 v[16:19], v[174:177], v[210:213], v[16:19]
	v_mfma_f32_16x16x32_bf16 v[4:7], v[148:151], v[218:221], v[4:7]
	v_mfma_f32_16x16x32_bf16 v[0:3], v[174:177], v[218:221], v[0:3]
	s_setprio 0
	s_barrier
	s_add_i32 s62, s62, 2
	s_add_u32 s60, s60, 0x100
	s_addc_u32 s61, s61, 0
	s_cmp_gt_u32 s62, 41
	s_mov_b64 s[36:37], s[38:39]
	s_cbranch_scc0 .LBB0_741

.LBB0_835:
	s_ashr_i32 s29, s28, 31
	s_lshl_b64 s[30:31], s[28:29], 19
	s_add_u32 s30, s12, s30
	s_addc_u32 s31, s13, s31
	s_and_b64 s[34:35], s[4:5], exec
	s_cselect_b32 s29, s31, s41
	s_cselect_b32 s37, s30, s40
	s_ashr_i32 s27, s26, 31
	s_lshl_b64 s[34:35], s[26:27], 19
	s_add_u32 s34, s2, s34
	s_addc_u32 s35, s46, s35
	s_and_b64 s[44:45], s[4:5], exec
	s_cselect_b32 s27, s35, s43
	s_cselect_b32 s39, s34, s42
	s_add_u32 s40, s40, 0x40080
	s_addc_u32 s41, s41, 0
	s_add_u32 s61, s42, 0x100
	s_addc_u32 s62, s43, 0
	s_mov_b32 s63, -2
	ds_read_b128 v[88:91], v235
	ds_read_b128 v[92:95], v235 offset:1024
	ds_read_b128 v[104:107], v235 offset:2048
	ds_read_b128 v[108:111], v235 offset:3072
	ds_read_b128 v[136:139], v236
	ds_read_b128 v[140:143], v236 offset:1024
	ds_read_b128 v[148:151], v236 offset:2048
	ds_read_b128 v[152:155], v236 offset:3072
	s_add_u32 s42, s40, 0xfffc0080
	s_addc_u32 s43, s41, -1
	s_cmp_eq_u32 s63, 12
	s_cselect_b32 s45, s29, s43
	s_cselect_b32 s44, s37, s42
	s_cselect_b32 s43, s27, s62
	s_cselect_b32 s42, s39, s61
	s_add_i32 m0, s48, 0xc000
	ds_read_b128 v[160:163], v237
	ds_read_b128 v[164:167], v237 offset:1024
	ds_read_b128 v[168:171], v237 offset:2048
	ds_read_b128 v[172:175], v237 offset:3072
	ds_read_b128 v[176:179], v237 offset:4096
	ds_read_b128 v[180:183], v237 offset:5120
	ds_read_b128 v[184:187], v237 offset:6144
	ds_read_b128 v[188:191], v237 offset:7168
	global_load_lds_dwordx4 v200, s[40:41]
	s_add_i32 m0, s48, 0xe000
	s_nop 0
	global_load_lds_dwordx4 v202, s[40:41]
	s_waitcnt vmcnt(8)
	s_waitcnt lgkmcnt(0)
	s_barrier
	s_setprio 1
	s_waitcnt lgkmcnt(0)
	v_mfma_f32_16x16x32_bf16 v[124:127], v[88:91], v[160:163], 0
	v_mfma_f32_16x16x32_bf16 v[120:123], v[104:107], v[160:163], 0
	v_mfma_f32_16x16x32_bf16 v[156:159], v[88:91], v[168:171], 0
	v_mfma_f32_16x16x32_bf16 v[144:147], v[104:107], v[168:171], 0
	v_mfma_f32_16x16x32_bf16 v[100:103], v[88:91], v[176:179], 0
	v_mfma_f32_16x16x32_bf16 v[96:99], v[104:107], v[176:179], 0
	v_mfma_f32_16x16x32_bf16 v[76:79], v[88:91], v[184:187], 0
	v_mfma_f32_16x16x32_bf16 v[72:75], v[104:107], v[184:187], 0
	v_mfma_f32_16x16x32_bf16 v[124:127], v[92:95], v[164:167], v[124:127]
	v_mfma_f32_16x16x32_bf16 v[120:123], v[108:111], v[164:167], v[120:123]
	v_mfma_f32_16x16x32_bf16 v[156:159], v[92:95], v[172:175], v[156:159]
	v_mfma_f32_16x16x32_bf16 v[144:147], v[108:111], v[172:175], v[144:147]
	v_mfma_f32_16x16x32_bf16 v[100:103], v[92:95], v[180:183], v[100:103]
	v_mfma_f32_16x16x32_bf16 v[96:99], v[108:111], v[180:183], v[96:99]
	v_mfma_f32_16x16x32_bf16 v[76:79], v[92:95], v[188:191], v[76:79]
	v_mfma_f32_16x16x32_bf16 v[72:75], v[108:111], v[188:191], v[72:75]
	v_mfma_f32_16x16x32_bf16 v[116:119], v[136:139], v[160:163], 0
	v_mfma_f32_16x16x32_bf16 v[112:115], v[148:151], v[160:163], 0
	v_mfma_f32_16x16x32_bf16 v[132:135], v[136:139], v[168:171], 0
	v_mfma_f32_16x16x32_bf16 v[128:131], v[148:151], v[168:171], 0
	v_mfma_f32_16x16x32_bf16 v[84:87], v[136:139], v[176:179], 0
	v_mfma_f32_16x16x32_bf16 v[80:83], v[148:151], v[176:179], 0
	v_mfma_f32_16x16x32_bf16 v[68:71], v[136:139], v[184:187], 0
	v_mfma_f32_16x16x32_bf16 v[64:67], v[148:151], v[184:187], 0
	v_mfma_f32_16x16x32_bf16 v[116:119], v[140:143], v[164:167], v[116:119]
	v_mfma_f32_16x16x32_bf16 v[112:115], v[152:155], v[164:167], v[112:115]
	v_mfma_f32_16x16x32_bf16 v[132:135], v[140:143], v[172:175], v[132:135]
	v_mfma_f32_16x16x32_bf16 v[128:131], v[152:155], v[172:175], v[128:131]
	v_mfma_f32_16x16x32_bf16 v[84:87], v[140:143], v[180:183], v[84:87]
	v_mfma_f32_16x16x32_bf16 v[80:83], v[152:155], v[180:183], v[80:83]
	v_mfma_f32_16x16x32_bf16 v[68:71], v[140:143], v[188:191], v[68:71]
	v_mfma_f32_16x16x32_bf16 v[64:67], v[152:155], v[188:191], v[64:67]
	s_setprio 0
	s_barrier
	s_add_u32 s98, s42, s22
	s_addc_u32 s99, s43, s23
	s_add_u32 s100, s44, s22
	s_addc_u32 s101, s45, s23
	s_add_i32 s64, s59, s47
	s_mov_b32 m0, s64
	ds_read_b128 v[160:163], v237 offset:16384
	ds_read_b128 v[164:167], v237 offset:17408
	ds_read_b128 v[168:171], v237 offset:18432
	ds_read_b128 v[172:175], v237 offset:19456
	ds_read_b128 v[176:179], v237 offset:20480
	ds_read_b128 v[180:183], v237 offset:21504
	ds_read_b128 v[184:187], v237 offset:22528
	ds_read_b128 v[188:191], v237 offset:23552
	global_load_lds_dwordx4 v194, s[42:43]
	s_add_i32 m0, s64, 0x2000
	s_add_u32 s64, s42, 0x40000
	s_addc_u32 s65, s43, 0
	s_add_i32 s66, s60, s47
	global_load_lds_dwordx4 v198, s[42:43]
	s_mov_b32 m0, s66
	s_nop 0
	global_load_lds_dwordx4 v194, s[64:65]
	s_add_i32 m0, s66, 0x2000
	s_nop 0
	global_load_lds_dwordx4 v198, s[64:65]
	s_mov_b32 m0, s48
	s_nop 0
	global_load_lds_dwordx4 v192, s[44:45]
	s_mov_b32 m0, s49
	s_nop 0
	global_load_lds_dwordx4 v196, s[44:45]
	s_waitcnt vmcnt(8)
	s_waitcnt lgkmcnt(0)
	s_barrier
	s_setprio 1
	s_waitcnt lgkmcnt(0)
	v_mfma_f32_16x16x32_bf16 v[60:63], v[88:91], v[160:163], 0
	v_mfma_f32_16x16x32_bf16 v[56:59], v[104:107], v[160:163], 0
	v_mfma_f32_16x16x32_bf16 v[44:47], v[88:91], v[168:171], 0
	v_mfma_f32_16x16x32_bf16 v[40:43], v[104:107], v[168:171], 0
	v_mfma_f32_16x16x32_bf16 v[28:31], v[88:91], v[176:179], 0
	v_mfma_f32_16x16x32_bf16 v[24:27], v[104:107], v[176:179], 0
	v_mfma_f32_16x16x32_bf16 v[12:15], v[88:91], v[184:187], 0
	v_mfma_f32_16x16x32_bf16 v[8:11], v[104:107], v[184:187], 0
	v_mfma_f32_16x16x32_bf16 v[60:63], v[92:95], v[164:167], v[60:63]
	v_mfma_f32_16x16x32_bf16 v[56:59], v[108:111], v[164:167], v[56:59]
	v_mfma_f32_16x16x32_bf16 v[44:47], v[92:95], v[172:175], v[44:47]
	v_mfma_f32_16x16x32_bf16 v[40:43], v[108:111], v[172:175], v[40:43]
	v_mfma_f32_16x16x32_bf16 v[28:31], v[92:95], v[180:183], v[28:31]
	v_mfma_f32_16x16x32_bf16 v[24:27], v[108:111], v[180:183], v[24:27]
	v_mfma_f32_16x16x32_bf16 v[12:15], v[92:95], v[188:191], v[12:15]
	v_mfma_f32_16x16x32_bf16 v[8:11], v[108:111], v[188:191], v[8:11]
	v_mfma_f32_16x16x32_bf16 v[52:55], v[136:139], v[160:163], 0
	v_mfma_f32_16x16x32_bf16 v[48:51], v[148:151], v[160:163], 0
	v_mfma_f32_16x16x32_bf16 v[36:39], v[136:139], v[168:171], 0
	v_mfma_f32_16x16x32_bf16 v[32:35], v[148:151], v[168:171], 0
	v_mfma_f32_16x16x32_bf16 v[20:23], v[136:139], v[176:179], 0
	v_mfma_f32_16x16x32_bf16 v[16:19], v[148:151], v[176:179], 0
	v_mfma_f32_16x16x32_bf16 v[4:7], v[136:139], v[184:187], 0
	v_mfma_f32_16x16x32_bf16 v[0:3], v[148:151], v[184:187], 0
	v_mfma_f32_16x16x32_bf16 v[52:55], v[140:143], v[164:167], v[52:55]
	v_mfma_f32_16x16x32_bf16 v[48:51], v[152:155], v[164:167], v[48:51]
	v_mfma_f32_16x16x32_bf16 v[36:39], v[140:143], v[172:175], v[36:39]
	v_mfma_f32_16x16x32_bf16 v[32:35], v[152:155], v[172:175], v[32:35]
	v_mfma_f32_16x16x32_bf16 v[20:23], v[140:143], v[180:183], v[20:23]
	v_mfma_f32_16x16x32_bf16 v[16:19], v[152:155], v[180:183], v[16:19]
	v_mfma_f32_16x16x32_bf16 v[4:7], v[140:143], v[188:191], v[4:7]
	v_mfma_f32_16x16x32_bf16 v[0:3], v[152:155], v[188:191], v[0:3]
	s_setprio 0
	s_barrier
	s_add_i32 s64, 0, 0x18000
	s_add_i32 s65, 0, 0x1c000
	v_add_u32_e32 v108, s64, v233
	v_add_u32_e32 v152, s65, v233
	ds_read_b128 v[88:91], v108
	ds_read_b128 v[92:95], v108 offset:1024
	ds_read_b128 v[104:107], v108 offset:2048
	ds_read_b128 v[108:111], v108 offset:3072
	ds_read_b128 v[136:139], v152
	ds_read_b128 v[140:143], v152 offset:1024
	ds_read_b128 v[148:151], v152 offset:2048
	ds_read_b128 v[152:155], v152 offset:3072
	s_add_u32 s44, s44, 0x40000
	s_addc_u32 s45, s45, 0
	s_mov_b32 m0, s50
	ds_read_b128 v[160:163], v237 offset:32768
	ds_read_b128 v[164:167], v237 offset:33792
	ds_read_b128 v[168:171], v237 offset:34816
	ds_read_b128 v[172:175], v237 offset:35840
	ds_read_b128 v[176:179], v237 offset:36864
	ds_read_b128 v[180:183], v237 offset:37888
	ds_read_b128 v[184:187], v237 offset:38912
	ds_read_b128 v[188:191], v237 offset:39936
	global_load_lds_dwordx4 v192, s[44:45]
	s_mov_b32 m0, s51
	s_nop 0
	global_load_lds_dwordx4 v196, s[44:45]
	s_waitcnt vmcnt(8)
	s_waitcnt lgkmcnt(0)
	s_barrier
	s_setprio 1
	s_waitcnt lgkmcnt(0)
	v_mfma_f32_16x16x32_bf16 v[124:127], v[88:91], v[160:163], v[124:127]
	v_mfma_f32_16x16x32_bf16 v[120:123], v[104:107], v[160:163], v[120:123]
	v_mfma_f32_16x16x32_bf16 v[156:159], v[88:91], v[168:171], v[156:159]
	v_mfma_f32_16x16x32_bf16 v[144:147], v[104:107], v[168:171], v[144:147]
	v_mfma_f32_16x16x32_bf16 v[100:103], v[88:91], v[176:179], v[100:103]
	v_mfma_f32_16x16x32_bf16 v[96:99], v[104:107], v[176:179], v[96:99]
	v_mfma_f32_16x16x32_bf16 v[76:79], v[88:91], v[184:187], v[76:79]
	v_mfma_f32_16x16x32_bf16 v[72:75], v[104:107], v[184:187], v[72:75]
	v_mfma_f32_16x16x32_bf16 v[124:127], v[92:95], v[164:167], v[124:127]
	v_mfma_f32_16x16x32_bf16 v[120:123], v[108:111], v[164:167], v[120:123]
	v_mfma_f32_16x16x32_bf16 v[156:159], v[92:95], v[172:175], v[156:159]
	v_mfma_f32_16x16x32_bf16 v[144:147], v[108:111], v[172:175], v[144:147]
	v_mfma_f32_16x16x32_bf16 v[100:103], v[92:95], v[180:183], v[100:103]
	v_mfma_f32_16x16x32_bf16 v[96:99], v[108:111], v[180:183], v[96:99]
	v_mfma_f32_16x16x32_bf16 v[76:79], v[92:95], v[188:191], v[76:79]
	v_mfma_f32_16x16x32_bf16 v[72:75], v[108:111], v[188:191], v[72:75]
	v_mfma_f32_16x16x32_bf16 v[116:119], v[136:139], v[160:163], v[116:119]
	v_mfma_f32_16x16x32_bf16 v[112:115], v[148:151], v[160:163], v[112:115]
	v_mfma_f32_16x16x32_bf16 v[132:135], v[136:139], v[168:171], v[132:135]
	v_mfma_f32_16x16x32_bf16 v[128:131], v[148:151], v[168:171], v[128:131]
	v_mfma_f32_16x16x32_bf16 v[84:87], v[136:139], v[176:179], v[84:87]
	v_mfma_f32_16x16x32_bf16 v[80:83], v[148:151], v[176:179], v[80:83]
	v_mfma_f32_16x16x32_bf16 v[68:71], v[136:139], v[184:187], v[68:71]
	v_mfma_f32_16x16x32_bf16 v[64:67], v[148:151], v[184:187], v[64:67]
	v_mfma_f32_16x16x32_bf16 v[116:119], v[140:143], v[164:167], v[116:119]
	v_mfma_f32_16x16x32_bf16 v[112:115], v[152:155], v[164:167], v[112:115]
	v_mfma_f32_16x16x32_bf16 v[132:135], v[140:143], v[172:175], v[132:135]
	v_mfma_f32_16x16x32_bf16 v[128:131], v[152:155], v[172:175], v[128:131]
	v_mfma_f32_16x16x32_bf16 v[84:87], v[140:143], v[180:183], v[84:87]
	v_mfma_f32_16x16x32_bf16 v[80:83], v[152:155], v[180:183], v[80:83]
	v_mfma_f32_16x16x32_bf16 v[68:71], v[140:143], v[188:191], v[68:71]
	v_mfma_f32_16x16x32_bf16 v[64:67], v[152:155], v[188:191], v[64:67]
	s_setprio 0
	s_barrier
	s_add_i32 s44, s64, s47
	s_mov_b32 m0, s44
	ds_read_b128 v[160:163], v237 offset:49152
	ds_read_b128 v[164:167], v237 offset:50176
	ds_read_b128 v[168:171], v237 offset:51200
	ds_read_b128 v[172:175], v237 offset:52224
	ds_read_b128 v[176:179], v237 offset:53248
	ds_read_b128 v[180:183], v237 offset:54272
	ds_read_b128 v[184:187], v237 offset:55296
	ds_read_b128 v[188:191], v237 offset:56320
	global_load_lds_dwordx4 v194, s[98:99]
	s_add_i32 m0, s44, 0x2000
	s_add_u32 s42, s42, 0x40080
	s_addc_u32 s43, s43, 0
	s_add_i32 s44, s65, s47
	global_load_lds_dwordx4 v198, s[98:99]
	s_mov_b32 m0, s44
	s_nop 0
	global_load_lds_dwordx4 v194, s[42:43]
	s_add_i32 m0, s44, 0x2000
	s_nop 0
	global_load_lds_dwordx4 v198, s[42:43]
	s_mov_b32 m0, s55
	s_nop 0
	global_load_lds_dwordx4 v192, s[100:101]
	s_mov_b32 m0, s56
	s_nop 0
	global_load_lds_dwordx4 v196, s[100:101]
	s_waitcnt vmcnt(8)
	s_waitcnt lgkmcnt(0)
	s_barrier
	s_setprio 1
	s_waitcnt lgkmcnt(0)
	v_mfma_f32_16x16x32_bf16 v[60:63], v[88:91], v[160:163], v[60:63]
	v_mfma_f32_16x16x32_bf16 v[56:59], v[104:107], v[160:163], v[56:59]
	v_mfma_f32_16x16x32_bf16 v[44:47], v[88:91], v[168:171], v[44:47]
	v_mfma_f32_16x16x32_bf16 v[40:43], v[104:107], v[168:171], v[40:43]
	v_mfma_f32_16x16x32_bf16 v[28:31], v[88:91], v[176:179], v[28:31]
	v_mfma_f32_16x16x32_bf16 v[24:27], v[104:107], v[176:179], v[24:27]
	v_mfma_f32_16x16x32_bf16 v[12:15], v[88:91], v[184:187], v[12:15]
	v_mfma_f32_16x16x32_bf16 v[8:11], v[104:107], v[184:187], v[8:11]
	v_mfma_f32_16x16x32_bf16 v[60:63], v[92:95], v[164:167], v[60:63]
	v_mfma_f32_16x16x32_bf16 v[56:59], v[108:111], v[164:167], v[56:59]
	v_mfma_f32_16x16x32_bf16 v[44:47], v[92:95], v[172:175], v[44:47]
	v_mfma_f32_16x16x32_bf16 v[40:43], v[108:111], v[172:175], v[40:43]
	v_mfma_f32_16x16x32_bf16 v[28:31], v[92:95], v[180:183], v[28:31]
	v_mfma_f32_16x16x32_bf16 v[24:27], v[108:111], v[180:183], v[24:27]
	v_mfma_f32_16x16x32_bf16 v[12:15], v[92:95], v[188:191], v[12:15]
	v_mfma_f32_16x16x32_bf16 v[8:11], v[108:111], v[188:191], v[8:11]
	v_mfma_f32_16x16x32_bf16 v[52:55], v[136:139], v[160:163], v[52:55]
	v_mfma_f32_16x16x32_bf16 v[48:51], v[148:151], v[160:163], v[48:51]
	v_mfma_f32_16x16x32_bf16 v[36:39], v[136:139], v[168:171], v[36:39]
	v_mfma_f32_16x16x32_bf16 v[32:35], v[148:151], v[168:171], v[32:35]
	v_mfma_f32_16x16x32_bf16 v[20:23], v[136:139], v[176:179], v[20:23]
	v_mfma_f32_16x16x32_bf16 v[16:19], v[148:151], v[176:179], v[16:19]
	v_mfma_f32_16x16x32_bf16 v[4:7], v[136:139], v[184:187], v[4:7]
	v_mfma_f32_16x16x32_bf16 v[0:3], v[148:151], v[184:187], v[0:3]
	v_mfma_f32_16x16x32_bf16 v[52:55], v[140:143], v[164:167], v[52:55]
	v_mfma_f32_16x16x32_bf16 v[48:51], v[152:155], v[164:167], v[48:51]
	v_mfma_f32_16x16x32_bf16 v[36:39], v[140:143], v[172:175], v[36:39]
	v_mfma_f32_16x16x32_bf16 v[32:35], v[152:155], v[172:175], v[32:35]
	v_mfma_f32_16x16x32_bf16 v[20:23], v[140:143], v[180:183], v[20:23]
	v_mfma_f32_16x16x32_bf16 v[16:19], v[152:155], v[180:183], v[16:19]
	v_mfma_f32_16x16x32_bf16 v[4:7], v[140:143], v[188:191], v[4:7]
	v_mfma_f32_16x16x32_bf16 v[0:3], v[152:155], v[188:191], v[0:3]
	s_setprio 0
	s_barrier
	s_add_i32 s63, s63, 2
	s_add_u32 s40, s40, 0x100
	s_addc_u32 s41, s41, 0
	s_add_u32 s61, s61, 0x100
	s_addc_u32 s62, s62, 0
	s_cmp_gt_u32 s63, 13
	s_cbranch_scc1 .Lkexit_4
.LBB0_836:
	ds_read_b128 v[88:91], v235
	ds_read_b128 v[92:95], v235 offset:1024
	ds_read_b128 v[104:107], v235 offset:2048
	ds_read_b128 v[108:111], v235 offset:3072
	ds_read_b128 v[136:139], v236
	ds_read_b128 v[140:143], v236 offset:1024
	ds_read_b128 v[148:151], v236 offset:2048
	ds_read_b128 v[152:155], v236 offset:3072
	s_add_u32 s42, s40, 0xfffc0080
	s_addc_u32 s43, s41, -1
	s_cmp_eq_u32 s63, 12
	s_cselect_b32 s45, s29, s43
	s_cselect_b32 s44, s37, s42
	s_cselect_b32 s43, s27, s62
	s_cselect_b32 s42, s39, s61
	s_add_i32 m0, s48, 0xc000
	ds_read_b128 v[160:163], v237
	ds_read_b128 v[164:167], v237 offset:1024
	ds_read_b128 v[168:171], v237 offset:2048
	ds_read_b128 v[172:175], v237 offset:3072
	ds_read_b128 v[176:179], v237 offset:4096
	ds_read_b128 v[180:183], v237 offset:5120
	ds_read_b128 v[184:187], v237 offset:6144
	ds_read_b128 v[188:191], v237 offset:7168
	global_load_lds_dwordx4 v200, s[40:41]
	s_add_i32 m0, s48, 0xe000
	s_nop 0
	global_load_lds_dwordx4 v202, s[40:41]
	s_waitcnt vmcnt(8)
	s_waitcnt lgkmcnt(0)
	s_barrier
	s_setprio 1
	s_waitcnt lgkmcnt(0)
	v_mfma_f32_16x16x32_bf16 v[124:127], v[88:91], v[160:163], v[124:127]
	v_mfma_f32_16x16x32_bf16 v[120:123], v[104:107], v[160:163], v[120:123]
	v_mfma_f32_16x16x32_bf16 v[156:159], v[88:91], v[168:171], v[156:159]
	v_mfma_f32_16x16x32_bf16 v[144:147], v[104:107], v[168:171], v[144:147]
	v_mfma_f32_16x16x32_bf16 v[100:103], v[88:91], v[176:179], v[100:103]
	v_mfma_f32_16x16x32_bf16 v[96:99], v[104:107], v[176:179], v[96:99]
	v_mfma_f32_16x16x32_bf16 v[76:79], v[88:91], v[184:187], v[76:79]
	v_mfma_f32_16x16x32_bf16 v[72:75], v[104:107], v[184:187], v[72:75]
	v_mfma_f32_16x16x32_bf16 v[124:127], v[92:95], v[164:167], v[124:127]
	v_mfma_f32_16x16x32_bf16 v[120:123], v[108:111], v[164:167], v[120:123]
	v_mfma_f32_16x16x32_bf16 v[156:159], v[92:95], v[172:175], v[156:159]
	v_mfma_f32_16x16x32_bf16 v[144:147], v[108:111], v[172:175], v[144:147]
	v_mfma_f32_16x16x32_bf16 v[100:103], v[92:95], v[180:183], v[100:103]
	v_mfma_f32_16x16x32_bf16 v[96:99], v[108:111], v[180:183], v[96:99]
	v_mfma_f32_16x16x32_bf16 v[76:79], v[92:95], v[188:191], v[76:79]
	v_mfma_f32_16x16x32_bf16 v[72:75], v[108:111], v[188:191], v[72:75]
	v_mfma_f32_16x16x32_bf16 v[116:119], v[136:139], v[160:163], v[116:119]
	v_mfma_f32_16x16x32_bf16 v[112:115], v[148:151], v[160:163], v[112:115]
	v_mfma_f32_16x16x32_bf16 v[132:135], v[136:139], v[168:171], v[132:135]
	v_mfma_f32_16x16x32_bf16 v[128:131], v[148:151], v[168:171], v[128:131]
	v_mfma_f32_16x16x32_bf16 v[84:87], v[136:139], v[176:179], v[84:87]
	v_mfma_f32_16x16x32_bf16 v[80:83], v[148:151], v[176:179], v[80:83]
	v_mfma_f32_16x16x32_bf16 v[68:71], v[136:139], v[184:187], v[68:71]
	v_mfma_f32_16x16x32_bf16 v[64:67], v[148:151], v[184:187], v[64:67]
	v_mfma_f32_16x16x32_bf16 v[116:119], v[140:143], v[164:167], v[116:119]
	v_mfma_f32_16x16x32_bf16 v[112:115], v[152:155], v[164:167], v[112:115]
	v_mfma_f32_16x16x32_bf16 v[132:135], v[140:143], v[172:175], v[132:135]
	v_mfma_f32_16x16x32_bf16 v[128:131], v[152:155], v[172:175], v[128:131]
	v_mfma_f32_16x16x32_bf16 v[84:87], v[140:143], v[180:183], v[84:87]
	v_mfma_f32_16x16x32_bf16 v[80:83], v[152:155], v[180:183], v[80:83]
	v_mfma_f32_16x16x32_bf16 v[68:71], v[140:143], v[188:191], v[68:71]
	v_mfma_f32_16x16x32_bf16 v[64:67], v[152:155], v[188:191], v[64:67]
	s_setprio 0
	s_barrier
	s_add_u32 s98, s42, s22
	s_addc_u32 s99, s43, s23
	s_add_u32 s100, s44, s22
	s_addc_u32 s101, s45, s23
	s_add_i32 s64, s59, s47
	s_mov_b32 m0, s64
	ds_read_b128 v[160:163], v237 offset:16384
	ds_read_b128 v[164:167], v237 offset:17408
	ds_read_b128 v[168:171], v237 offset:18432
	ds_read_b128 v[172:175], v237 offset:19456
	ds_read_b128 v[176:179], v237 offset:20480
	ds_read_b128 v[180:183], v237 offset:21504
	ds_read_b128 v[184:187], v237 offset:22528
	ds_read_b128 v[188:191], v237 offset:23552
	global_load_lds_dwordx4 v194, s[42:43]
	s_add_i32 m0, s64, 0x2000
	s_add_u32 s64, s42, 0x40000
	s_addc_u32 s65, s43, 0
	s_add_i32 s66, s60, s47
	global_load_lds_dwordx4 v198, s[42:43]
	s_mov_b32 m0, s66
	s_nop 0
	global_load_lds_dwordx4 v194, s[64:65]
	s_add_i32 m0, s66, 0x2000
	s_nop 0
	global_load_lds_dwordx4 v198, s[64:65]
	s_mov_b32 m0, s48
	s_nop 0
	global_load_lds_dwordx4 v192, s[44:45]
	s_mov_b32 m0, s49
	s_nop 0
	global_load_lds_dwordx4 v196, s[44:45]
	s_waitcnt vmcnt(8)
	s_waitcnt lgkmcnt(0)
	s_barrier
	s_setprio 1
	s_waitcnt lgkmcnt(0)
	v_mfma_f32_16x16x32_bf16 v[60:63], v[88:91], v[160:163], v[60:63]
	v_mfma_f32_16x16x32_bf16 v[56:59], v[104:107], v[160:163], v[56:59]
	v_mfma_f32_16x16x32_bf16 v[44:47], v[88:91], v[168:171], v[44:47]
	v_mfma_f32_16x16x32_bf16 v[40:43], v[104:107], v[168:171], v[40:43]
	v_mfma_f32_16x16x32_bf16 v[28:31], v[88:91], v[176:179], v[28:31]
	v_mfma_f32_16x16x32_bf16 v[24:27], v[104:107], v[176:179], v[24:27]
	v_mfma_f32_16x16x32_bf16 v[12:15], v[88:91], v[184:187], v[12:15]
	v_mfma_f32_16x16x32_bf16 v[8:11], v[104:107], v[184:187], v[8:11]
	v_mfma_f32_16x16x32_bf16 v[60:63], v[92:95], v[164:167], v[60:63]
	v_mfma_f32_16x16x32_bf16 v[56:59], v[108:111], v[164:167], v[56:59]
	v_mfma_f32_16x16x32_bf16 v[44:47], v[92:95], v[172:175], v[44:47]
	v_mfma_f32_16x16x32_bf16 v[40:43], v[108:111], v[172:175], v[40:43]
	v_mfma_f32_16x16x32_bf16 v[28:31], v[92:95], v[180:183], v[28:31]
	v_mfma_f32_16x16x32_bf16 v[24:27], v[108:111], v[180:183], v[24:27]
	v_mfma_f32_16x16x32_bf16 v[12:15], v[92:95], v[188:191], v[12:15]
	v_mfma_f32_16x16x32_bf16 v[8:11], v[108:111], v[188:191], v[8:11]
	v_mfma_f32_16x16x32_bf16 v[52:55], v[136:139], v[160:163], v[52:55]
	v_mfma_f32_16x16x32_bf16 v[48:51], v[148:151], v[160:163], v[48:51]
	v_mfma_f32_16x16x32_bf16 v[36:39], v[136:139], v[168:171], v[36:39]
	v_mfma_f32_16x16x32_bf16 v[32:35], v[148:151], v[168:171], v[32:35]
	v_mfma_f32_16x16x32_bf16 v[20:23], v[136:139], v[176:179], v[20:23]
	v_mfma_f32_16x16x32_bf16 v[16:19], v[148:151], v[176:179], v[16:19]
	v_mfma_f32_16x16x32_bf16 v[4:7], v[136:139], v[184:187], v[4:7]
	v_mfma_f32_16x16x32_bf16 v[0:3], v[148:151], v[184:187], v[0:3]
	v_mfma_f32_16x16x32_bf16 v[52:55], v[140:143], v[164:167], v[52:55]
	v_mfma_f32_16x16x32_bf16 v[48:51], v[152:155], v[164:167], v[48:51]
	v_mfma_f32_16x16x32_bf16 v[36:39], v[140:143], v[172:175], v[36:39]
	v_mfma_f32_16x16x32_bf16 v[32:35], v[152:155], v[172:175], v[32:35]
	v_mfma_f32_16x16x32_bf16 v[20:23], v[140:143], v[180:183], v[20:23]
	v_mfma_f32_16x16x32_bf16 v[16:19], v[152:155], v[180:183], v[16:19]
	v_mfma_f32_16x16x32_bf16 v[4:7], v[140:143], v[188:191], v[4:7]
	v_mfma_f32_16x16x32_bf16 v[0:3], v[152:155], v[188:191], v[0:3]
	s_setprio 0
	s_barrier
	s_add_i32 s64, 0, 0x18000
	s_add_i32 s65, 0, 0x1c000
	v_add_u32_e32 v108, s64, v233
	v_add_u32_e32 v152, s65, v233
	ds_read_b128 v[88:91], v108
	ds_read_b128 v[92:95], v108 offset:1024
	ds_read_b128 v[104:107], v108 offset:2048
	ds_read_b128 v[108:111], v108 offset:3072
	ds_read_b128 v[136:139], v152
	ds_read_b128 v[140:143], v152 offset:1024
	ds_read_b128 v[148:151], v152 offset:2048
	ds_read_b128 v[152:155], v152 offset:3072
	s_add_u32 s44, s44, 0x40000
	s_addc_u32 s45, s45, 0
	s_mov_b32 m0, s50
	ds_read_b128 v[160:163], v237 offset:32768
	ds_read_b128 v[164:167], v237 offset:33792
	ds_read_b128 v[168:171], v237 offset:34816
	ds_read_b128 v[172:175], v237 offset:35840
	ds_read_b128 v[176:179], v237 offset:36864
	ds_read_b128 v[180:183], v237 offset:37888
	ds_read_b128 v[184:187], v237 offset:38912
	ds_read_b128 v[188:191], v237 offset:39936
	global_load_lds_dwordx4 v192, s[44:45]
	s_mov_b32 m0, s51
	s_nop 0
	global_load_lds_dwordx4 v196, s[44:45]
	s_waitcnt vmcnt(8)
	s_waitcnt lgkmcnt(0)
	s_barrier
	s_setprio 1
	s_waitcnt lgkmcnt(0)
	v_mfma_f32_16x16x32_bf16 v[124:127], v[88:91], v[160:163], v[124:127]
	v_mfma_f32_16x16x32_bf16 v[120:123], v[104:107], v[160:163], v[120:123]
	v_mfma_f32_16x16x32_bf16 v[156:159], v[88:91], v[168:171], v[156:159]
	v_mfma_f32_16x16x32_bf16 v[144:147], v[104:107], v[168:171], v[144:147]
	v_mfma_f32_16x16x32_bf16 v[100:103], v[88:91], v[176:179], v[100:103]
	v_mfma_f32_16x16x32_bf16 v[96:99], v[104:107], v[176:179], v[96:99]
	v_mfma_f32_16x16x32_bf16 v[76:79], v[88:91], v[184:187], v[76:79]
	v_mfma_f32_16x16x32_bf16 v[72:75], v[104:107], v[184:187], v[72:75]
	v_mfma_f32_16x16x32_bf16 v[124:127], v[92:95], v[164:167], v[124:127]
	v_mfma_f32_16x16x32_bf16 v[120:123], v[108:111], v[164:167], v[120:123]
	v_mfma_f32_16x16x32_bf16 v[156:159], v[92:95], v[172:175], v[156:159]
	v_mfma_f32_16x16x32_bf16 v[144:147], v[108:111], v[172:175], v[144:147]
	v_mfma_f32_16x16x32_bf16 v[100:103], v[92:95], v[180:183], v[100:103]
	v_mfma_f32_16x16x32_bf16 v[96:99], v[108:111], v[180:183], v[96:99]
	v_mfma_f32_16x16x32_bf16 v[76:79], v[92:95], v[188:191], v[76:79]
	v_mfma_f32_16x16x32_bf16 v[72:75], v[108:111], v[188:191], v[72:75]
	v_mfma_f32_16x16x32_bf16 v[116:119], v[136:139], v[160:163], v[116:119]
	v_mfma_f32_16x16x32_bf16 v[112:115], v[148:151], v[160:163], v[112:115]
	v_mfma_f32_16x16x32_bf16 v[132:135], v[136:139], v[168:171], v[132:135]
	v_mfma_f32_16x16x32_bf16 v[128:131], v[148:151], v[168:171], v[128:131]
	v_mfma_f32_16x16x32_bf16 v[84:87], v[136:139], v[176:179], v[84:87]
	v_mfma_f32_16x16x32_bf16 v[80:83], v[148:151], v[176:179], v[80:83]
	v_mfma_f32_16x16x32_bf16 v[68:71], v[136:139], v[184:187], v[68:71]
	v_mfma_f32_16x16x32_bf16 v[64:67], v[148:151], v[184:187], v[64:67]
	v_mfma_f32_16x16x32_bf16 v[116:119], v[140:143], v[164:167], v[116:119]
	v_mfma_f32_16x16x32_bf16 v[112:115], v[152:155], v[164:167], v[112:115]
	v_mfma_f32_16x16x32_bf16 v[132:135], v[140:143], v[172:175], v[132:135]
	v_mfma_f32_16x16x32_bf16 v[128:131], v[152:155], v[172:175], v[128:131]
	v_mfma_f32_16x16x32_bf16 v[84:87], v[140:143], v[180:183], v[84:87]
	v_mfma_f32_16x16x32_bf16 v[80:83], v[152:155], v[180:183], v[80:83]
	v_mfma_f32_16x16x32_bf16 v[68:71], v[140:143], v[188:191], v[68:71]
	v_mfma_f32_16x16x32_bf16 v[64:67], v[152:155], v[188:191], v[64:67]
	s_setprio 0
	s_barrier
	s_add_i32 s44, s64, s47
	s_mov_b32 m0, s44
	ds_read_b128 v[160:163], v237 offset:49152
	ds_read_b128 v[164:167], v237 offset:50176
	ds_read_b128 v[168:171], v237 offset:51200
	ds_read_b128 v[172:175], v237 offset:52224
	ds_read_b128 v[176:179], v237 offset:53248
	ds_read_b128 v[180:183], v237 offset:54272
	ds_read_b128 v[184:187], v237 offset:55296
	ds_read_b128 v[188:191], v237 offset:56320
	global_load_lds_dwordx4 v194, s[98:99]
	s_add_i32 m0, s44, 0x2000
	s_add_u32 s42, s42, 0x40080
	s_addc_u32 s43, s43, 0
	s_add_i32 s44, s65, s47
	global_load_lds_dwordx4 v198, s[98:99]
	s_mov_b32 m0, s44
	s_nop 0
	global_load_lds_dwordx4 v194, s[42:43]
	s_add_i32 m0, s44, 0x2000
	s_nop 0
	global_load_lds_dwordx4 v198, s[42:43]
	s_mov_b32 m0, s55
	s_nop 0
	global_load_lds_dwordx4 v192, s[100:101]
	s_mov_b32 m0, s56
	s_nop 0
	global_load_lds_dwordx4 v196, s[100:101]
	s_waitcnt vmcnt(8)
	s_waitcnt lgkmcnt(0)
	s_barrier
	s_setprio 1
	s_waitcnt lgkmcnt(0)
	v_mfma_f32_16x16x32_bf16 v[60:63], v[88:91], v[160:163], v[60:63]
	v_mfma_f32_16x16x32_bf16 v[56:59], v[104:107], v[160:163], v[56:59]
	v_mfma_f32_16x16x32_bf16 v[44:47], v[88:91], v[168:171], v[44:47]
	v_mfma_f32_16x16x32_bf16 v[40:43], v[104:107], v[168:171], v[40:43]
	v_mfma_f32_16x16x32_bf16 v[28:31], v[88:91], v[176:179], v[28:31]
	v_mfma_f32_16x16x32_bf16 v[24:27], v[104:107], v[176:179], v[24:27]
	v_mfma_f32_16x16x32_bf16 v[12:15], v[88:91], v[184:187], v[12:15]
	v_mfma_f32_16x16x32_bf16 v[8:11], v[104:107], v[184:187], v[8:11]
	v_mfma_f32_16x16x32_bf16 v[60:63], v[92:95], v[164:167], v[60:63]
	v_mfma_f32_16x16x32_bf16 v[56:59], v[108:111], v[164:167], v[56:59]
	v_mfma_f32_16x16x32_bf16 v[44:47], v[92:95], v[172:175], v[44:47]
	v_mfma_f32_16x16x32_bf16 v[40:43], v[108:111], v[172:175], v[40:43]
	v_mfma_f32_16x16x32_bf16 v[28:31], v[92:95], v[180:183], v[28:31]
	v_mfma_f32_16x16x32_bf16 v[24:27], v[108:111], v[180:183], v[24:27]
	v_mfma_f32_16x16x32_bf16 v[12:15], v[92:95], v[188:191], v[12:15]
	v_mfma_f32_16x16x32_bf16 v[8:11], v[108:111], v[188:191], v[8:11]
	v_mfma_f32_16x16x32_bf16 v[52:55], v[136:139], v[160:163], v[52:55]
	v_mfma_f32_16x16x32_bf16 v[48:51], v[148:151], v[160:163], v[48:51]
	v_mfma_f32_16x16x32_bf16 v[36:39], v[136:139], v[168:171], v[36:39]
	v_mfma_f32_16x16x32_bf16 v[32:35], v[148:151], v[168:171], v[32:35]
	v_mfma_f32_16x16x32_bf16 v[20:23], v[136:139], v[176:179], v[20:23]
	v_mfma_f32_16x16x32_bf16 v[16:19], v[148:151], v[176:179], v[16:19]
	v_mfma_f32_16x16x32_bf16 v[4:7], v[136:139], v[184:187], v[4:7]
	v_mfma_f32_16x16x32_bf16 v[0:3], v[148:151], v[184:187], v[0:3]
	v_mfma_f32_16x16x32_bf16 v[52:55], v[140:143], v[164:167], v[52:55]
	v_mfma_f32_16x16x32_bf16 v[48:51], v[152:155], v[164:167], v[48:51]
	v_mfma_f32_16x16x32_bf16 v[36:39], v[140:143], v[172:175], v[36:39]
	v_mfma_f32_16x16x32_bf16 v[32:35], v[152:155], v[172:175], v[32:35]
	v_mfma_f32_16x16x32_bf16 v[20:23], v[140:143], v[180:183], v[20:23]
	v_mfma_f32_16x16x32_bf16 v[16:19], v[152:155], v[180:183], v[16:19]
	v_mfma_f32_16x16x32_bf16 v[4:7], v[140:143], v[188:191], v[4:7]
	v_mfma_f32_16x16x32_bf16 v[0:3], v[152:155], v[188:191], v[0:3]
	s_setprio 0
	s_barrier
	s_add_i32 s63, s63, 2
	s_add_u32 s40, s40, 0x100
	s_addc_u32 s41, s41, 0
	s_add_u32 s61, s61, 0x100
	s_addc_u32 s62, s62, 0
	s_cmp_gt_u32 s63, 13
	s_cbranch_scc0 .LBB0_836
